# wait cleanup + row-sum chain folded into the running sum (bit-identical order) + second-half V base adds folded into ds_read immediates: 2-3 fewer VALU per step in the attention loops
# speedup vs baseline: 1.0052x; 1.0052x over previous
; #define WAIT_BAR(N) asm volatile("s_waitcnt vmcnt(" #N ") lgkmcnt(0)\n\ts_barrier":::"memory")
;   #define RESC() do{ if(resc){ asm volatile("s_waitcnt lgkmcnt(0)":::"memory"); \
;       _Pragma("unroll") for(int d_=0;d_<2;++d_) _Pragma("unroll") for(int r=0;r<16;++r)o[d_][r]*=wsf[crow(r,hi)]; } }while(0)
;   #define ROT() do{sl_prev=sl_cur;sl_cur=sl_next;sl_next=(sl_next==(NSLOT-1)*SLOTB)?0:sl_next+SLOTB;}while(0)
; #define WAIT_BAR(N) asm volatile("s_waitcnt vmcnt(" #N ") lgkmcnt(0)\n\ts_barrier":::"memory")
;   #define RESC() do{ if(resc){ asm volatile("s_waitcnt lgkmcnt(0)":::"memory"); \
;       _Pragma("unroll") for(int d_=0;d_<4;++d_) _Pragma("unroll") for(int r=0;r<16;++r)o[d_][r]*=wsf[crow(r,hi)]; } }while(0)
;   #define ROT() do{sl_prev=sl_cur;sl_cur=sl_next;sl_next=(sl_next==(NSLOT-1)*SLOTB)?0:sl_next+SLOTB;}while(0)
; #define WAIT_BAR(N) asm volatile("s_waitcnt vmcnt(" #N ") lgkmcnt(0)\n\ts_barrier":::"memory")
;   #define RESC() do{ if(resc){ asm volatile("s_waitcnt lgkmcnt(0)":::"memory"); \
;       _Pragma("unroll") for(int d_=0;d_<2;++d_) _Pragma("unroll") for(int r=0;r<16;++r)o[d_][r]*=wsf[crow(r,hi)]; } }while(0)
;   #define ROT() do{sl_prev=sl_cur;sl_cur=sl_next;sl_next=(sl_next==(NSLOT-1)*SLOTB)?0:sl_next+SLOTB;}while(0)
; template<int THRL,bool FIXED> __device__ __forceinline__ void attn_unit(int qb,const bf16*Qp,const unsigned char*__restrict__ K8h,const bf16*__restrict__ Vh,bf16*Op,int PO,char*shm){
;     ...
;   for(;t+5<NT;t+=2){
;     STEP(pB0,pB1,pA0,pA1,t,true,true,true);     WAIT_BAR(3); RESC(); ROT();
;     STEP(pA0,pA1,pB0,pB1,t+1,true,true,true);   WAIT_BAR(3); RESC(); ROT();
.LBB0_543:
	s_add_i32 s22, s10, 0x8000
	s_and_b32 s22, s22, 0x6000
	v_add_u32_e32 v116, s22, v166
	ds_read_b64_tr_b16 v[120:121], v116 offset:24576
	ds_read_b64_tr_b16 v[122:123], v116 offset:25088
	s_add_i32 s23, s10, 0x2000
	v_add_f32_e32 v96, v64, v65
	v_add_f32_e32 v96, v66, v96
	v_add_f32_e32 v96, v67, v96
	v_add_f32_e32 v96, v68, v96
	v_add_f32_e32 v117, v69, v96
	v_cvt_pk_bf16_f32 v148, v64, v65
	v_cvt_pk_bf16_f32 v149, v66, v67
	v_mfma_scale_f32_32x32x64_f8f6f4 v[96:111], v[88:95], v[128:135], v[32:47], v242, v241 op_sel_hi:[0,0,0]
	ds_read_b64_tr_b16 v[64:65], v116 offset:28672
	ds_read_b64_tr_b16 v[66:67], v116 offset:29184
	v_add_f32_e32 v88, v70, v117
	v_add_f32_e32 v88, v71, v88
	v_add_f32_e32 v88, v72, v88
	v_add_f32_e32 v117, v73, v88
	v_mfma_scale_f32_32x32x64_f8f6f4 v[80:95], v[80:87], v[128:135], v[32:47], v242, v241 op_sel_hi:[0,0,0]
	v_cvt_pk_bf16_f32 v150, v68, v69
	v_cvt_pk_bf16_f32 v151, v70, v71
	ds_read_b64_tr_b16 v[68:69], v116 offset:25600
	ds_read_b64_tr_b16 v[70:71], v116 offset:26112
	v_add_f32_e32 v117, v74, v117
	v_add_f32_e32 v117, v75, v117
	v_add_f32_e32 v117, v76, v117
	v_add_f32_e32 v117, v77, v117
	v_cvt_pk_bf16_f32 v144, v72, v73
	v_cvt_pk_bf16_f32 v145, v74, v75
	ds_read_b64_tr_b16 v[72:73], v116 offset:29696
	ds_read_b64_tr_b16 v[74:75], v116 offset:30208
	v_add_f32_e32 v117, v78, v117
	v_add_f32_e32 v117, v79, v117
	v_add_f32_e32 v117, v48, v117
	v_add_f32_e32 v117, v49, v117
	v_cvt_pk_bf16_f32 v146, v76, v77
	v_cvt_pk_bf16_f32 v147, v78, v79
	ds_read_b64_tr_b16 v[76:77], v116 offset:26624
	ds_read_b64_tr_b16 v[78:79], v116 offset:27136
	v_add_f32_e32 v117, v50, v117
	v_add_f32_e32 v117, v51, v117
	v_add_f32_e32 v117, v52, v117
	v_add_f32_e32 v117, v53, v117
	v_cvt_pk_bf16_f32 v140, v48, v49
	v_cvt_pk_bf16_f32 v141, v50, v51
	ds_read_b64_tr_b16 v[124:125], v116 offset:30720
	ds_read_b64_tr_b16 v[126:127], v116 offset:31232
	v_add_f32_e32 v48, v54, v117
	v_add_f32_e32 v48, v55, v48
	v_add_f32_e32 v48, v56, v48
	v_add_f32_e32 v48, v57, v48
	v_cvt_pk_bf16_f32 v142, v52, v53
	v_cvt_pk_bf16_f32 v143, v54, v55
	ds_read_b64_tr_b16 v[168:169], v116 offset:27648
	ds_read_b64_tr_b16 v[170:171], v116 offset:28160
	v_add_f32_e32 v48, v58, v48
	v_add_f32_e32 v48, v59, v48
	v_add_f32_e32 v48, v60, v48
	v_add_f32_e32 v48, v61, v48
	v_cvt_pk_bf16_f32 v136, v56, v57
	v_cvt_pk_bf16_f32 v137, v58, v59
	ds_read_b64_tr_b16 v[172:173], v116 offset:31744
	ds_read_b64_tr_b16 v[174:175], v116 offset:32256
	v_add_f32_e32 v48, v62, v48
	v_add_f32_e32 v48, v63, v48
	v_add_f32_e32 v119, v118, v48
	v_cvt_pk_bf16_f32 v138, v60, v61
	v_cvt_pk_bf16_f32 v139, v62, v63
	v_lshl_add_u64 v[116:117], v[114:115], 0, s[10:11]
	s_add_i32 s50, s50, s29
	s_mov_b32 m0, s50
	v_lshl_add_u64 v[48:49], v[116:117], 0, s[60:61]
	global_load_lds_dwordx4 v[48:49], off
	s_add_i32 s50, s10, 0x6000
	s_and_b32 s50, s50, 0x6000
	s_add_i32 s50, s50, s44
	s_mov_b32 m0, s50
	v_lshl_add_u64 v[48:49], v[112:113], 0, s[36:37]
	global_load_lds_dwordx4 v[48:49], off
	s_waitcnt lgkmcnt(8)
	v_mfma_f32_32x32x16_bf16 v[0:15], v[148:151], v[120:123], v[0:15]
	v_exp_f32_e32 v96, v96
	v_exp_f32_e32 v97, v97
	v_exp_f32_e32 v98, v98
	v_exp_f32_e32 v99, v99
	v_mfma_f32_32x32x16_bf16 v[16:31], v[148:151], v[64:67], v[16:31]
	v_exp_f32_e32 v100, v100
	v_exp_f32_e32 v101, v101
	v_exp_f32_e32 v102, v102
	v_exp_f32_e32 v103, v103
	v_add_u32_e32 v60, s13, v165
	ds_read_b128 v[48:51], v60
	v_mfma_f32_32x32x16_bf16 v[0:15], v[144:147], v[68:71], v[0:15]
	v_exp_f32_e32 v104, v104
	v_exp_f32_e32 v105, v105
	v_exp_f32_e32 v106, v106
	v_exp_f32_e32 v107, v107
	ds_read_b128 v[52:55], v60 offset:1024
	v_mfma_f32_32x32x16_bf16 v[16:31], v[144:147], v[72:75], v[16:31]
	v_exp_f32_e32 v108, v108
	v_exp_f32_e32 v109, v109
	v_exp_f32_e32 v110, v110
	v_exp_f32_e32 v111, v111
	ds_read_b128 v[56:59], v60 offset:512
	s_waitcnt lgkmcnt(3)
	v_mfma_f32_32x32x16_bf16 v[0:15], v[140:143], v[76:79], v[0:15]
	v_exp_f32_e32 v80, v80
	v_exp_f32_e32 v81, v81
	v_exp_f32_e32 v82, v82
	v_exp_f32_e32 v83, v83
	ds_read_b128 v[60:63], v60 offset:1536
	v_mfma_f32_32x32x16_bf16 v[16:31], v[140:143], v[124:127], v[16:31]
	v_exp_f32_e32 v84, v84
	v_exp_f32_e32 v85, v85
	v_exp_f32_e32 v86, v86
	v_exp_f32_e32 v87, v87
	v_mfma_f32_32x32x16_bf16 v[0:15], v[136:139], v[168:171], v[0:15]
	v_exp_f32_e32 v88, v88
	v_exp_f32_e32 v89, v89
	v_exp_f32_e32 v90, v90
	v_exp_f32_e32 v91, v91
	v_mfma_f32_32x32x16_bf16 v[16:31], v[136:139], v[172:175], v[16:31]
	v_exp_f32_e32 v92, v92
	v_exp_f32_e32 v93, v93
	v_exp_f32_e32 v94, v94
	v_exp_f32_e32 v95, v95
	s_waitcnt vmcnt(3) lgkmcnt(0)
	s_barrier
; #define WAIT_BAR(N) asm volatile("s_waitcnt vmcnt(" #N ") lgkmcnt(0)\n\ts_barrier":::"memory")
;   #define RESC() do{ if(resc){ asm volatile("s_waitcnt lgkmcnt(0)":::"memory"); \
;       _Pragma("unroll") for(int d_=0;d_<2;++d_) _Pragma("unroll") for(int r=0;r<16;++r)o[d_][r]*=wsf[crow(r,hi)]; } }while(0)
;   #define ROT() do{sl_prev=sl_cur;sl_cur=sl_next;sl_next=(sl_next==(NSLOT-1)*SLOTB)?0:sl_next+SLOTB;}while(0)
; #define WAIT_BAR(N) asm volatile("s_waitcnt vmcnt(" #N ") lgkmcnt(0)\n\ts_barrier":::"memory")
;   #define RESC() do{ if(resc){ asm volatile("s_waitcnt lgkmcnt(0)":::"memory"); \
;       _Pragma("unroll") for(int d_=0;d_<4;++d_) _Pragma("unroll") for(int r=0;r<16;++r)o[d_][r]*=wsf[crow(r,hi)]; } }while(0)
;   #define ROT() do{sl_prev=sl_cur;sl_cur=sl_next;sl_next=(sl_next==(NSLOT-1)*SLOTB)?0:sl_next+SLOTB;}while(0)
; #define WAIT_BAR(N) asm volatile("s_waitcnt vmcnt(" #N ") lgkmcnt(0)\n\ts_barrier":::"memory")
;   #define RESC() do{ if(resc){ asm volatile("s_waitcnt lgkmcnt(0)":::"memory"); \
;       _Pragma("unroll") for(int d_=0;d_<2;++d_) _Pragma("unroll") for(int r=0;r<16;++r)o[d_][r]*=wsf[crow(r,hi)]; } }while(0)
;   #define ROT() do{sl_prev=sl_cur;sl_cur=sl_next;sl_next=(sl_next==(NSLOT-1)*SLOTB)?0:sl_next+SLOTB;}while(0)
; template<int THRL,bool FIXED> __device__ __forceinline__ void attn_unit(int qb,const bf16*Qp,const unsigned char*__restrict__ K8h,const bf16*__restrict__ Vh,bf16*Op,int PO,char*shm){
;     ...
;   for(;t+5<NT;t+=2){
;     STEP(pB0,pB1,pA0,pA1,t,true,true,true);     WAIT_BAR(3); RESC(); ROT();
;     STEP(pA0,pA1,pB0,pB1,t+1,true,true,true);   WAIT_BAR(3); RESC(); ROT();
	s_add_i32 s50, s13, 0x2000
	s_cmpk_lg_i32 s13, 0x4000
	s_cselect_b32 s50, s50, 0
	s_and_b32 s23, s23, 0x6000
	v_add_u32_e32 v160, s23, v166
	ds_read_b64_tr_b16 v[120:121], v160 offset:24576
	ds_read_b64_tr_b16 v[122:123], v160 offset:25088
	v_add_f32_e32 v64, v96, v97
	v_add_f32_e32 v64, v98, v64
	v_add_f32_e32 v64, v99, v64
	v_add_f32_e32 v64, v100, v64
	v_add_f32_e32 v124, v101, v64
	v_mfma_scale_f32_32x32x64_f8f6f4 v[64:79], v[48:55], v[128:135], v[32:47], v242, v241 op_sel_hi:[0,0,0]
	v_cvt_pk_bf16_f32 v148, v96, v97
	v_cvt_pk_bf16_f32 v149, v98, v99
	ds_read_b64_tr_b16 v[96:97], v160 offset:28672
	ds_read_b64_tr_b16 v[98:99], v160 offset:29184
	v_add_f32_e32 v48, v102, v124
	v_add_f32_e32 v48, v103, v48
	v_add_f32_e32 v48, v104, v48
	v_add_f32_e32 v124, v105, v48
	v_mfma_scale_f32_32x32x64_f8f6f4 v[48:63], v[56:63], v[128:135], v[32:47], v242, v241 op_sel_hi:[0,0,0]
	v_cvt_pk_bf16_f32 v150, v100, v101
	v_cvt_pk_bf16_f32 v151, v102, v103
	ds_read_b64_tr_b16 v[100:101], v160 offset:25600
	ds_read_b64_tr_b16 v[102:103], v160 offset:26112
	v_add_f32_e32 v124, v106, v124
	v_add_f32_e32 v124, v107, v124
	v_add_f32_e32 v124, v108, v124
	v_add_f32_e32 v124, v109, v124
	v_cvt_pk_bf16_f32 v144, v104, v105
	v_cvt_pk_bf16_f32 v145, v106, v107
	ds_read_b64_tr_b16 v[104:105], v160 offset:29696
	ds_read_b64_tr_b16 v[106:107], v160 offset:30208
	v_add_f32_e32 v124, v110, v124
	v_add_f32_e32 v124, v111, v124
	v_add_f32_e32 v124, v80, v124
	v_add_f32_e32 v124, v81, v124
	v_cvt_pk_bf16_f32 v146, v108, v109
	v_cvt_pk_bf16_f32 v147, v110, v111
	ds_read_b64_tr_b16 v[108:109], v160 offset:26624
	ds_read_b64_tr_b16 v[110:111], v160 offset:27136
	v_add_f32_e32 v124, v82, v124
	v_add_f32_e32 v124, v83, v124
	v_add_f32_e32 v124, v84, v124
	v_add_f32_e32 v136, v85, v124
	v_cvt_pk_bf16_f32 v140, v80, v81
	v_cvt_pk_bf16_f32 v141, v82, v83
	ds_read_b64_tr_b16 v[124:125], v160 offset:30720
	ds_read_b64_tr_b16 v[126:127], v160 offset:31232
	v_add_f32_e32 v80, v86, v136
	v_add_f32_e32 v80, v87, v80
	v_add_f32_e32 v80, v88, v80
	v_add_f32_e32 v80, v89, v80
	v_cvt_pk_bf16_f32 v142, v84, v85
	v_cvt_pk_bf16_f32 v143, v86, v87
	ds_read_b64_tr_b16 v[168:169], v160 offset:27648
	ds_read_b64_tr_b16 v[170:171], v160 offset:28160
	v_add_f32_e32 v80, v90, v80
	v_add_f32_e32 v80, v91, v80
	v_add_f32_e32 v80, v92, v80
	v_add_f32_e32 v80, v93, v80
	v_cvt_pk_bf16_f32 v136, v88, v89
	v_cvt_pk_bf16_f32 v137, v90, v91
	ds_read_b64_tr_b16 v[172:173], v160 offset:31744
	ds_read_b64_tr_b16 v[174:175], v160 offset:32256
	v_add_f32_e32 v80, v94, v80
	v_add_f32_e32 v80, v95, v80
	v_add_f32_e32 v118, v119, v80
	v_cvt_pk_bf16_f32 v138, v92, v93
	v_cvt_pk_bf16_f32 v139, v94, v95
	s_add_i32 s13, s13, s29
	s_mov_b32 m0, s13
	v_lshl_add_u64 v[80:81], v[116:117], 0, s[56:57]
	global_load_lds_dwordx4 v[80:81], off
	s_add_i32 s13, s22, s44
	s_mov_b32 m0, s13
	s_nop 0
	global_load_lds_dwordx4 v[112:113], off
	s_waitcnt lgkmcnt(8)
	v_mfma_f32_32x32x16_bf16 v[0:15], v[148:151], v[120:123], v[0:15]
	v_exp_f32_e32 v64, v64
	v_exp_f32_e32 v65, v65
	v_exp_f32_e32 v66, v66
	v_exp_f32_e32 v67, v67
	v_mfma_f32_32x32x16_bf16 v[16:31], v[148:151], v[96:99], v[16:31]
	v_exp_f32_e32 v68, v68
	v_exp_f32_e32 v69, v69
	v_exp_f32_e32 v70, v70
	v_exp_f32_e32 v71, v71
	v_add_u32_e32 v84, s50, v165
	ds_read_b128 v[88:91], v84
	v_mfma_f32_32x32x16_bf16 v[0:15], v[144:147], v[100:103], v[0:15]
	v_exp_f32_e32 v72, v72
	v_exp_f32_e32 v73, v73
	v_exp_f32_e32 v74, v74
	v_exp_f32_e32 v75, v75
	ds_read_b128 v[92:95], v84 offset:1024
	v_mfma_f32_32x32x16_bf16 v[16:31], v[144:147], v[104:107], v[16:31]
	v_exp_f32_e32 v76, v76
	v_exp_f32_e32 v77, v77
	v_exp_f32_e32 v78, v78
	v_exp_f32_e32 v79, v79
	ds_read_b128 v[80:83], v84 offset:512
	s_waitcnt lgkmcnt(3)
	v_mfma_f32_32x32x16_bf16 v[0:15], v[140:143], v[108:111], v[0:15]
	v_exp_f32_e32 v48, v48
	v_exp_f32_e32 v49, v49
	v_exp_f32_e32 v50, v50
	v_exp_f32_e32 v51, v51
	ds_read_b128 v[84:87], v84 offset:1536
	v_mfma_f32_32x32x16_bf16 v[16:31], v[140:143], v[124:127], v[16:31]
	v_exp_f32_e32 v52, v52
	v_exp_f32_e32 v53, v53
	v_exp_f32_e32 v54, v54
	v_exp_f32_e32 v55, v55
	v_mfma_f32_32x32x16_bf16 v[0:15], v[136:139], v[168:171], v[0:15]
	v_exp_f32_e32 v56, v56
	v_exp_f32_e32 v57, v57
	v_exp_f32_e32 v58, v58
	v_exp_f32_e32 v59, v59
	v_mfma_f32_32x32x16_bf16 v[16:31], v[136:139], v[172:175], v[16:31]
	v_exp_f32_e32 v60, v60
	v_exp_f32_e32 v61, v61
	v_exp_f32_e32 v62, v62
	v_exp_f32_e32 v63, v63
	s_add_i32 s13, s50, 0x2000
	s_cmpk_lg_i32 s50, 0x4000
	s_cselect_b32 s13, s13, 0
	s_add_i32 s12, s12, 2
	s_waitcnt vmcnt(3) lgkmcnt(0)
	s_barrier
	s_add_u32 s10, s10, 0x4000
	s_addc_u32 s11, s11, 0
	v_lshl_add_u64 v[112:113], v[112:113], 0, s[40:41]
	s_cmpk_gt_u32 s12, 0xf8
	s_cbranch_scc0 .LBB0_543
;   #define RESC() do{ if(resc){ asm volatile("s_waitcnt lgkmcnt(0)":::"memory"); \
;       _Pragma("unroll") for(int d_=0;d_<2;++d_) _Pragma("unroll") for(int r=0;r<16;++r)o[d_][r]*=wsf[crow(r,hi)]; } }while(0)
;   #define ROT() do{sl_prev=sl_cur;sl_cur=sl_next;sl_next=(sl_next==(NSLOT-1)*SLOTB)?0:sl_next+SLOTB;}while(0)
;   #define ENDW(tt) do{ if((tt)+3<NT){WAIT_BAR(3);} else if((tt)+2<NT){WAIT_BAR(2);} else {WAIT_BAR(0);} }while(0)
;   #define RESC() do{ if(resc){ asm volatile("s_waitcnt lgkmcnt(0)":::"memory"); \
;       _Pragma("unroll") for(int d_=0;d_<4;++d_) _Pragma("unroll") for(int r=0;r<16;++r)o[d_][r]*=wsf[crow(r,hi)]; } }while(0)
;   #define ROT() do{sl_prev=sl_cur;sl_cur=sl_next;sl_next=(sl_next==(NSLOT-1)*SLOTB)?0:sl_next+SLOTB;}while(0)
;   #define ENDW(tt) do{ if((tt)+3<NT){WAIT_BAR(5);} else if((tt)+2<NT){WAIT_BAR(4);} else {WAIT_BAR(0);} }while(0)
;   #define RESC() do{ if(resc){ asm volatile("s_waitcnt lgkmcnt(0)":::"memory"); \
;       _Pragma("unroll") for(int d_=0;d_<2;++d_) _Pragma("unroll") for(int r=0;r<16;++r)o[d_][r]*=wsf[crow(r,hi)]; } }while(0)
;   #define ROT() do{sl_prev=sl_cur;sl_cur=sl_next;sl_next=(sl_next==(NSLOT-1)*SLOTB)?0:sl_next+SLOTB;}while(0)
;   #define ENDW(tt) do{ if((tt)+3<NT){WAIT_BAR(3);} else if((tt)+2<NT){WAIT_BAR(2);} else {WAIT_BAR(0);} }while(0)
; template<int THRL,bool FIXED> __device__ __forceinline__ void attn_unit(int qb,const bf16*Qp,const unsigned char*__restrict__ K8h,const bf16*__restrict__ Vh,bf16*Op,int PO,char*shm){
;     ...
;   for(;t+1<NT;t+=2){
;     STEP(pB0,pB1,pA0,pA1,t,(t+3<NT),(t+2<NT),(t+1<NT));       ENDW(t);   RESC(); ROT();
;     STEP(pA0,pA1,pB0,pB1,t+1,(t+4<NT),(t+3<NT),(t+2<NT));     ENDW(t+1); RESC(); ROT();
	s_mov_b32 m0, s101
	s_and_b32 s10, s34, 0x3fffffc0
	s_lshl_b32 s10, s10, 2
	s_add_i32 s12, s10, 0
	ds_read_b64_tr_b16 v[112:113], v166 offset:40960
	ds_read_b64_tr_b16 v[114:115], v166 offset:41472
	v_add_f32_e32 v96, v64, v65
	v_add_f32_e32 v96, v66, v96
	v_add_f32_e32 v96, v67, v96
	v_add_f32_e32 v96, v68, v96
	v_add_f32_e32 v116, v69, v96
	v_cvt_pk_bf16_f32 v148, v64, v65
	v_cvt_pk_bf16_f32 v149, v66, v67
	s_waitcnt lgkmcnt(4)
	v_mfma_scale_f32_32x32x64_f8f6f4 v[96:111], v[88:95], v[128:135], v[32:47], v242, v241 op_sel_hi:[0,0,0]
	ds_read_b64_tr_b16 v[64:65], v166 offset:45056
	ds_read_b64_tr_b16 v[66:67], v166 offset:45568
	v_add_f32_e32 v88, v70, v116
	v_add_f32_e32 v88, v71, v88
	v_add_f32_e32 v88, v72, v88
	v_add_f32_e32 v116, v73, v88
	v_cvt_pk_bf16_f32 v150, v68, v69
	v_cvt_pk_bf16_f32 v151, v70, v71
	s_waitcnt lgkmcnt(4)
	v_mfma_scale_f32_32x32x64_f8f6f4 v[80:95], v[80:87], v[128:135], v[32:47], v242, v241 op_sel_hi:[0,0,0]
	ds_read_b64_tr_b16 v[68:69], v166 offset:41984
	ds_read_b64_tr_b16 v[70:71], v166 offset:42496
	v_add_f32_e32 v116, v74, v116
	v_add_f32_e32 v116, v75, v116
	v_add_f32_e32 v116, v76, v116
	v_add_f32_e32 v116, v77, v116
	v_cvt_pk_bf16_f32 v144, v72, v73
	v_cvt_pk_bf16_f32 v145, v74, v75
	ds_read_b64_tr_b16 v[72:73], v166 offset:46080
	ds_read_b64_tr_b16 v[74:75], v166 offset:46592
	v_add_f32_e32 v116, v78, v116
	v_add_f32_e32 v116, v79, v116
	v_add_f32_e32 v116, v48, v116
	v_add_f32_e32 v116, v49, v116
	v_cvt_pk_bf16_f32 v146, v76, v77
	v_cvt_pk_bf16_f32 v147, v78, v79
	ds_read_b64_tr_b16 v[76:77], v166 offset:43008
	ds_read_b64_tr_b16 v[78:79], v166 offset:43520
	v_add_f32_e32 v116, v50, v116
	v_add_f32_e32 v116, v51, v116
	v_add_f32_e32 v116, v52, v116
	v_add_f32_e32 v116, v53, v116
	v_cvt_pk_bf16_f32 v140, v48, v49
	v_cvt_pk_bf16_f32 v141, v50, v51
	ds_read_b64_tr_b16 v[120:121], v166 offset:47104
	ds_read_b64_tr_b16 v[122:123], v166 offset:47616
	v_add_f32_e32 v48, v54, v116
	v_add_f32_e32 v48, v55, v48
	v_add_f32_e32 v48, v56, v48
	v_add_f32_e32 v48, v57, v48
	v_cvt_pk_bf16_f32 v142, v52, v53
	v_cvt_pk_bf16_f32 v143, v54, v55
	ds_read_b64_tr_b16 v[124:125], v166 offset:44032
	ds_read_b64_tr_b16 v[126:127], v166 offset:44544
	v_add_f32_e32 v48, v58, v48
	v_add_f32_e32 v48, v59, v48
	v_add_f32_e32 v48, v60, v48
	v_add_f32_e32 v48, v61, v48
	v_cvt_pk_bf16_f32 v136, v56, v57
	v_cvt_pk_bf16_f32 v137, v58, v59
	ds_read_b64_tr_b16 v[168:169], v166 offset:48128
	ds_read_b64_tr_b16 v[170:171], v166 offset:48640
	v_add_f32_e32 v48, v62, v48
	v_add_f32_e32 v48, v63, v48
	v_add_f32_e32 v48, 0, v48
	v_cvt_pk_bf16_f32 v138, v60, v61
	v_cvt_pk_bf16_f32 v139, v62, v63
	s_mov_b64 s[22:23], 0x1fc000
	v_add_f32_e32 v160, v118, v48
	s_add_i32 s10, s50, s29
	v_lshl_add_u64 v[48:49], v[154:155], 0, s[22:23]
	s_mov_b32 s11, m0
	s_mov_b32 m0, s10
	s_nop 0
	global_load_lds_dwordx4 v[48:49], off
	s_mov_b32 m0, s11
	s_mov_b64 s[10:11], 0x4728000
	s_cmp_lg_u32 0, -1
	v_lshl_add_u64 v[48:49], v[152:153], 0, s[10:11]
	s_cselect_b32 s10, 0, 0
	s_add_i32 s11, s10, s28
	s_add_i32 s22, s11, 0x8000
	s_mov_b32 s23, m0
	s_mov_b32 m0, s22
	s_nop 0
	global_load_lds_dwordx4 v[48:49], off
	s_mov_b32 m0, s23
	s_waitcnt lgkmcnt(14)
	v_mfma_f32_32x32x16_bf16 v[0:15], v[148:151], v[112:115], v[0:15]
	v_exp_f32_e32 v96, v96
	v_exp_f32_e32 v97, v97
	v_exp_f32_e32 v98, v98
	v_exp_f32_e32 v99, v99
	s_waitcnt lgkmcnt(12)
	v_mfma_f32_32x32x16_bf16 v[16:31], v[148:151], v[64:67], v[16:31]
	v_exp_f32_e32 v100, v100
	v_exp_f32_e32 v101, v101
	v_exp_f32_e32 v102, v102
	v_exp_f32_e32 v103, v103
	v_add_u32_e32 v60, s13, v165
	ds_read_b128 v[48:51], v60
	s_waitcnt lgkmcnt(11)
	v_mfma_f32_32x32x16_bf16 v[0:15], v[144:147], v[68:71], v[0:15]
	v_exp_f32_e32 v104, v104
	v_exp_f32_e32 v105, v105
	v_exp_f32_e32 v106, v106
	v_exp_f32_e32 v107, v107
	ds_read_b128 v[52:55], v60 offset:1024
	s_waitcnt lgkmcnt(10)
	v_mfma_f32_32x32x16_bf16 v[16:31], v[144:147], v[72:75], v[16:31]
	v_exp_f32_e32 v108, v108
	v_exp_f32_e32 v109, v109
	v_exp_f32_e32 v110, v110
	v_exp_f32_e32 v111, v111
	ds_read_b128 v[56:59], v60 offset:512
	s_waitcnt lgkmcnt(9)
	v_mfma_f32_32x32x16_bf16 v[0:15], v[140:143], v[76:79], v[0:15]
	v_exp_f32_e32 v80, v80
	v_exp_f32_e32 v81, v81
	v_exp_f32_e32 v82, v82
	v_exp_f32_e32 v83, v83
	ds_read_b128 v[60:63], v60 offset:1536
	s_waitcnt lgkmcnt(8)
	v_mfma_f32_32x32x16_bf16 v[16:31], v[140:143], v[120:123], v[16:31]
	v_exp_f32_e32 v84, v84
	v_exp_f32_e32 v85, v85
	v_exp_f32_e32 v86, v86
	v_exp_f32_e32 v87, v87
	s_waitcnt lgkmcnt(6)
	v_mfma_f32_32x32x16_bf16 v[0:15], v[136:139], v[124:127], v[0:15]
	v_exp_f32_e32 v88, v88
	v_exp_f32_e32 v89, v89
	v_exp_f32_e32 v90, v90
	v_exp_f32_e32 v91, v91
	s_waitcnt lgkmcnt(4)
	v_mfma_f32_32x32x16_bf16 v[16:31], v[136:139], v[168:171], v[16:31]
	v_exp_f32_e32 v92, v92
	v_exp_f32_e32 v93, v93
	v_exp_f32_e32 v94, v94
	v_exp_f32_e32 v95, v95
	s_waitcnt vmcnt(3) lgkmcnt(0)
	s_barrier
;   #define RESC() do{ if(resc){ asm volatile("s_waitcnt lgkmcnt(0)":::"memory"); \
;       _Pragma("unroll") for(int d_=0;d_<2;++d_) _Pragma("unroll") for(int r=0;r<16;++r)o[d_][r]*=wsf[crow(r,hi)]; } }while(0)
;   #define ROT() do{sl_prev=sl_cur;sl_cur=sl_next;sl_next=(sl_next==(NSLOT-1)*SLOTB)?0:sl_next+SLOTB;}while(0)
;   #define ENDW(tt) do{ if((tt)+3<NT){WAIT_BAR(3);} else if((tt)+2<NT){WAIT_BAR(2);} else {WAIT_BAR(0);} }while(0)
;   #define RESC() do{ if(resc){ asm volatile("s_waitcnt lgkmcnt(0)":::"memory"); \
;       _Pragma("unroll") for(int d_=0;d_<4;++d_) _Pragma("unroll") for(int r=0;r<16;++r)o[d_][r]*=wsf[crow(r,hi)]; } }while(0)
;   #define ROT() do{sl_prev=sl_cur;sl_cur=sl_next;sl_next=(sl_next==(NSLOT-1)*SLOTB)?0:sl_next+SLOTB;}while(0)
;   #define ENDW(tt) do{ if((tt)+3<NT){WAIT_BAR(5);} else if((tt)+2<NT){WAIT_BAR(4);} else {WAIT_BAR(0);} }while(0)
;   #define RESC() do{ if(resc){ asm volatile("s_waitcnt lgkmcnt(0)":::"memory"); \
;       _Pragma("unroll") for(int d_=0;d_<2;++d_) _Pragma("unroll") for(int r=0;r<16;++r)o[d_][r]*=wsf[crow(r,hi)]; } }while(0)
;   #define ROT() do{sl_prev=sl_cur;sl_cur=sl_next;sl_next=(sl_next==(NSLOT-1)*SLOTB)?0:sl_next+SLOTB;}while(0)
;   #define ENDW(tt) do{ if((tt)+3<NT){WAIT_BAR(3);} else if((tt)+2<NT){WAIT_BAR(2);} else {WAIT_BAR(0);} }while(0)
; template<int THRL,bool FIXED> __device__ __forceinline__ void attn_unit(int qb,const bf16*Qp,const unsigned char*__restrict__ K8h,const bf16*__restrict__ Vh,bf16*Op,int PO,char*shm){
;     ...
;   for(;t+1<NT;t+=2){
;     STEP(pB0,pB1,pA0,pA1,t,(t+3<NT),(t+2<NT),(t+1<NT));       ENDW(t);   RESC(); ROT();
;     STEP(pA0,pA1,pB0,pB1,t+1,(t+4<NT),(t+3<NT),(t+2<NT));     ENDW(t+1); RESC(); ROT();
	s_add_i32 s22, s13, 0x2000
	s_cmpk_lg_i32 s13, 0x4000
	s_cselect_b32 s22, s22, 0
	ds_read_b64_tr_b16 v[64:65], v166 offset:49152
	ds_read_b64_tr_b16 v[66:67], v166 offset:49664
	v_add_f32_e32 v68, v96, v97
	v_add_f32_e32 v68, v98, v68
	v_add_f32_e32 v68, v99, v68
	v_add_f32_e32 v68, v100, v68
	v_add_f32_e32 v72, v101, v68
	v_cvt_pk_bf16_f32 v148, v96, v97
	v_cvt_pk_bf16_f32 v149, v98, v99
	s_waitcnt lgkmcnt(4)
	v_mfma_scale_f32_32x32x64_f8f6f4 v[112:127], v[48:55], v[128:135], v[32:47], v242, v241 op_sel_hi:[0,0,0]
	ds_read_b64_tr_b16 v[68:69], v166 offset:53248
	ds_read_b64_tr_b16 v[70:71], v166 offset:53760
	v_add_f32_e32 v48, v102, v72
	v_add_f32_e32 v48, v103, v48
	v_add_f32_e32 v48, v104, v48
	v_add_f32_e32 v76, v105, v48
	s_waitcnt lgkmcnt(4)
	v_mfma_scale_f32_32x32x64_f8f6f4 v[48:63], v[56:63], v[128:135], v[32:47], v242, v241 op_sel_hi:[0,0,0]
	v_cvt_pk_bf16_f32 v150, v100, v101
	v_cvt_pk_bf16_f32 v151, v102, v103
	ds_read_b64_tr_b16 v[72:73], v166 offset:50176
	ds_read_b64_tr_b16 v[74:75], v166 offset:50688
	v_add_f32_e32 v76, v106, v76
	v_add_f32_e32 v76, v107, v76
	v_add_f32_e32 v76, v108, v76
	v_add_f32_e32 v96, v109, v76
	v_cvt_pk_bf16_f32 v144, v104, v105
	v_cvt_pk_bf16_f32 v145, v106, v107
	ds_read_b64_tr_b16 v[76:77], v166 offset:54272
	ds_read_b64_tr_b16 v[78:79], v166 offset:54784
	v_add_f32_e32 v96, v110, v96
	v_add_f32_e32 v96, v111, v96
	v_add_f32_e32 v96, v80, v96
	v_add_f32_e32 v100, v81, v96
	v_cvt_pk_bf16_f32 v146, v108, v109
	v_cvt_pk_bf16_f32 v147, v110, v111
	ds_read_b64_tr_b16 v[96:97], v166 offset:51200
	ds_read_b64_tr_b16 v[98:99], v166 offset:51712
	v_add_f32_e32 v100, v82, v100
	v_add_f32_e32 v100, v83, v100
	v_add_f32_e32 v100, v84, v100
	v_add_f32_e32 v100, v85, v100
	v_cvt_pk_bf16_f32 v140, v80, v81
	v_cvt_pk_bf16_f32 v141, v82, v83
	ds_read_b64_tr_b16 v[80:81], v166 offset:55296
	ds_read_b64_tr_b16 v[82:83], v166 offset:55808
	v_add_f32_e32 v100, v86, v100
	v_add_f32_e32 v100, v87, v100
	v_add_f32_e32 v100, v88, v100
	v_add_f32_e32 v100, v89, v100
	v_cvt_pk_bf16_f32 v142, v84, v85
	v_cvt_pk_bf16_f32 v143, v86, v87
	ds_read_b64_tr_b16 v[84:85], v166 offset:52224
	ds_read_b64_tr_b16 v[86:87], v166 offset:52736
	v_add_f32_e32 v100, v90, v100
	v_add_f32_e32 v100, v91, v100
	v_add_f32_e32 v100, v92, v100
	v_add_f32_e32 v100, v93, v100
	v_cvt_pk_bf16_f32 v136, v88, v89
	v_cvt_pk_bf16_f32 v137, v90, v91
	ds_read_b64_tr_b16 v[88:89], v166 offset:56320
	ds_read_b64_tr_b16 v[90:91], v166 offset:56832
	v_add_f32_e32 v100, v94, v100
	v_add_f32_e32 v100, v95, v100
	v_add_f32_e32 v100, 0, v100
	v_cvt_pk_bf16_f32 v138, v92, v93
	v_cvt_pk_bf16_f32 v139, v94, v95
	s_mov_b64 s[50:51], 0x1fe000
	s_add_i32 s13, s13, s29
	v_lshl_add_u64 v[92:93], v[154:155], 0, s[50:51]
	s_mov_b32 s23, m0
	s_mov_b32 m0, s13
	s_nop 0
	global_load_lds_dwordx4 v[92:93], off
	s_mov_b32 m0, s23
	v_lshl_add_u64 v[92:93], v[152:153], 0, s[42:43]
	s_add_i32 s11, s11, 0xa000
	s_mov_b32 s13, m0
	s_mov_b32 m0, s11
	s_nop 0
	global_load_lds_dwordx4 v[92:93], off
	s_mov_b32 m0, s13
	v_add_f32_e32 v160, v160, v100
	s_waitcnt lgkmcnt(14)
	v_mfma_f32_32x32x16_bf16 v[0:15], v[148:151], v[64:67], v[0:15]
	v_exp_f32_e32 v112, v112
	v_exp_f32_e32 v113, v113
	v_exp_f32_e32 v114, v114
	v_exp_f32_e32 v115, v115
	s_waitcnt lgkmcnt(12)
	v_mfma_f32_32x32x16_bf16 v[16:31], v[148:151], v[68:71], v[16:31]
	v_exp_f32_e32 v116, v116
	v_exp_f32_e32 v117, v117
	v_exp_f32_e32 v118, v118
	v_exp_f32_e32 v119, v119
	v_add_u32_e32 v92, s22, v165
	ds_read_b128 v[64:67], v92
	s_waitcnt lgkmcnt(11)
	v_mfma_f32_32x32x16_bf16 v[0:15], v[144:147], v[72:75], v[0:15]
	v_exp_f32_e32 v120, v120
	v_exp_f32_e32 v121, v121
	v_exp_f32_e32 v122, v122
	v_exp_f32_e32 v123, v123
	ds_read_b128 v[68:71], v92 offset:1024
	s_waitcnt lgkmcnt(10)
	v_mfma_f32_32x32x16_bf16 v[16:31], v[144:147], v[76:79], v[16:31]
	v_exp_f32_e32 v124, v124
	v_exp_f32_e32 v125, v125
	v_exp_f32_e32 v126, v126
	v_exp_f32_e32 v127, v127
	ds_read_b128 v[72:75], v92 offset:512
	s_waitcnt lgkmcnt(9)
	v_mfma_f32_32x32x16_bf16 v[0:15], v[140:143], v[96:99], v[0:15]
	v_exp_f32_e32 v48, v48
	v_exp_f32_e32 v49, v49
	v_exp_f32_e32 v50, v50
	v_exp_f32_e32 v51, v51
	ds_read_b128 v[76:79], v92 offset:1536
	s_waitcnt lgkmcnt(8)
	v_mfma_f32_32x32x16_bf16 v[16:31], v[140:143], v[80:83], v[16:31]
	v_exp_f32_e32 v52, v52
	v_exp_f32_e32 v53, v53
	v_exp_f32_e32 v54, v54
	v_exp_f32_e32 v55, v55
	s_waitcnt lgkmcnt(6)
	v_mfma_f32_32x32x16_bf16 v[0:15], v[136:139], v[84:87], v[0:15]
	v_exp_f32_e32 v56, v56
	v_exp_f32_e32 v57, v57
	v_exp_f32_e32 v58, v58
	v_exp_f32_e32 v59, v59
	s_waitcnt lgkmcnt(4)
	v_mfma_f32_32x32x16_bf16 v[16:31], v[136:139], v[88:91], v[16:31]
	v_exp_f32_e32 v60, v60
	v_exp_f32_e32 v61, v61
	v_exp_f32_e32 v62, v62
	v_exp_f32_e32 v63, v63
	s_waitcnt vmcnt(3) lgkmcnt(0)
	s_barrier
;   #define RESC() do{ if(resc){ asm volatile("s_waitcnt lgkmcnt(0)":::"memory"); \
;       _Pragma("unroll") for(int d_=0;d_<2;++d_) _Pragma("unroll") for(int r=0;r<16;++r)o[d_][r]*=wsf[crow(r,hi)]; } }while(0)
;   #define ROT() do{sl_prev=sl_cur;sl_cur=sl_next;sl_next=(sl_next==(NSLOT-1)*SLOTB)?0:sl_next+SLOTB;}while(0)
;   #define ENDW(tt) do{ if((tt)+3<NT){WAIT_BAR(3);} else if((tt)+2<NT){WAIT_BAR(2);} else {WAIT_BAR(0);} }while(0)
;   #define RESC() do{ if(resc){ asm volatile("s_waitcnt lgkmcnt(0)":::"memory"); \
;       _Pragma("unroll") for(int d_=0;d_<4;++d_) _Pragma("unroll") for(int r=0;r<16;++r)o[d_][r]*=wsf[crow(r,hi)]; } }while(0)
;   #define ROT() do{sl_prev=sl_cur;sl_cur=sl_next;sl_next=(sl_next==(NSLOT-1)*SLOTB)?0:sl_next+SLOTB;}while(0)
;   #define ENDW(tt) do{ if((tt)+3<NT){WAIT_BAR(5);} else if((tt)+2<NT){WAIT_BAR(4);} else {WAIT_BAR(0);} }while(0)
;   #define RESC() do{ if(resc){ asm volatile("s_waitcnt lgkmcnt(0)":::"memory"); \
;       _Pragma("unroll") for(int d_=0;d_<2;++d_) _Pragma("unroll") for(int r=0;r<16;++r)o[d_][r]*=wsf[crow(r,hi)]; } }while(0)
;   #define ROT() do{sl_prev=sl_cur;sl_cur=sl_next;sl_next=(sl_next==(NSLOT-1)*SLOTB)?0:sl_next+SLOTB;}while(0)
;   #define ENDW(tt) do{ if((tt)+3<NT){WAIT_BAR(3);} else if((tt)+2<NT){WAIT_BAR(2);} else {WAIT_BAR(0);} }while(0)
; template<int THRL,bool FIXED> __device__ __forceinline__ void attn_unit(int qb,const bf16*Qp,const unsigned char*__restrict__ K8h,const bf16*__restrict__ Vh,bf16*Op,int PO,char*shm){
;     ...
;   for(;t+1<NT;t+=2){
;     STEP(pB0,pB1,pA0,pA1,t,(t+3<NT),(t+2<NT),(t+1<NT));       ENDW(t);   RESC(); ROT();
;     STEP(pA0,pA1,pB0,pB1,t+1,(t+4<NT),(t+3<NT),(t+2<NT));     ENDW(t+1); RESC(); ROT();
	s_add_i32 s11, s22, 0x2000
	s_cmpk_lg_i32 s22, 0x4000
	s_cselect_b32 s11, s11, 0
	ds_read_b64_tr_b16 v[80:81], v166 offset:24576
	ds_read_b64_tr_b16 v[82:83], v166 offset:25088
	v_add_f32_e32 v84, v112, v113
	v_add_f32_e32 v84, v114, v84
	v_add_f32_e32 v84, v115, v84
	v_add_f32_e32 v84, v116, v84
	v_add_f32_e32 v88, v117, v84
	v_cvt_pk_bf16_f32 v148, v112, v113
	v_cvt_pk_bf16_f32 v149, v114, v115
	s_waitcnt lgkmcnt(4)
	v_mfma_scale_f32_32x32x64_f8f6f4 v[96:111], v[64:71], v[128:135], v[32:47], v242, v241 op_sel_hi:[0,0,0]
	ds_read_b64_tr_b16 v[84:85], v166 offset:28672
	ds_read_b64_tr_b16 v[86:87], v166 offset:29184
	v_add_f32_e32 v64, v118, v88
	v_add_f32_e32 v64, v119, v64
	v_add_f32_e32 v64, v120, v64
	v_add_f32_e32 v92, v121, v64
	v_cvt_pk_bf16_f32 v150, v116, v117
	v_cvt_pk_bf16_f32 v151, v118, v119
	s_waitcnt lgkmcnt(4)
	v_mfma_scale_f32_32x32x64_f8f6f4 v[64:79], v[72:79], v[128:135], v[32:47], v242, v241 op_sel_hi:[0,0,0]
	ds_read_b64_tr_b16 v[88:89], v166 offset:25600
	ds_read_b64_tr_b16 v[90:91], v166 offset:26112
	v_add_f32_e32 v92, v122, v92
	v_add_f32_e32 v92, v123, v92
	v_add_f32_e32 v92, v124, v92
	v_add_f32_e32 v112, v125, v92
	v_cvt_pk_bf16_f32 v144, v120, v121
	v_cvt_pk_bf16_f32 v145, v122, v123
	ds_read_b64_tr_b16 v[92:93], v166 offset:29696
	ds_read_b64_tr_b16 v[94:95], v166 offset:30208
	v_add_f32_e32 v112, v126, v112
	v_add_f32_e32 v112, v127, v112
	v_add_f32_e32 v112, v48, v112
	v_add_f32_e32 v116, v49, v112
	v_cvt_pk_bf16_f32 v146, v124, v125
	v_cvt_pk_bf16_f32 v147, v126, v127
	ds_read_b64_tr_b16 v[112:113], v166 offset:26624
	ds_read_b64_tr_b16 v[114:115], v166 offset:27136
	v_add_f32_e32 v116, v50, v116
	v_add_f32_e32 v116, v51, v116
	v_add_f32_e32 v116, v52, v116
	v_add_f32_e32 v120, v53, v116
	v_cvt_pk_bf16_f32 v140, v48, v49
	v_cvt_pk_bf16_f32 v141, v50, v51
	ds_read_b64_tr_b16 v[116:117], v166 offset:30720
	ds_read_b64_tr_b16 v[118:119], v166 offset:31232
	v_add_f32_e32 v48, v54, v120
	v_add_f32_e32 v48, v55, v48
	v_add_f32_e32 v48, v56, v48
	v_add_f32_e32 v48, v57, v48
	v_cvt_pk_bf16_f32 v142, v52, v53
	v_cvt_pk_bf16_f32 v143, v54, v55
	ds_read_b64_tr_b16 v[120:121], v166 offset:27648
	ds_read_b64_tr_b16 v[122:123], v166 offset:28160
	v_add_f32_e32 v48, v58, v48
	v_add_f32_e32 v48, v59, v48
	v_add_f32_e32 v48, v60, v48
	v_add_f32_e32 v48, v61, v48
	v_cvt_pk_bf16_f32 v136, v56, v57
	v_cvt_pk_bf16_f32 v137, v58, v59
	ds_read_b64_tr_b16 v[124:125], v166 offset:31744
	ds_read_b64_tr_b16 v[126:127], v166 offset:32256
	v_add_f32_e32 v48, v62, v48
	v_add_f32_e32 v48, v63, v48
	v_add_f32_e32 v48, 0, v48
	v_cvt_pk_bf16_f32 v138, v60, v61
	v_cvt_pk_bf16_f32 v139, v62, v63
	s_add_i32 s10, s10, 0xc000
	v_add_f32_e32 v160, v160, v48
	v_lshl_add_u64 v[48:49], v[152:153], 0, s[46:47]
	s_add_i32 s28, s28, s10
	s_mov_b32 s13, m0
	s_mov_b32 m0, s28
	s_nop 0
	global_load_lds_dwordx4 v[48:49], off
	s_mov_b32 m0, s13
	s_waitcnt lgkmcnt(14)
	v_mfma_f32_32x32x16_bf16 v[0:15], v[148:151], v[80:83], v[0:15]
	v_exp_f32_e32 v96, v96
	v_exp_f32_e32 v97, v97
	v_exp_f32_e32 v98, v98
	v_exp_f32_e32 v99, v99
	s_waitcnt lgkmcnt(12)
	v_mfma_f32_32x32x16_bf16 v[16:31], v[148:151], v[84:87], v[16:31]
	v_exp_f32_e32 v100, v100
	v_exp_f32_e32 v101, v101
	v_exp_f32_e32 v102, v102
	v_exp_f32_e32 v103, v103
	v_add_u32_e32 v60, s11, v165
	ds_read_b128 v[48:51], v60
	s_waitcnt lgkmcnt(11)
	v_mfma_f32_32x32x16_bf16 v[0:15], v[144:147], v[88:91], v[0:15]
	v_exp_f32_e32 v104, v104
	v_exp_f32_e32 v105, v105
	v_exp_f32_e32 v106, v106
	v_exp_f32_e32 v107, v107
	ds_read_b128 v[52:55], v60 offset:1024
	s_waitcnt lgkmcnt(10)
	v_mfma_f32_32x32x16_bf16 v[16:31], v[144:147], v[92:95], v[16:31]
	v_exp_f32_e32 v108, v108
	v_exp_f32_e32 v109, v109
	v_exp_f32_e32 v110, v110
	v_exp_f32_e32 v111, v111
	ds_read_b128 v[56:59], v60 offset:512
	s_waitcnt lgkmcnt(9)
	v_mfma_f32_32x32x16_bf16 v[0:15], v[140:143], v[112:115], v[0:15]
	v_exp_f32_e32 v64, v64
	v_exp_f32_e32 v65, v65
	v_exp_f32_e32 v66, v66
	v_exp_f32_e32 v67, v67
	ds_read_b128 v[60:63], v60 offset:1536
	s_waitcnt lgkmcnt(8)
	v_mfma_f32_32x32x16_bf16 v[16:31], v[140:143], v[116:119], v[16:31]
	v_exp_f32_e32 v68, v68
	v_exp_f32_e32 v69, v69
	v_exp_f32_e32 v70, v70
	v_exp_f32_e32 v71, v71
	s_waitcnt lgkmcnt(6)
	v_mfma_f32_32x32x16_bf16 v[0:15], v[136:139], v[120:123], v[0:15]
	v_exp_f32_e32 v72, v72
	v_exp_f32_e32 v73, v73
	v_exp_f32_e32 v74, v74
	v_exp_f32_e32 v75, v75
	s_waitcnt lgkmcnt(4)
	v_mfma_f32_32x32x16_bf16 v[16:31], v[136:139], v[124:127], v[16:31]
	v_exp_f32_e32 v76, v76
	v_exp_f32_e32 v77, v77
	v_exp_f32_e32 v78, v78
	v_exp_f32_e32 v79, v79
	s_waitcnt vmcnt(2) lgkmcnt(0)
	s_barrier
;   #define RESC() do{ if(resc){ asm volatile("s_waitcnt lgkmcnt(0)":::"memory"); \
;       _Pragma("unroll") for(int d_=0;d_<2;++d_) _Pragma("unroll") for(int r=0;r<16;++r)o[d_][r]*=wsf[crow(r,hi)]; } }while(0)
;   #define ROT() do{sl_prev=sl_cur;sl_cur=sl_next;sl_next=(sl_next==(NSLOT-1)*SLOTB)?0:sl_next+SLOTB;}while(0)
;   #define ENDW(tt) do{ if((tt)+3<NT){WAIT_BAR(3);} else if((tt)+2<NT){WAIT_BAR(2);} else {WAIT_BAR(0);} }while(0)
;   #define RESC() do{ if(resc){ asm volatile("s_waitcnt lgkmcnt(0)":::"memory"); \
;       _Pragma("unroll") for(int d_=0;d_<4;++d_) _Pragma("unroll") for(int r=0;r<16;++r)o[d_][r]*=wsf[crow(r,hi)]; } }while(0)
;   #define ROT() do{sl_prev=sl_cur;sl_cur=sl_next;sl_next=(sl_next==(NSLOT-1)*SLOTB)?0:sl_next+SLOTB;}while(0)
;   #define ENDW(tt) do{ if((tt)+3<NT){WAIT_BAR(5);} else if((tt)+2<NT){WAIT_BAR(4);} else {WAIT_BAR(0);} }while(0)
;   #define RESC() do{ if(resc){ asm volatile("s_waitcnt lgkmcnt(0)":::"memory"); \
;       _Pragma("unroll") for(int d_=0;d_<2;++d_) _Pragma("unroll") for(int r=0;r<16;++r)o[d_][r]*=wsf[crow(r,hi)]; } }while(0)
;   #define ROT() do{sl_prev=sl_cur;sl_cur=sl_next;sl_next=(sl_next==(NSLOT-1)*SLOTB)?0:sl_next+SLOTB;}while(0)
;   #define ENDW(tt) do{ if((tt)+3<NT){WAIT_BAR(3);} else if((tt)+2<NT){WAIT_BAR(2);} else {WAIT_BAR(0);} }while(0)
; template<int THRL,bool FIXED> __device__ __forceinline__ void attn_unit(int qb,const bf16*Qp,const unsigned char*__restrict__ K8h,const bf16*__restrict__ Vh,bf16*Op,int PO,char*shm){
;     ...
;   for(;t+1<NT;t+=2){
;     STEP(pB0,pB1,pA0,pA1,t,(t+3<NT),(t+2<NT),(t+1<NT));       ENDW(t);   RESC(); ROT();
;     STEP(pA0,pA1,pB0,pB1,t+1,(t+4<NT),(t+3<NT),(t+2<NT));     ENDW(t+1); RESC(); ROT();
	s_add_i32 s13, s11, 0x2000
	s_cmpk_lg_i32 s11, 0x4000
	s_cselect_b32 s11, s13, 0
	ds_read_b64_tr_b16 v[112:113], v166 offset:32768
	ds_read_b64_tr_b16 v[114:115], v166 offset:33280
	v_add_f32_e32 v80, v96, v97
	v_add_f32_e32 v80, v98, v80
	v_add_f32_e32 v80, v99, v80
	v_add_f32_e32 v80, v100, v80
	v_add_f32_e32 v116, v101, v80
	v_cvt_pk_bf16_f32 v148, v96, v97
	v_cvt_pk_bf16_f32 v149, v98, v99
	s_waitcnt lgkmcnt(4)
	v_mfma_scale_f32_32x32x64_f8f6f4 v[80:95], v[48:55], v[128:135], v[32:47], v242, v241 op_sel_hi:[0,0,0]
	ds_read_b64_tr_b16 v[96:97], v166 offset:36864
	ds_read_b64_tr_b16 v[98:99], v166 offset:37376
	v_add_f32_e32 v48, v102, v116
	v_add_f32_e32 v48, v103, v48
	v_add_f32_e32 v48, v104, v48
	v_add_f32_e32 v116, v105, v48
	s_waitcnt lgkmcnt(4)
	v_mfma_scale_f32_32x32x64_f8f6f4 v[48:63], v[56:63], v[128:135], v[32:47], v242, v241 op_sel_hi:[0,0,0]
	v_cvt_pk_bf16_f32 v150, v100, v101
	v_cvt_pk_bf16_f32 v151, v102, v103
	ds_read_b64_tr_b16 v[100:101], v166 offset:33792
	ds_read_b64_tr_b16 v[102:103], v166 offset:34304
	v_add_f32_e32 v116, v106, v116
	v_add_f32_e32 v116, v107, v116
	v_add_f32_e32 v116, v108, v116
	v_add_f32_e32 v120, v109, v116
	v_cvt_pk_bf16_f32 v144, v104, v105
	v_cvt_pk_bf16_f32 v145, v106, v107
	ds_read_b64_tr_b16 v[116:117], v166 offset:37888
	ds_read_b64_tr_b16 v[118:119], v166 offset:38400
	v_add_f32_e32 v104, v110, v120
	v_add_f32_e32 v104, v111, v104
	v_add_f32_e32 v104, v64, v104
	v_add_f32_e32 v104, v65, v104
	v_cvt_pk_bf16_f32 v146, v108, v109
	v_cvt_pk_bf16_f32 v147, v110, v111
	ds_read_b64_tr_b16 v[120:121], v166 offset:34816
	ds_read_b64_tr_b16 v[122:123], v166 offset:35328
	v_add_f32_e32 v104, v66, v104
	v_add_f32_e32 v104, v67, v104
	v_add_f32_e32 v104, v68, v104
	v_add_f32_e32 v104, v69, v104
	v_cvt_pk_bf16_f32 v140, v64, v65
	v_cvt_pk_bf16_f32 v141, v66, v67
	ds_read_b64_tr_b16 v[124:125], v166 offset:38912
	ds_read_b64_tr_b16 v[126:127], v166 offset:39424
	v_add_f32_e32 v64, v70, v104
	v_add_f32_e32 v64, v71, v64
	v_add_f32_e32 v64, v72, v64
	v_add_f32_e32 v64, v73, v64
	v_cvt_pk_bf16_f32 v142, v68, v69
	v_cvt_pk_bf16_f32 v143, v70, v71
	ds_read_b64_tr_b16 v[152:153], v166 offset:35840
	ds_read_b64_tr_b16 v[154:155], v166 offset:36352
	v_add_f32_e32 v64, v74, v64
	v_add_f32_e32 v64, v75, v64
	v_add_f32_e32 v64, v76, v64
	v_add_f32_e32 v64, v77, v64
	v_cvt_pk_bf16_f32 v136, v72, v73
	v_cvt_pk_bf16_f32 v137, v74, v75
	ds_read_b64_tr_b16 v[72:73], v166 offset:39936
	ds_read_b64_tr_b16 v[74:75], v166 offset:40448
	v_add_f32_e32 v64, v78, v64
	v_add_f32_e32 v64, v79, v64
	v_add_f32_e32 v64, 0, v64
	v_cvt_pk_bf16_f32 v138, v76, v77
	v_cvt_pk_bf16_f32 v139, v78, v79
	s_nop 0
	v_add_f32_e32 v104, v160, v64
	s_waitcnt lgkmcnt(14)
	v_mfma_f32_32x32x16_bf16 v[0:15], v[148:151], v[112:115], v[0:15]
	v_exp_f32_e32 v80, v80
	v_exp_f32_e32 v81, v81
	v_exp_f32_e32 v82, v82
	v_exp_f32_e32 v83, v83
	s_waitcnt lgkmcnt(12)
	v_mfma_f32_32x32x16_bf16 v[16:31], v[148:151], v[96:99], v[16:31]
	v_exp_f32_e32 v84, v84
	v_exp_f32_e32 v85, v85
	v_exp_f32_e32 v86, v86
	v_exp_f32_e32 v87, v87
	v_add_u32_e32 v76, s11, v165
	ds_read_b128 v[64:67], v76
	s_waitcnt lgkmcnt(11)
	v_mfma_f32_32x32x16_bf16 v[0:15], v[144:147], v[100:103], v[0:15]
	v_exp_f32_e32 v88, v88
	v_exp_f32_e32 v89, v89
	v_exp_f32_e32 v90, v90
	v_exp_f32_e32 v91, v91
	ds_read_b128 v[68:71], v76 offset:1024
	s_waitcnt lgkmcnt(10)
	v_mfma_f32_32x32x16_bf16 v[16:31], v[144:147], v[116:119], v[16:31]
	v_exp_f32_e32 v92, v92
	v_exp_f32_e32 v93, v93
	v_exp_f32_e32 v94, v94
	v_exp_f32_e32 v95, v95
	ds_read_b128 v[106:109], v76 offset:512
	s_waitcnt lgkmcnt(9)
	v_mfma_f32_32x32x16_bf16 v[0:15], v[140:143], v[120:123], v[0:15]
	v_exp_f32_e32 v48, v48
	v_exp_f32_e32 v49, v49
	v_exp_f32_e32 v50, v50
	v_exp_f32_e32 v51, v51
	ds_read_b128 v[110:113], v76 offset:1536
	s_waitcnt lgkmcnt(8)
	v_mfma_f32_32x32x16_bf16 v[16:31], v[140:143], v[124:127], v[16:31]
	v_exp_f32_e32 v52, v52
	v_exp_f32_e32 v53, v53
	v_exp_f32_e32 v54, v54
	v_exp_f32_e32 v55, v55
	s_waitcnt lgkmcnt(6)
	v_mfma_f32_32x32x16_bf16 v[0:15], v[136:139], v[152:155], v[0:15]
	v_exp_f32_e32 v56, v56
	v_exp_f32_e32 v57, v57
	v_exp_f32_e32 v58, v58
	v_exp_f32_e32 v59, v59
	s_waitcnt lgkmcnt(4)
	v_mfma_f32_32x32x16_bf16 v[16:31], v[136:139], v[72:75], v[16:31]
	v_exp_f32_e32 v60, v60
	v_exp_f32_e32 v61, v61
	v_exp_f32_e32 v62, v62
	v_exp_f32_e32 v63, v63
	s_waitcnt vmcnt(0) lgkmcnt(0)
	s_barrier
; #define SBAR() __builtin_amdgcn_sched_barrier(0)
;   #define RESC() do{ if(resc){ asm volatile("s_waitcnt lgkmcnt(0)":::"memory"); \
;       _Pragma("unroll") for(int d_=0;d_<2;++d_) _Pragma("unroll") for(int r=0;r<16;++r)o[d_][r]*=wsf[crow(r,hi)]; } }while(0)
;   #define PKW(P,B) cvtpk_s(P[B],P[B+1])
; #define SBAR() __builtin_amdgcn_sched_barrier(0)
;   #define RESC() do{ if(resc){ asm volatile("s_waitcnt lgkmcnt(0)":::"memory"); \
;       _Pragma("unroll") for(int d_=0;d_<4;++d_) _Pragma("unroll") for(int r=0;r<16;++r)o[d_][r]*=wsf[crow(r,hi)]; } }while(0)
;   #define PKW(P,B) cvtpk_s(P[B],P[B+1])
; #define SBAR() __builtin_amdgcn_sched_barrier(0)
;   #define RESC() do{ if(resc){ asm volatile("s_waitcnt lgkmcnt(0)":::"memory"); \
;       _Pragma("unroll") for(int d_=0;d_<2;++d_) _Pragma("unroll") for(int r=0;r<16;++r)o[d_][r]*=wsf[crow(r,hi)]; } }while(0)
; __device__ __forceinline__ void pv(f32x16*o,int vb,bf16x8 pa0,bf16x8 pa1,bf16x8 pa2,bf16x8 pa3){
;   #pragma unroll
;   for(int d0=0;d0<2;++d0){s16x4 lo[4],hi[4];
;     #pragma unroll
;     for(int ks=0;ks<4;++ks){
;       asm volatile("ds_read_b64_tr_b16 %0,%1 offset:%c2":"=&v"(lo[ks]):"v"(vb),"i"(d0*4096+ks*1024):"memory");
;       asm volatile("ds_read_b64_tr_b16 %0,%1 offset:%c2":"=&v"(hi[ks]):"v"(vb),"i"(d0*4096+ks*1024+512):"memory");}
;     asm volatile("s_waitcnt lgkmcnt(0)":::"memory");SBAR();
;     ...
;     o[d0]=__builtin_amdgcn_mfma_f32_32x32x16_bf16(pa0,PK(0),o[d0],0,0,0);
;     o[d0]=__builtin_amdgcn_mfma_f32_32x32x16_bf16(pa1,PK(1),o[d0],0,0,0);
;     o[d0]=__builtin_amdgcn_mfma_f32_32x32x16_bf16(pa2,PK(2),o[d0],0,0,0);
;     o[d0]=__builtin_amdgcn_mfma_f32_32x32x16_bf16(pa3,PK(3),o[d0],0,0,0);
;     ...
;   }
; }
; template<int THRL,bool FIXED> __device__ __forceinline__ void attn_unit(int qb,const bf16*Qp,const unsigned char*__restrict__ K8h,const bf16*__restrict__ Vh,bf16*Op,int PO,char*shm){
;     ...
;   STEP(pB0,pB1,pA0,pA1,NT-1,false,false,false); RESC();
;   { float sacc=pB0[0]+pB0[1]; _Pragma("unroll") for(int r=2;r<16;++r)sacc+=pB0[r]; _Pragma("unroll") for(int r=0;r<16;++r)sacc+=pB1[r]; l_reg+=sacc;
;     pw0=(u32x4){PKW(pB0,0),PKW(pB0,2),PKW(pB0,4),PKW(pB0,6)};pw1=(u32x4){PKW(pB0,8),PKW(pB0,10),PKW(pB0,12),PKW(pB0,14)};pw2=(u32x4){PKW(pB1,0),PKW(pB1,2),PKW(pB1,4),PKW(pB1,6)};pw3=(u32x4){PKW(pB1,8),PKW(pB1,10),PKW(pB1,12),PKW(pB1,14)};
;     SBAR(); pv(o,vb0+VSL(NT-1),PAF(0),PAF(1),PAF(2),PAF(3)); }
	ds_read_b64_tr_b16 v[96:97], v166 offset:40960
	ds_read_b64_tr_b16 v[98:99], v166 offset:41472
	v_add_f32_e32 v72, v80, v81
	v_add_f32_e32 v72, v82, v72
	v_add_f32_e32 v72, v83, v72
	v_add_f32_e32 v72, v84, v72
	v_add_f32_e32 v100, v85, v72
	v_cvt_pk_bf16_f32 v148, v80, v81
	v_cvt_pk_bf16_f32 v149, v82, v83
	s_waitcnt lgkmcnt(4)
	v_mfma_scale_f32_32x32x64_f8f6f4 v[64:79], v[64:71], v[128:135], v[32:47], v242, v241 op_sel_hi:[0,0,0]
	ds_read_b64_tr_b16 v[80:81], v166 offset:45056
	ds_read_b64_tr_b16 v[82:83], v166 offset:45568
	s_waitcnt lgkmcnt(4)
	v_mfma_scale_f32_32x32x64_f8f6f4 v[32:47], v[106:113], v[128:135], v[32:47], v242, v241 op_sel_hi:[0,0,0]
	v_add_f32_e32 v100, v86, v100
	v_add_f32_e32 v100, v87, v100
	v_add_f32_e32 v100, v88, v100
	v_add_f32_e32 v105, v89, v100
	v_cvt_pk_bf16_f32 v150, v84, v85
	v_cvt_pk_bf16_f32 v151, v86, v87
	ds_read_b64_tr_b16 v[100:101], v166 offset:41984
	ds_read_b64_tr_b16 v[102:103], v166 offset:42496
	v_add_f32_e32 v84, v90, v105
	v_add_f32_e32 v84, v91, v84
	v_add_f32_e32 v84, v92, v84
	v_add_f32_e32 v105, v93, v84
	v_cvt_pk_bf16_f32 v144, v88, v89
	v_cvt_pk_bf16_f32 v145, v90, v91
	ds_read_b64_tr_b16 v[84:85], v166 offset:46080
	ds_read_b64_tr_b16 v[86:87], v166 offset:46592
	v_add_f32_e32 v88, v94, v105
	v_add_f32_e32 v88, v95, v88
	v_add_f32_e32 v88, v48, v88
	v_add_f32_e32 v105, v49, v88
	v_cvt_pk_bf16_f32 v146, v92, v93
	v_cvt_pk_bf16_f32 v147, v94, v95
	ds_read_b64_tr_b16 v[88:89], v166 offset:43008
	ds_read_b64_tr_b16 v[90:91], v166 offset:43520
	v_add_f32_e32 v92, v50, v105
	v_add_f32_e32 v92, v51, v92
	v_add_f32_e32 v92, v52, v92
	v_add_f32_e32 v92, v53, v92
	v_cvt_pk_bf16_f32 v140, v48, v49
	v_cvt_pk_bf16_f32 v141, v50, v51
	ds_read_b64_tr_b16 v[48:49], v166 offset:47104
	ds_read_b64_tr_b16 v[50:51], v166 offset:47616
	v_add_f32_e32 v92, v54, v92
	v_add_f32_e32 v92, v55, v92
	v_add_f32_e32 v92, v56, v92
	v_add_f32_e32 v105, v57, v92
	v_cvt_pk_bf16_f32 v142, v52, v53
	v_cvt_pk_bf16_f32 v143, v54, v55
	ds_read_b64_tr_b16 v[92:93], v166 offset:44032
	ds_read_b64_tr_b16 v[94:95], v166 offset:44544
	v_add_f32_e32 v52, v58, v105
	v_add_f32_e32 v52, v59, v52
	v_add_f32_e32 v52, v60, v52
	v_add_f32_e32 v105, v61, v52
	v_cvt_pk_bf16_f32 v136, v56, v57
	v_cvt_pk_bf16_f32 v137, v58, v59
	ds_read_b64_tr_b16 v[52:53], v166 offset:48128
	ds_read_b64_tr_b16 v[54:55], v166 offset:48640
	v_add_f32_e32 v56, v62, v105
	v_add_f32_e32 v56, v63, v56
	v_add_f32_e32 v56, 0, v56
	v_cvt_pk_bf16_f32 v138, v60, v61
	v_cvt_pk_bf16_f32 v139, v62, v63
	v_exp_f32_e32 v64, v64
	v_exp_f32_e32 v65, v65
	v_exp_f32_e32 v66, v66
	v_exp_f32_e32 v67, v67
	s_nop 0
	v_exp_f32_e32 v68, v68
	v_exp_f32_e32 v69, v69
	v_exp_f32_e32 v70, v70
	v_exp_f32_e32 v71, v71
	s_nop 0
	v_exp_f32_e32 v72, v72
	v_exp_f32_e32 v73, v73
	v_exp_f32_e32 v74, v74
	v_exp_f32_e32 v75, v75
	s_nop 0
	v_exp_f32_e32 v76, v76
	v_exp_f32_e32 v77, v77
	v_exp_f32_e32 v78, v78
	v_exp_f32_e32 v79, v79
	v_exp_f32_e32 v32, v32
	v_exp_f32_e32 v33, v33
	v_exp_f32_e32 v34, v34
	v_exp_f32_e32 v35, v35
	s_nop 0
	v_exp_f32_e32 v36, v36
	v_exp_f32_e32 v37, v37
	v_exp_f32_e32 v38, v38
	v_exp_f32_e32 v39, v39
	s_nop 0
	v_exp_f32_e32 v40, v40
	v_exp_f32_e32 v41, v41
	v_exp_f32_e32 v42, v42
	v_exp_f32_e32 v43, v43
	s_nop 0
	v_exp_f32_e32 v44, v44
	v_exp_f32_e32 v45, v45
	v_exp_f32_e32 v46, v46
	v_exp_f32_e32 v47, v47
	s_waitcnt lgkmcnt(14)
	v_mfma_f32_32x32x16_bf16 v[0:15], v[148:151], v[96:99], v[0:15]
	v_add_f32_e32 v57, v64, v65
	v_add_f32_e32 v57, v66, v57
	v_add_f32_e32 v57, v67, v57
	v_add_f32_e32 v57, v68, v57
	v_add_f32_e32 v57, v69, v57
	v_add_f32_e32 v57, v70, v57
	v_add_f32_e32 v57, v71, v57
	s_waitcnt lgkmcnt(12)
	v_mfma_f32_32x32x16_bf16 v[16:31], v[148:151], v[80:83], v[16:31]
	v_add_f32_e32 v57, v72, v57
	v_add_f32_e32 v57, v73, v57
	v_add_f32_e32 v57, v74, v57
	v_add_f32_e32 v57, v75, v57
	v_add_f32_e32 v57, v76, v57
	v_add_f32_e32 v57, v77, v57
	v_add_f32_e32 v57, v78, v57
	s_waitcnt lgkmcnt(10)
	v_mfma_f32_32x32x16_bf16 v[0:15], v[144:147], v[100:103], v[0:15]
	v_add_f32_e32 v57, v79, v57
	v_add_f32_e32 v57, v32, v57
	v_add_f32_e32 v57, v33, v57
	v_add_f32_e32 v57, v34, v57
	v_add_f32_e32 v57, v35, v57
	v_add_f32_e32 v57, v36, v57
	v_add_f32_e32 v57, v37, v57
	s_waitcnt lgkmcnt(8)
	v_mfma_f32_32x32x16_bf16 v[16:31], v[144:147], v[84:87], v[16:31]
	v_add_f32_e32 v57, v38, v57
	v_add_f32_e32 v57, v39, v57
	v_add_f32_e32 v57, v40, v57
	v_add_f32_e32 v57, v41, v57
	v_add_f32_e32 v57, v42, v57
	v_add_f32_e32 v57, v43, v57
	v_add_f32_e32 v57, v44, v57
	s_waitcnt lgkmcnt(6)
	v_mfma_f32_32x32x16_bf16 v[0:15], v[140:143], v[88:91], v[0:15]
	v_add_f32_e32 v57, v45, v57
	v_add_f32_e32 v57, v46, v57
	v_add_f32_e32 v57, v47, v57
	v_add_f32_e32 v56, v104, v56
	v_add_f32_e32 v56, v56, v57
	v_cvt_pk_bf16_f32 v32, v32, v33
	v_cvt_pk_bf16_f32 v58, v64, v65
	s_waitcnt lgkmcnt(4)
	v_mfma_f32_32x32x16_bf16 v[16:31], v[140:143], v[48:51], v[16:31]
	v_cvt_pk_bf16_f32 v59, v66, v67
	v_cvt_pk_bf16_f32 v60, v68, v69
	v_cvt_pk_bf16_f32 v61, v70, v71
	v_cvt_pk_bf16_f32 v62, v72, v73
	v_cvt_pk_bf16_f32 v63, v74, v75
	v_cvt_pk_bf16_f32 v64, v76, v77
	v_cvt_pk_bf16_f32 v65, v78, v79
	s_waitcnt lgkmcnt(2)
	v_mfma_f32_32x32x16_bf16 v[0:15], v[136:139], v[92:95], v[0:15]
	v_cvt_pk_bf16_f32 v33, v34, v35
	v_cvt_pk_bf16_f32 v34, v36, v37
	v_cvt_pk_bf16_f32 v35, v38, v39
	v_cvt_pk_bf16_f32 v36, v40, v41
	v_cvt_pk_bf16_f32 v37, v42, v43
	v_cvt_pk_bf16_f32 v38, v44, v45
	v_cvt_pk_bf16_f32 v39, v46, v47
	s_waitcnt lgkmcnt(0)
	v_mfma_f32_32x32x16_bf16 v[16:31], v[136:139], v[52:55], v[16:31]
	v_add_u32_e32 v40, s10, v163
	v_add3_u32 v57, v40, v162, v164
	ds_read_b64_tr_b16 v[40:41],v57 offset:0
	ds_read_b64_tr_b16 v[42:43],v57 offset:512
	ds_read_b64_tr_b16 v[44:45],v57 offset:1024
	ds_read_b64_tr_b16 v[46:47],v57 offset:1536
	ds_read_b64_tr_b16 v[48:49],v57 offset:2048
	ds_read_b64_tr_b16 v[50:51],v57 offset:2560
	ds_read_b64_tr_b16 v[52:53],v57 offset:3072
	ds_read_b64_tr_b16 v[54:55],v57 offset:3584
	s_waitcnt lgkmcnt(0)
	s_nop 0
	v_mfma_f32_32x32x16_bf16 v[0:15], v[58:61], v[40:43], v[0:15]
	ds_read_b64_tr_b16 v[40:41],v57 offset:4096
	ds_read_b64_tr_b16 v[42:43],v57 offset:4608
	v_mfma_f32_32x32x16_bf16 v[0:15], v[62:65], v[44:47], v[0:15]
	ds_read_b64_tr_b16 v[44:45],v57 offset:5120
	ds_read_b64_tr_b16 v[46:47],v57 offset:5632
	v_mfma_f32_32x32x16_bf16 v[0:15], v[32:35], v[48:51], v[0:15]
	ds_read_b64_tr_b16 v[48:49],v57 offset:6144
	ds_read_b64_tr_b16 v[50:51],v57 offset:6656
	v_mfma_f32_32x32x16_bf16 v[0:15], v[36:39], v[52:55], v[0:15]
	ds_read_b64_tr_b16 v[52:53],v57 offset:7168
	ds_read_b64_tr_b16 v[54:55],v57 offset:7680
	s_waitcnt lgkmcnt(0)
	v_mfma_f32_32x32x16_bf16 v[16:31], v[58:61], v[40:43], v[16:31]
	v_cmp_gt_u32_e32 vcc, 32, v156
	v_mfma_f32_32x32x16_bf16 v[16:31], v[62:65], v[44:47], v[16:31]
	v_mfma_f32_32x32x16_bf16 v[16:31], v[32:35], v[48:51], v[16:31]
	v_mov_b32_e32 v32, v56
	s_nop 1
	v_permlane32_swap_b32_e32 v56, v32
	v_mfma_f32_32x32x16_bf16 v[16:31], v[36:39], v[52:55], v[16:31]
	s_and_saveexec_b64 s[10:11], vcc
	s_cbranch_execz .LBB0_541
; template<int THRL,bool FIXED> __device__ __forceinline__ void attn_unit(int qb,const bf16*Qp,const unsigned char*__restrict__ K8h,const bf16*__restrict__ Vh,bf16*Op,int PO,char*shm){
;     ...
;   {auto rr=__builtin_amdgcn_permlane32_swap(__float_as_uint(l_reg),__float_as_uint(l_reg),false,false);l_reg=__uint_as_float(rr[0])+__uint_as_float(rr[1]);}
;   if(hi==0)wsf[32+r32]=l_reg;asm volatile("s_waitcnt lgkmcnt(0)":::"memory");
	v_lshl_add_u32 v33, v158, 2, s12
	v_add_f32_e32 v32, v56, v32
	ds_write_b32 v33, v32 offset:57472
	s_branch .LBB0_541

.LBB0_550:
	s_and_b32 s22, s51, 0xc000
	v_add_u32_e32 v160, s22, v214
	ds_read_b64_tr_b16 v[222:223], v160 offset:24576
	ds_read_b64_tr_b16 v[224:225], v160 offset:25088
	s_add_i32 s23, s51, 0xffff4000
	v_add_f32_e32 v116, v96, v97
	v_add_f32_e32 v116, v98, v116
	v_add_f32_e32 v116, v99, v116
	v_add_f32_e32 v116, v100, v116
	v_add_f32_e32 v116, v101, v116
	v_cvt_pk_bf16_f32 v182, v96, v97
	v_cvt_pk_bf16_f32 v183, v98, v99
	v_mfma_f32_32x32x16_bf16 v[128:143], v[112:115], v[190:193], v[64:79]
	ds_read_b64_tr_b16 v[96:97], v160 offset:28672
	ds_read_b64_tr_b16 v[98:99], v160 offset:29184
	v_add_f32_e32 v112, v102, v116
	v_add_f32_e32 v112, v103, v112
	v_add_f32_e32 v112, v104, v112
	v_add_f32_e32 v166, v105, v112
	v_mfma_f32_32x32x16_bf16 v[112:127], v[202:205], v[190:193], v[64:79]
	v_cvt_pk_bf16_f32 v184, v100, v101
	v_cvt_pk_bf16_f32 v185, v102, v103
	ds_read_b64_tr_b16 v[100:101], v160 offset:25600
	ds_read_b64_tr_b16 v[102:103], v160 offset:26112
	v_add_f32_e32 v166, v106, v166
	v_add_f32_e32 v166, v107, v166
	v_add_f32_e32 v166, v108, v166
	v_add_f32_e32 v166, v109, v166
	v_cvt_pk_bf16_f32 v178, v104, v105
	v_cvt_pk_bf16_f32 v179, v106, v107
	v_mfma_f32_32x32x16_bf16 v[128:143], v[198:201], v[186:189], v[128:143]
	ds_read_b64_tr_b16 v[104:105], v160 offset:29696
	ds_read_b64_tr_b16 v[106:107], v160 offset:30208
	v_mfma_f32_32x32x16_bf16 v[112:127], v[194:197], v[186:189], v[112:127]
	v_add_f32_e32 v166, v110, v166
	v_add_f32_e32 v166, v111, v166
	v_add_f32_e32 v166, v80, v166
	v_add_f32_e32 v166, v81, v166
	v_cvt_pk_bf16_f32 v180, v108, v109
	v_cvt_pk_bf16_f32 v181, v110, v111
	ds_read_b64_tr_b16 v[108:109], v160 offset:26624
	ds_read_b64_tr_b16 v[110:111], v160 offset:27136
	v_mfma_f32_32x32x16_bf16 v[128:143], v[156:159], v[174:177], v[128:143]
	v_add_f32_e32 v156, v82, v166
	v_add_f32_e32 v156, v83, v156
	v_add_f32_e32 v156, v84, v156
	v_add_f32_e32 v156, v85, v156
	v_cvt_pk_bf16_f32 v170, v80, v81
	v_cvt_pk_bf16_f32 v171, v82, v83
	ds_read_b64_tr_b16 v[80:81], v160 offset:30720
	ds_read_b64_tr_b16 v[82:83], v160 offset:31232
	v_mfma_f32_32x32x16_bf16 v[112:127], v[152:155], v[174:177], v[112:127]
	v_add_f32_e32 v152, v86, v156
	v_add_f32_e32 v152, v87, v152
	v_add_f32_e32 v152, v88, v152
	v_add_f32_e32 v152, v89, v152
	v_cvt_pk_bf16_f32 v172, v84, v85
	v_cvt_pk_bf16_f32 v173, v86, v87
	ds_read_b64_tr_b16 v[84:85], v160 offset:27648
	ds_read_b64_tr_b16 v[86:87], v160 offset:28160
	v_mfma_f32_32x32x16_bf16 v[128:143], v[148:151], v[162:165], v[128:143]
	v_add_f32_e32 v148, v90, v152
	v_add_f32_e32 v148, v91, v148
	v_add_f32_e32 v148, v92, v148
	v_add_f32_e32 v148, v93, v148
	v_cvt_pk_bf16_f32 v166, v88, v89
	v_cvt_pk_bf16_f32 v167, v90, v91
	ds_read_b64_tr_b16 v[88:89], v160 offset:31744
	ds_read_b64_tr_b16 v[90:91], v160 offset:32256
	v_mfma_f32_32x32x16_bf16 v[112:127], v[144:147], v[162:165], v[112:127]
	v_add_f32_e32 v144, v94, v148
	v_add_f32_e32 v144, v95, v144
	v_add_f32_e32 v243, v216, v144
	v_cvt_pk_bf16_f32 v168, v92, v93
	v_cvt_pk_bf16_f32 v169, v94, v95
	s_add_i32 s50, s50, s29
	s_mov_b32 m0, s50
	v_lshl_add_u64 v[92:93], v[212:213], 0, s[20:21]
	global_load_lds_dwordx4 v[92:93], off
	s_add_i32 s50, s51, 0xffffc000
	s_and_b32 s50, s50, 0xc000
	s_add_i32 s50, s50, s35
	s_mov_b32 m0, s50
	v_lshl_add_u64 v[92:93], v[210:211], 0, s[36:37]
	global_load_lds_dwordx4 v[92:93], off
	s_addk_i32 s50, 0x2000
	s_mov_b32 m0, s50
	v_lshl_add_u64 v[92:93], v[210:211], 0, s[26:27]
	global_load_lds_dwordx4 v[92:93], off
	s_waitcnt lgkmcnt(8)
	v_mfma_f32_32x32x16_bf16 v[0:15], v[182:185], v[222:225], v[0:15]
	v_exp_f32_e32 v128, v128
	v_exp_f32_e32 v129, v129
	ds_read_b64_tr_b16 v[92:93], v160 offset:32768
	ds_read_b64_tr_b16 v[94:95], v160 offset:33280
	v_mfma_f32_32x32x16_bf16 v[16:31], v[182:185], v[96:99], v[16:31]
	v_exp_f32_e32 v130, v130
	v_exp_f32_e32 v131, v131
	ds_read_b64_tr_b16 v[96:97], v160 offset:36864
	ds_read_b64_tr_b16 v[98:99], v160 offset:37376
	v_mfma_f32_32x32x16_bf16 v[0:15], v[178:181], v[100:103], v[0:15]
	v_exp_f32_e32 v132, v132
	v_exp_f32_e32 v133, v133
	ds_read_b64_tr_b16 v[100:101], v160 offset:33792
	ds_read_b64_tr_b16 v[102:103], v160 offset:34304
	v_mfma_f32_32x32x16_bf16 v[16:31], v[178:181], v[104:107], v[16:31]
	v_exp_f32_e32 v134, v134
	v_exp_f32_e32 v135, v135
	ds_read_b64_tr_b16 v[104:105], v160 offset:37888
	ds_read_b64_tr_b16 v[106:107], v160 offset:38400
	s_waitcnt lgkmcnt(8)
	v_mfma_f32_32x32x16_bf16 v[0:15], v[170:173], v[108:111], v[0:15]
	v_exp_f32_e32 v136, v136
	v_exp_f32_e32 v137, v137
	ds_read_b64_tr_b16 v[108:109], v160 offset:34816
	ds_read_b64_tr_b16 v[110:111], v160 offset:35328
	v_mfma_f32_32x32x16_bf16 v[16:31], v[170:173], v[80:83], v[16:31]
	v_exp_f32_e32 v138, v138
	v_exp_f32_e32 v139, v139
	ds_read_b64_tr_b16 v[80:81], v160 offset:38912
	ds_read_b64_tr_b16 v[82:83], v160 offset:39424
	v_mfma_f32_32x32x16_bf16 v[0:15], v[166:169], v[84:87], v[0:15]
	v_exp_f32_e32 v140, v140
	v_exp_f32_e32 v141, v141
	ds_read_b64_tr_b16 v[84:85], v160 offset:35840
	ds_read_b64_tr_b16 v[86:87], v160 offset:36352
	v_mfma_f32_32x32x16_bf16 v[16:31], v[166:169], v[88:91], v[16:31]
	v_exp_f32_e32 v142, v142
	v_exp_f32_e32 v143, v143
	ds_read_b64_tr_b16 v[88:89], v160 offset:39936
	ds_read_b64_tr_b16 v[90:91], v160 offset:40448
	s_waitcnt lgkmcnt(8)
	v_mfma_f32_32x32x16_bf16 v[32:47], v[182:185], v[92:95], v[32:47]
	v_exp_f32_e32 v112, v112
	v_exp_f32_e32 v113, v113
	v_mfma_f32_32x32x16_bf16 v[48:63], v[182:185], v[96:99], v[48:63]
	v_exp_f32_e32 v114, v114
	v_exp_f32_e32 v115, v115
	v_add_u32_e32 v96, s34, v215
	ds_read_b128 v[92:95], v96
	ds_read_b128 v[144:147], v96 offset:512
	v_mfma_f32_32x32x16_bf16 v[32:47], v[178:181], v[100:103], v[32:47]
	v_exp_f32_e32 v116, v116
	v_exp_f32_e32 v117, v117
	ds_read_b128 v[148:151], v96 offset:2048
	ds_read_b128 v[152:155], v96 offset:2560
	v_mfma_f32_32x32x16_bf16 v[48:63], v[178:181], v[104:107], v[48:63]
	v_exp_f32_e32 v118, v118
	v_exp_f32_e32 v119, v119
	ds_read_b128 v[156:159], v96 offset:4096
	ds_read_b128 v[194:197], v96 offset:4608
	s_waitcnt lgkmcnt(6)
	v_mfma_f32_32x32x16_bf16 v[32:47], v[170:173], v[108:111], v[32:47]
	v_exp_f32_e32 v120, v120
	v_exp_f32_e32 v121, v121
	ds_read_b128 v[198:201], v96 offset:6144
	ds_read_b128 v[202:205], v96 offset:6656
	v_mfma_f32_32x32x16_bf16 v[48:63], v[170:173], v[80:83], v[48:63]
	v_exp_f32_e32 v122, v122
	v_exp_f32_e32 v123, v123
	v_mfma_f32_32x32x16_bf16 v[32:47], v[166:169], v[84:87], v[32:47]
	v_exp_f32_e32 v124, v124
	v_exp_f32_e32 v125, v125
	v_mfma_f32_32x32x16_bf16 v[48:63], v[166:169], v[88:91], v[48:63]
	v_exp_f32_e32 v126, v126
	v_exp_f32_e32 v127, v127
	s_waitcnt vmcnt(5) lgkmcnt(0)
	s_barrier
; #define WAIT_BAR(N) asm volatile("s_waitcnt vmcnt(" #N ") lgkmcnt(0)\n\ts_barrier":::"memory")
;   #define RESC() do{ if(resc){ asm volatile("s_waitcnt lgkmcnt(0)":::"memory"); \
;       _Pragma("unroll") for(int d_=0;d_<2;++d_) _Pragma("unroll") for(int r=0;r<16;++r)o[d_][r]*=wsf[crow(r,hi)]; } }while(0)
;   #define ROT() do{sl_prev=sl_cur;sl_cur=sl_next;sl_next=(sl_next==(NSLOT-1)*SLOTB)?0:sl_next+SLOTB;}while(0)
; #define WAIT_BAR(N) asm volatile("s_waitcnt vmcnt(" #N ") lgkmcnt(0)\n\ts_barrier":::"memory")
;   #define RESC() do{ if(resc){ asm volatile("s_waitcnt lgkmcnt(0)":::"memory"); \
;       _Pragma("unroll") for(int d_=0;d_<4;++d_) _Pragma("unroll") for(int r=0;r<16;++r)o[d_][r]*=wsf[crow(r,hi)]; } }while(0)
;   #define ROT() do{sl_prev=sl_cur;sl_cur=sl_next;sl_next=(sl_next==(NSLOT-1)*SLOTB)?0:sl_next+SLOTB;}while(0)
; #define WAIT_BAR(N) asm volatile("s_waitcnt vmcnt(" #N ") lgkmcnt(0)\n\ts_barrier":::"memory")
;   #define RESC() do{ if(resc){ asm volatile("s_waitcnt lgkmcnt(0)":::"memory"); \
;       _Pragma("unroll") for(int d_=0;d_<2;++d_) _Pragma("unroll") for(int r=0;r<16;++r)o[d_][r]*=wsf[crow(r,hi)]; } }while(0)
;   #define ROT() do{sl_prev=sl_cur;sl_cur=sl_next;sl_next=(sl_next==(NSLOT-1)*SLOTB)?0:sl_next+SLOTB;}while(0)
; template<int THRL,bool FIXED> __device__ __forceinline__ void attn_unit(int qb,const bf16*Qp,const bf16*__restrict__ Kh,const bf16*__restrict__ Vh,bf16*Op,int PO,char*shm,bool comb,float lam,const float*gsub,float gscale){
;     ...
;   int t=1;
;     ...
;   for(;t+5<NT;t+=2){
;     STEP(pB0,pB1,pA0,pA1,t,true,true,true);     WAIT_BAR(5); RESC(); ROT();
	s_add_i32 s50, s34, 0x2000
	s_cmpk_lg_i32 s34, 0x4000
	s_cselect_b32 s50, s50, 0
	s_and_b32 s23, s23, 0xc000
	v_add_u32_e32 v217, s23, v214
	ds_read_b64_tr_b16 v[222:223], v217 offset:24576
	ds_read_b64_tr_b16 v[224:225], v217 offset:25088
	v_mfma_f32_32x32x16_bf16 v[96:111], v[92:95], v[190:193], v[64:79]
	v_add_f32_e32 v80, v128, v129
	v_add_f32_e32 v80, v130, v80
	v_add_f32_e32 v80, v131, v80
	v_add_f32_e32 v80, v132, v80
	v_add_f32_e32 v80, v133, v80
	v_cvt_pk_bf16_f32 v182, v128, v129
	v_cvt_pk_bf16_f32 v183, v130, v131
	ds_read_b64_tr_b16 v[128:129], v217 offset:28672
	ds_read_b64_tr_b16 v[130:131], v217 offset:29184
	v_add_f32_e32 v80, v134, v80
	v_add_f32_e32 v80, v135, v80
	v_add_f32_e32 v80, v136, v80
	v_add_f32_e32 v166, v137, v80
	v_mfma_f32_32x32x16_bf16 v[80:95], v[144:147], v[190:193], v[64:79]
	v_cvt_pk_bf16_f32 v184, v132, v133
	v_cvt_pk_bf16_f32 v185, v134, v135
	ds_read_b64_tr_b16 v[132:133], v217 offset:25600
	ds_read_b64_tr_b16 v[134:135], v217 offset:26112
	v_mfma_f32_32x32x16_bf16 v[96:111], v[148:151], v[186:189], v[96:111]
	v_add_f32_e32 v144, v138, v166
	v_add_f32_e32 v144, v139, v144
	v_add_f32_e32 v144, v140, v144
	v_add_f32_e32 v144, v141, v144
	v_cvt_pk_bf16_f32 v178, v136, v137
	v_cvt_pk_bf16_f32 v179, v138, v139
	ds_read_b64_tr_b16 v[136:137], v217 offset:29696
	ds_read_b64_tr_b16 v[138:139], v217 offset:30208
	v_mfma_f32_32x32x16_bf16 v[80:95], v[152:155], v[186:189], v[80:95]
	v_add_f32_e32 v144, v142, v144
	v_add_f32_e32 v144, v143, v144
	v_add_f32_e32 v144, v112, v144
	v_add_f32_e32 v144, v113, v144
	v_cvt_pk_bf16_f32 v180, v140, v141
	v_cvt_pk_bf16_f32 v181, v142, v143
	ds_read_b64_tr_b16 v[140:141], v217 offset:26624
	ds_read_b64_tr_b16 v[142:143], v217 offset:27136
	v_mfma_f32_32x32x16_bf16 v[96:111], v[156:159], v[174:177], v[96:111]
	v_add_f32_e32 v144, v114, v144
	v_add_f32_e32 v144, v115, v144
	v_add_f32_e32 v144, v116, v144
	v_add_f32_e32 v144, v117, v144
	v_cvt_pk_bf16_f32 v170, v112, v113
	v_cvt_pk_bf16_f32 v171, v114, v115
	ds_read_b64_tr_b16 v[112:113], v217 offset:30720
	ds_read_b64_tr_b16 v[114:115], v217 offset:31232
	v_mfma_f32_32x32x16_bf16 v[80:95], v[194:197], v[174:177], v[80:95]
	v_add_f32_e32 v144, v118, v144
	v_add_f32_e32 v144, v119, v144
	v_add_f32_e32 v144, v120, v144
	v_add_f32_e32 v144, v121, v144
	v_cvt_pk_bf16_f32 v172, v116, v117
	v_cvt_pk_bf16_f32 v173, v118, v119
	ds_read_b64_tr_b16 v[116:117], v217 offset:27648
	ds_read_b64_tr_b16 v[118:119], v217 offset:28160
	v_mfma_f32_32x32x16_bf16 v[96:111], v[198:201], v[162:165], v[96:111]
	v_add_f32_e32 v144, v122, v144
	v_add_f32_e32 v144, v123, v144
	v_add_f32_e32 v144, v124, v144
	v_add_f32_e32 v144, v125, v144
	v_cvt_pk_bf16_f32 v166, v120, v121
	v_cvt_pk_bf16_f32 v167, v122, v123
	ds_read_b64_tr_b16 v[120:121], v217 offset:31744
	ds_read_b64_tr_b16 v[122:123], v217 offset:32256
	v_mfma_f32_32x32x16_bf16 v[80:95], v[202:205], v[162:165], v[80:95]
	v_add_f32_e32 v144, v126, v144
	v_add_f32_e32 v144, v127, v144
	v_add_f32_e32 v216, v243, v144
	v_cvt_pk_bf16_f32 v168, v124, v125
	v_cvt_pk_bf16_f32 v169, v126, v127
	s_add_i32 s23, s34, s29
	s_mov_b32 m0, s23
	v_lshl_add_u64 v[124:125], v[212:213], 0, s[38:39]
	global_load_lds_dwordx4 v[124:125], off
	s_add_i32 s22, s22, s35
	s_mov_b32 m0, s22
	s_nop 0
	global_load_lds_dwordx4 v[210:211], off
	s_addk_i32 s22, 0x2000
	s_mov_b32 m0, s22
	v_lshl_add_u64 v[124:125], v[210:211], 0, s[24:25]
	global_load_lds_dwordx4 v[124:125], off
	s_waitcnt lgkmcnt(8)
	v_mfma_f32_32x32x16_bf16 v[0:15], v[182:185], v[222:225], v[0:15]
	v_exp_f32_e32 v96, v96
	v_exp_f32_e32 v97, v97
	ds_read_b64_tr_b16 v[124:125], v217 offset:32768
	ds_read_b64_tr_b16 v[126:127], v217 offset:33280
	v_mfma_f32_32x32x16_bf16 v[16:31], v[182:185], v[128:131], v[16:31]
	v_exp_f32_e32 v98, v98
	v_exp_f32_e32 v99, v99
	ds_read_b64_tr_b16 v[128:129], v217 offset:36864
	ds_read_b64_tr_b16 v[130:131], v217 offset:37376
	v_mfma_f32_32x32x16_bf16 v[0:15], v[178:181], v[132:135], v[0:15]
	v_exp_f32_e32 v100, v100
	v_exp_f32_e32 v101, v101
	ds_read_b64_tr_b16 v[132:133], v217 offset:33792
	ds_read_b64_tr_b16 v[134:135], v217 offset:34304
	v_mfma_f32_32x32x16_bf16 v[16:31], v[178:181], v[136:139], v[16:31]
	v_exp_f32_e32 v102, v102
	v_exp_f32_e32 v103, v103
	ds_read_b64_tr_b16 v[136:137], v217 offset:37888
	ds_read_b64_tr_b16 v[138:139], v217 offset:38400
	s_waitcnt lgkmcnt(8)
	v_mfma_f32_32x32x16_bf16 v[0:15], v[170:173], v[140:143], v[0:15]
	v_exp_f32_e32 v104, v104
	v_exp_f32_e32 v105, v105
	ds_read_b64_tr_b16 v[140:141], v217 offset:34816
	ds_read_b64_tr_b16 v[142:143], v217 offset:35328
	v_mfma_f32_32x32x16_bf16 v[16:31], v[170:173], v[112:115], v[16:31]
	v_exp_f32_e32 v106, v106
	v_exp_f32_e32 v107, v107
	ds_read_b64_tr_b16 v[222:223], v217 offset:38912
	ds_read_b64_tr_b16 v[224:225], v217 offset:39424
	v_mfma_f32_32x32x16_bf16 v[0:15], v[166:169], v[116:119], v[0:15]
	v_exp_f32_e32 v108, v108
	v_exp_f32_e32 v109, v109
	ds_read_b64_tr_b16 v[116:117], v217 offset:35840
	ds_read_b64_tr_b16 v[118:119], v217 offset:36352
	v_mfma_f32_32x32x16_bf16 v[16:31], v[166:169], v[120:123], v[16:31]
	v_exp_f32_e32 v110, v110
	v_exp_f32_e32 v111, v111
	ds_read_b64_tr_b16 v[120:121], v217 offset:39936
	ds_read_b64_tr_b16 v[122:123], v217 offset:40448
	s_waitcnt lgkmcnt(8)
	v_mfma_f32_32x32x16_bf16 v[32:47], v[182:185], v[124:127], v[32:47]
	v_exp_f32_e32 v80, v80
	v_exp_f32_e32 v81, v81
	v_mfma_f32_32x32x16_bf16 v[48:63], v[182:185], v[128:131], v[48:63]
	v_exp_f32_e32 v82, v82
	v_exp_f32_e32 v83, v83
	v_add_u32_e32 v124, s50, v215
	ds_read_b128 v[112:115], v124
	ds_read_b128 v[202:205], v124 offset:512
	v_mfma_f32_32x32x16_bf16 v[32:47], v[178:181], v[132:135], v[32:47]
	v_exp_f32_e32 v84, v84
	v_exp_f32_e32 v85, v85
	ds_read_b128 v[198:201], v124 offset:2048
	ds_read_b128 v[194:197], v124 offset:2560
	v_mfma_f32_32x32x16_bf16 v[48:63], v[178:181], v[136:139], v[48:63]
	v_exp_f32_e32 v86, v86
	v_exp_f32_e32 v87, v87
	ds_read_b128 v[156:159], v124 offset:4096
	ds_read_b128 v[152:155], v124 offset:4608
	s_waitcnt lgkmcnt(6)
	v_mfma_f32_32x32x16_bf16 v[32:47], v[170:173], v[140:143], v[32:47]
	v_exp_f32_e32 v88, v88
	v_exp_f32_e32 v89, v89
	ds_read_b128 v[148:151], v124 offset:6144
	ds_read_b128 v[144:147], v124 offset:6656
	v_mfma_f32_32x32x16_bf16 v[48:63], v[170:173], v[222:225], v[48:63]
	v_exp_f32_e32 v90, v90
	v_exp_f32_e32 v91, v91
	v_mfma_f32_32x32x16_bf16 v[32:47], v[166:169], v[116:119], v[32:47]
	v_exp_f32_e32 v92, v92
	v_exp_f32_e32 v93, v93
	v_mfma_f32_32x32x16_bf16 v[48:63], v[166:169], v[120:123], v[48:63]
	v_exp_f32_e32 v94, v94
	v_exp_f32_e32 v95, v95
	s_add_i32 s22, s50, 0x2000
	s_waitcnt vmcnt(5) lgkmcnt(0)
	s_barrier
; #define WAIT_BAR(N) asm volatile("s_waitcnt vmcnt(" #N ") lgkmcnt(0)\n\ts_barrier":::"memory")
;   #define RESC() do{ if(resc){ asm volatile("s_waitcnt lgkmcnt(0)":::"memory"); \
;       _Pragma("unroll") for(int d_=0;d_<2;++d_) _Pragma("unroll") for(int r=0;r<16;++r)o[d_][r]*=wsf[crow(r,hi)]; } }while(0)
;   #define ROT() do{sl_prev=sl_cur;sl_cur=sl_next;sl_next=(sl_next==(NSLOT-1)*SLOTB)?0:sl_next+SLOTB;}while(0)
;   #define ENDW(tt) do{ if((tt)+3<NT){WAIT_BAR(3);} else if((tt)+2<NT){WAIT_BAR(2);} else {WAIT_BAR(0);} }while(0)
; #define WAIT_BAR(N) asm volatile("s_waitcnt vmcnt(" #N ") lgkmcnt(0)\n\ts_barrier":::"memory")
;   #define RESC() do{ if(resc){ asm volatile("s_waitcnt lgkmcnt(0)":::"memory"); \
;       _Pragma("unroll") for(int d_=0;d_<4;++d_) _Pragma("unroll") for(int r=0;r<16;++r)o[d_][r]*=wsf[crow(r,hi)]; } }while(0)
;   #define ROT() do{sl_prev=sl_cur;sl_cur=sl_next;sl_next=(sl_next==(NSLOT-1)*SLOTB)?0:sl_next+SLOTB;}while(0)
;   #define ENDW(tt) do{ if((tt)+3<NT){WAIT_BAR(5);} else if((tt)+2<NT){WAIT_BAR(4);} else {WAIT_BAR(0);} }while(0)
; #define WAIT_BAR(N) asm volatile("s_waitcnt vmcnt(" #N ") lgkmcnt(0)\n\ts_barrier":::"memory")
;   #define RESC() do{ if(resc){ asm volatile("s_waitcnt lgkmcnt(0)":::"memory"); \
;       _Pragma("unroll") for(int d_=0;d_<2;++d_) _Pragma("unroll") for(int r=0;r<16;++r)o[d_][r]*=wsf[crow(r,hi)]; } }while(0)
;   #define ROT() do{sl_prev=sl_cur;sl_cur=sl_next;sl_next=(sl_next==(NSLOT-1)*SLOTB)?0:sl_next+SLOTB;}while(0)
;   #define ENDW(tt) do{ if((tt)+3<NT){WAIT_BAR(3);} else if((tt)+2<NT){WAIT_BAR(2);} else {WAIT_BAR(0);} }while(0)
; template<int THRL,bool FIXED> __device__ __forceinline__ void attn_unit(int qb,const bf16*Qp,const bf16*__restrict__ Kh,const bf16*__restrict__ Vh,bf16*Op,int PO,char*shm,bool comb,float lam,const float*gsub,float gscale){
;     ...
;   int t=1;
;     ...
;   for(;t+5<NT;t+=2){
;     STEP(pB0,pB1,pA0,pA1,t,true,true,true);     WAIT_BAR(5); RESC(); ROT();
;     STEP(pA0,pA1,pB0,pB1,t+1,true,true,true);   WAIT_BAR(5); RESC(); ROT();
;   }
;     ...
;   for(;t+1<NT;t+=2){
;     STEP(pB0,pB1,pA0,pA1,t,(t+3<NT),(t+2<NT),(t+1<NT));       ENDW(t);   RESC(); ROT();
	s_cmpk_lg_i32 s50, 0x4000
	s_cselect_b32 s34, s22, 0
	s_add_i32 s44, s44, 2
	s_add_i32 s51, s51, 0x8000
	v_lshl_add_u64 v[210:211], v[210:211], 0, s[40:41]
	v_lshl_add_u64 v[212:213], v[212:213], 0, s[40:41]
	s_cmpk_gt_u32 s44, 0xf8
	s_cbranch_scc0 .LBB0_550
	s_mov_b32 m0, s101
	s_and_b32 s22, s28, 0x3fffffc0
	s_lshl_b32 s22, s22, 2
	s_add_i32 s28, s22, 0
	s_add_i32 s28, s28, 0x16000
	v_add_u32_e32 v210, 0x6000, v214
	v_add_u32_e32 v160, 0x10000, v214
	v_mov_b32_e32 v211, v160
	ds_read_b64_tr_b16 v[244:245], v214 offset:57344
	ds_read_b64_tr_b16 v[246:247], v214 offset:57856
	v_add_f32_e32 v116, v96, v97
	v_add_f32_e32 v116, v98, v116
	v_add_f32_e32 v116, v99, v116
	v_add_f32_e32 v116, v100, v116
	v_add_f32_e32 v116, v101, v116
	v_cvt_pk_bf16_f32 v182, v96, v97
	v_cvt_pk_bf16_f32 v183, v98, v99
	s_waitcnt lgkmcnt(9)
	v_mfma_f32_32x32x16_bf16 v[128:143], v[112:115], v[190:193], v[64:79]
	ds_read_b64_tr_b16 v[248:249], v214 offset:61440
	ds_read_b64_tr_b16 v[250:251], v214 offset:61952
	v_add_f32_e32 v96, v102, v116
	v_add_f32_e32 v96, v103, v96
	v_add_f32_e32 v96, v104, v96
	v_add_f32_e32 v96, v105, v96
	v_cvt_pk_bf16_f32 v184, v100, v101
	v_cvt_pk_bf16_f32 v185, v102, v103
	s_waitcnt lgkmcnt(10)
	v_mfma_f32_32x32x16_bf16 v[112:127], v[202:205], v[190:193], v[64:79]
	ds_read_b64_tr_b16 v[98:99], v214 offset:58368
	ds_read_b64_tr_b16 v[100:101], v214 offset:58880
	v_add_f32_e32 v96, v106, v96
	v_add_f32_e32 v96, v107, v96
	v_add_f32_e32 v96, v108, v96
	v_add_f32_e32 v96, v109, v96
	v_cvt_pk_bf16_f32 v178, v104, v105
	v_cvt_pk_bf16_f32 v179, v106, v107
	s_waitcnt lgkmcnt(11)
	v_mfma_f32_32x32x16_bf16 v[128:143], v[198:201], v[186:189], v[128:143]
	ds_read_b64_tr_b16 v[102:103], v214 offset:62464
	ds_read_b64_tr_b16 v[104:105], v214 offset:62976
	v_add_f32_e32 v96, v110, v96
	v_add_f32_e32 v96, v111, v96
	v_add_f32_e32 v96, v80, v96
	v_add_f32_e32 v96, v81, v96
	v_cvt_pk_bf16_f32 v180, v108, v109
	v_cvt_pk_bf16_f32 v181, v110, v111
	s_waitcnt lgkmcnt(12)
	v_mfma_f32_32x32x16_bf16 v[112:127], v[194:197], v[186:189], v[112:127]
	ds_read_b64_tr_b16 v[106:107], v214 offset:59392
	ds_read_b64_tr_b16 v[108:109], v214 offset:59904
	v_add_f32_e32 v96, v82, v96
	v_add_f32_e32 v96, v83, v96
	v_add_f32_e32 v96, v84, v96
	v_add_f32_e32 v96, v85, v96
	v_cvt_pk_bf16_f32 v170, v80, v81
	v_cvt_pk_bf16_f32 v171, v82, v83
	s_waitcnt lgkmcnt(13)
	v_mfma_f32_32x32x16_bf16 v[128:143], v[156:159], v[174:177], v[128:143]
	ds_read_b64_tr_b16 v[80:81], v214 offset:63488
	ds_read_b64_tr_b16 v[82:83], v214 offset:64000
	v_add_f32_e32 v96, v86, v96
	v_add_f32_e32 v96, v87, v96
	v_add_f32_e32 v96, v88, v96
	v_add_f32_e32 v96, v89, v96
	v_cvt_pk_bf16_f32 v172, v84, v85
	v_cvt_pk_bf16_f32 v173, v86, v87
	s_waitcnt lgkmcnt(14)
	v_mfma_f32_32x32x16_bf16 v[112:127], v[152:155], v[174:177], v[112:127]
	ds_read_b64_tr_b16 v[84:85], v214 offset:60416
	ds_read_b64_tr_b16 v[86:87], v214 offset:60928
	v_add_f32_e32 v96, v90, v96
	v_add_f32_e32 v96, v91, v96
	v_add_f32_e32 v96, v92, v96
	v_add_f32_e32 v96, v93, v96
	v_cvt_pk_bf16_f32 v166, v88, v89
	v_cvt_pk_bf16_f32 v167, v90, v91
	s_waitcnt lgkmcnt(14)
	v_mfma_f32_32x32x16_bf16 v[128:143], v[148:151], v[162:165], v[128:143]
	ds_read_b64_tr_b16 v[88:89], v214 offset:64512
	ds_read_b64_tr_b16 v[90:91], v214 offset:65024
	v_add_f32_e32 v96, v94, v96
	v_add_f32_e32 v96, v95, v96
	v_add_f32_e32 v96, 0, v96
	v_cvt_pk_bf16_f32 v168, v92, v93
	v_cvt_pk_bf16_f32 v169, v94, v95
	v_mfma_f32_32x32x16_bf16 v[112:127], v[144:147], v[162:165], v[112:127]
	s_add_i32 s22, s50, s29
	s_cmp_lg_u32 0, -1
	v_lshl_add_u64 v[92:93], v[208:209], 0, s[42:43]
	s_mov_b32 s23, m0
	s_mov_b32 m0, s22
	s_nop 0
	global_load_lds_dwordx4 v[92:93], off
	s_mov_b32 m0, s23
	s_cselect_b32 s44, 0, 0
	s_mov_b64 s[22:23], 0x4728000
	s_add_i32 s35, s44, s3
	v_lshl_add_u64 v[92:93], v[206:207], 0, s[22:23]
	s_add_i32 s22, s35, 0xa000
	s_mov_b32 s23, m0
	s_mov_b32 m0, s22
	s_nop 0
	global_load_lds_dwordx4 v[92:93], off
	s_mov_b32 m0, s23
	s_mov_b64 s[22:23], 0x4728080
	v_lshl_add_u64 v[92:93], v[206:207], 0, s[22:23]
	s_add_i32 s22, s35, 0xc000
	s_mov_b32 s23, m0
	s_mov_b32 m0, s22
	s_nop 0
	global_load_lds_dwordx4 v[92:93], off
	s_mov_b32 m0, s23
	v_add_f32_e32 v96, v216, v96
	s_waitcnt lgkmcnt(14)
	v_mfma_f32_32x32x16_bf16 v[0:15], v[182:185], v[244:247], v[0:15]
	v_exp_f32_e32 v128, v128
	v_exp_f32_e32 v129, v129
	ds_read_b64_tr_b16 v[92:93], v211
	ds_read_b64_tr_b16 v[94:95], v211 offset:512
	s_waitcnt lgkmcnt(14)
	v_mfma_f32_32x32x16_bf16 v[16:31], v[182:185], v[248:251], v[16:31]
	v_exp_f32_e32 v130, v130
	v_exp_f32_e32 v131, v131
	ds_read_b64_tr_b16 v[144:145], v211 offset:4096
	ds_read_b64_tr_b16 v[146:147], v211 offset:4608
	s_waitcnt lgkmcnt(14)
	v_mfma_f32_32x32x16_bf16 v[0:15], v[178:181], v[98:101], v[0:15]
	v_exp_f32_e32 v132, v132
	v_exp_f32_e32 v133, v133
	ds_read_b64_tr_b16 v[98:99], v211 offset:1024
	ds_read_b64_tr_b16 v[100:101], v211 offset:1536
	s_waitcnt lgkmcnt(14)
	v_mfma_f32_32x32x16_bf16 v[16:31], v[178:181], v[102:105], v[16:31]
	v_exp_f32_e32 v134, v134
	v_exp_f32_e32 v135, v135
	ds_read_b64_tr_b16 v[102:103], v211 offset:5120
	ds_read_b64_tr_b16 v[104:105], v211 offset:5632
	s_waitcnt lgkmcnt(14)
	v_mfma_f32_32x32x16_bf16 v[0:15], v[170:173], v[106:109], v[0:15]
	v_exp_f32_e32 v136, v136
	v_exp_f32_e32 v137, v137
	ds_read_b64_tr_b16 v[106:107], v211 offset:2048
	ds_read_b64_tr_b16 v[108:109], v211 offset:2560
	s_waitcnt lgkmcnt(14)
	v_mfma_f32_32x32x16_bf16 v[16:31], v[170:173], v[80:83], v[16:31]
	v_exp_f32_e32 v138, v138
	v_exp_f32_e32 v139, v139
	ds_read_b64_tr_b16 v[80:81], v211 offset:6144
	ds_read_b64_tr_b16 v[82:83], v211 offset:6656
	s_waitcnt lgkmcnt(14)
; #define WAIT_BAR(N) asm volatile("s_waitcnt vmcnt(" #N ") lgkmcnt(0)\n\ts_barrier":::"memory")
;   #define RESC() do{ if(resc){ asm volatile("s_waitcnt lgkmcnt(0)":::"memory"); \
;       _Pragma("unroll") for(int d_=0;d_<2;++d_) _Pragma("unroll") for(int r=0;r<16;++r)o[d_][r]*=wsf[crow(r,hi)]; } }while(0)
;   #define ROT() do{sl_prev=sl_cur;sl_cur=sl_next;sl_next=(sl_next==(NSLOT-1)*SLOTB)?0:sl_next+SLOTB;}while(0)
;   #define ENDW(tt) do{ if((tt)+3<NT){WAIT_BAR(3);} else if((tt)+2<NT){WAIT_BAR(2);} else {WAIT_BAR(0);} }while(0)
; #define WAIT_BAR(N) asm volatile("s_waitcnt vmcnt(" #N ") lgkmcnt(0)\n\ts_barrier":::"memory")
;   #define RESC() do{ if(resc){ asm volatile("s_waitcnt lgkmcnt(0)":::"memory"); \
;       _Pragma("unroll") for(int d_=0;d_<4;++d_) _Pragma("unroll") for(int r=0;r<16;++r)o[d_][r]*=wsf[crow(r,hi)]; } }while(0)
;   #define ROT() do{sl_prev=sl_cur;sl_cur=sl_next;sl_next=(sl_next==(NSLOT-1)*SLOTB)?0:sl_next+SLOTB;}while(0)
;   #define ENDW(tt) do{ if((tt)+3<NT){WAIT_BAR(5);} else if((tt)+2<NT){WAIT_BAR(4);} else {WAIT_BAR(0);} }while(0)
; #define WAIT_BAR(N) asm volatile("s_waitcnt vmcnt(" #N ") lgkmcnt(0)\n\ts_barrier":::"memory")
;   #define RESC() do{ if(resc){ asm volatile("s_waitcnt lgkmcnt(0)":::"memory"); \
;       _Pragma("unroll") for(int d_=0;d_<2;++d_) _Pragma("unroll") for(int r=0;r<16;++r)o[d_][r]*=wsf[crow(r,hi)]; } }while(0)
;   #define ROT() do{sl_prev=sl_cur;sl_cur=sl_next;sl_next=(sl_next==(NSLOT-1)*SLOTB)?0:sl_next+SLOTB;}while(0)
;   #define ENDW(tt) do{ if((tt)+3<NT){WAIT_BAR(3);} else if((tt)+2<NT){WAIT_BAR(2);} else {WAIT_BAR(0);} }while(0)
; template<int THRL,bool FIXED> __device__ __forceinline__ void attn_unit(int qb,const bf16*Qp,const bf16*__restrict__ Kh,const bf16*__restrict__ Vh,bf16*Op,int PO,char*shm,bool comb,float lam,const float*gsub,float gscale){
;     ...
;   int t=1;
;     ...
;   for(;t+5<NT;t+=2){
;     STEP(pB0,pB1,pA0,pA1,t,true,true,true);     WAIT_BAR(5); RESC(); ROT();
;     STEP(pA0,pA1,pB0,pB1,t+1,true,true,true);   WAIT_BAR(5); RESC(); ROT();
;   }
;     ...
;   for(;t+1<NT;t+=2){
;     STEP(pB0,pB1,pA0,pA1,t,(t+3<NT),(t+2<NT),(t+1<NT));       ENDW(t);   RESC(); ROT();
;     STEP(pA0,pA1,pB0,pB1,t+1,(t+4<NT),(t+3<NT),(t+2<NT));     ENDW(t+1); RESC(); ROT();
	v_mfma_f32_32x32x16_bf16 v[0:15], v[166:169], v[84:87], v[0:15]
	v_exp_f32_e32 v140, v140
	v_exp_f32_e32 v141, v141
	ds_read_b64_tr_b16 v[84:85], v211 offset:3072
	ds_read_b64_tr_b16 v[86:87], v211 offset:3584
	s_waitcnt lgkmcnt(14)
	v_mfma_f32_32x32x16_bf16 v[16:31], v[166:169], v[88:91], v[16:31]
	v_exp_f32_e32 v142, v142
	v_exp_f32_e32 v143, v143
	ds_read_b64_tr_b16 v[88:89], v211 offset:7168
	ds_read_b64_tr_b16 v[90:91], v211 offset:7680
	s_waitcnt lgkmcnt(14)
	v_mfma_f32_32x32x16_bf16 v[32:47], v[182:185], v[92:95], v[32:47]
	v_exp_f32_e32 v112, v112
	v_exp_f32_e32 v113, v113
	s_waitcnt lgkmcnt(12)
	v_mfma_f32_32x32x16_bf16 v[48:63], v[182:185], v[144:147], v[48:63]
	v_exp_f32_e32 v114, v114
	v_exp_f32_e32 v115, v115
	v_add_u32_e32 v97, s34, v215
	ds_read_b128 v[92:95], v97
	ds_read_b128 v[194:197], v97 offset:512
	s_waitcnt lgkmcnt(12)
	v_mfma_f32_32x32x16_bf16 v[32:47], v[178:181], v[98:101], v[32:47]
	v_exp_f32_e32 v116, v116
	v_exp_f32_e32 v117, v117
	ds_read_b128 v[98:101], v97 offset:2048
	ds_read_b128 v[198:201], v97 offset:2560
	s_waitcnt lgkmcnt(12)
	v_mfma_f32_32x32x16_bf16 v[48:63], v[178:181], v[102:105], v[48:63]
	v_exp_f32_e32 v118, v118
	v_exp_f32_e32 v119, v119
	ds_read_b128 v[102:105], v97 offset:4096
	ds_read_b128 v[202:205], v97 offset:4608
	s_waitcnt lgkmcnt(12)
	v_mfma_f32_32x32x16_bf16 v[32:47], v[170:173], v[106:109], v[32:47]
	v_exp_f32_e32 v120, v120
	v_exp_f32_e32 v121, v121
	ds_read_b128 v[106:109], v97 offset:6144
	ds_read_b128 v[244:247], v97 offset:6656
	s_waitcnt lgkmcnt(12)
	v_mfma_f32_32x32x16_bf16 v[48:63], v[170:173], v[80:83], v[48:63]
	v_exp_f32_e32 v122, v122
	v_exp_f32_e32 v123, v123
	s_waitcnt lgkmcnt(10)
	v_mfma_f32_32x32x16_bf16 v[32:47], v[166:169], v[84:87], v[32:47]
	v_exp_f32_e32 v124, v124
	v_exp_f32_e32 v125, v125
	s_waitcnt lgkmcnt(8)
	v_mfma_f32_32x32x16_bf16 v[48:63], v[166:169], v[88:91], v[48:63]
	v_exp_f32_e32 v126, v126
	v_exp_f32_e32 v127, v127
	s_waitcnt vmcnt(5) lgkmcnt(0)
	s_barrier
	s_add_i32 s22, s34, 0x2000
	s_cmpk_lg_i32 s34, 0x4000
	s_cselect_b32 s22, s22, 0
	v_add_u32_e32 v211, 0x14000, v214
	ds_read_b64_tr_b16 v[248:249], v210 offset:49152
	ds_read_b64_tr_b16 v[250:251], v210 offset:49664
	v_add_f32_e32 v80, v128, v129
	v_add_f32_e32 v80, v130, v80
	v_add_f32_e32 v80, v131, v80
	v_add_f32_e32 v80, v132, v80
	v_add_f32_e32 v80, v133, v80
	v_cvt_pk_bf16_f32 v182, v128, v129
	v_cvt_pk_bf16_f32 v183, v130, v131
	s_waitcnt lgkmcnt(9)
	v_mfma_f32_32x32x16_bf16 v[144:159], v[92:95], v[190:193], v[64:79]
	ds_read_b64_tr_b16 v[222:223], v210 offset:53248
	ds_read_b64_tr_b16 v[224:225], v210 offset:53760
	v_add_f32_e32 v80, v134, v80
	v_add_f32_e32 v80, v135, v80
	v_add_f32_e32 v80, v136, v80
	v_add_f32_e32 v97, v137, v80
	s_waitcnt lgkmcnt(10)
	v_mfma_f32_32x32x16_bf16 v[80:95], v[194:197], v[190:193], v[64:79]
	v_cvt_pk_bf16_f32 v184, v132, v133
	v_cvt_pk_bf16_f32 v185, v134, v135
	ds_read_b64_tr_b16 v[130:131], v210 offset:50176
	ds_read_b64_tr_b16 v[132:133], v210 offset:50688
	v_add_f32_e32 v97, v138, v97
	v_add_f32_e32 v97, v139, v97
	v_add_f32_e32 v97, v140, v97
	v_add_f32_e32 v97, v141, v97
	v_cvt_pk_bf16_f32 v178, v136, v137
	v_cvt_pk_bf16_f32 v179, v138, v139
	s_waitcnt lgkmcnt(11)
	v_mfma_f32_32x32x16_bf16 v[144:159], v[98:101], v[186:189], v[144:159]
	ds_read_b64_tr_b16 v[98:99], v210 offset:54272
	ds_read_b64_tr_b16 v[100:101], v210 offset:54784
	s_waitcnt lgkmcnt(12)
	v_mfma_f32_32x32x16_bf16 v[80:95], v[198:201], v[186:189], v[80:95]
	v_add_f32_e32 v97, v142, v97
	v_add_f32_e32 v97, v143, v97
	v_add_f32_e32 v97, v112, v97
	v_add_f32_e32 v97, v113, v97
	v_cvt_pk_bf16_f32 v180, v140, v141
	v_cvt_pk_bf16_f32 v181, v142, v143
	ds_read_b64_tr_b16 v[134:135], v210 offset:51200
	ds_read_b64_tr_b16 v[136:137], v210 offset:51712
	v_add_f32_e32 v97, v114, v97
	v_add_f32_e32 v97, v115, v97
	v_add_f32_e32 v97, v116, v97
	v_add_f32_e32 v97, v117, v97
	v_cvt_pk_bf16_f32 v170, v112, v113
	v_cvt_pk_bf16_f32 v171, v114, v115
	s_waitcnt lgkmcnt(13)
	v_mfma_f32_32x32x16_bf16 v[144:159], v[102:105], v[174:177], v[144:159]
	ds_read_b64_tr_b16 v[102:103], v210 offset:55296
	ds_read_b64_tr_b16 v[104:105], v210 offset:55808
	s_waitcnt lgkmcnt(14)
	v_mfma_f32_32x32x16_bf16 v[80:95], v[202:205], v[174:177], v[80:95]
	v_add_f32_e32 v97, v118, v97
	v_add_f32_e32 v97, v119, v97
	v_add_f32_e32 v97, v120, v97
	v_add_f32_e32 v97, v121, v97
	v_cvt_pk_bf16_f32 v172, v116, v117
	v_cvt_pk_bf16_f32 v173, v118, v119
	ds_read_b64_tr_b16 v[110:111], v210 offset:52224
	ds_read_b64_tr_b16 v[112:113], v210 offset:52736
	v_add_f32_e32 v97, v122, v97
	v_add_f32_e32 v97, v123, v97
	v_add_f32_e32 v97, v124, v97
	v_add_f32_e32 v97, v125, v97
	v_cvt_pk_bf16_f32 v166, v120, v121
	v_cvt_pk_bf16_f32 v167, v122, v123
	s_waitcnt lgkmcnt(14)
	v_mfma_f32_32x32x16_bf16 v[144:159], v[106:109], v[162:165], v[144:159]
	ds_read_b64_tr_b16 v[106:107], v210 offset:56320
	ds_read_b64_tr_b16 v[108:109], v210 offset:56832
	v_mfma_f32_32x32x16_bf16 v[80:95], v[244:247], v[162:165], v[80:95]
	v_add_f32_e32 v97, v126, v97
	v_add_f32_e32 v97, v127, v97
	v_add_f32_e32 v97, 0, v97
	v_cvt_pk_bf16_f32 v168, v124, v125
	v_cvt_pk_bf16_f32 v169, v126, v127
	s_nop 0
	v_add_f32_e32 v128, v96, v97
	s_add_i32 s23, s34, s29
	v_lshl_add_u64 v[96:97], v[208:209], 0, s[46:47]
	s_mov_b32 s29, m0
	s_mov_b32 m0, s23
	s_nop 0
	global_load_lds_dwordx4 v[96:97], off
	s_mov_b32 m0, s29
	v_lshl_add_u64 v[96:97], v[206:207], 0, s[42:43]
	s_add_i32 s23, s35, 0xe000
	s_mov_b32 s29, m0
	s_mov_b32 m0, s23
	s_nop 0
	global_load_lds_dwordx4 v[96:97], off
	s_mov_b32 m0, s29
	s_mov_b64 s[50:51], 0x4770080
	v_lshl_add_u64 v[96:97], v[206:207], 0, s[50:51]
	s_add_i32 s23, s35, 0x10000
	s_mov_b32 s29, m0
	s_mov_b32 m0, s23
	s_nop 0
	global_load_lds_dwordx4 v[96:97], off
	s_mov_b32 m0, s29
	s_waitcnt lgkmcnt(14)
; #define WAIT_BAR(N) asm volatile("s_waitcnt vmcnt(" #N ") lgkmcnt(0)\n\ts_barrier":::"memory")
;   #define RESC() do{ if(resc){ asm volatile("s_waitcnt lgkmcnt(0)":::"memory"); \
;       _Pragma("unroll") for(int d_=0;d_<2;++d_) _Pragma("unroll") for(int r=0;r<16;++r)o[d_][r]*=wsf[crow(r,hi)]; } }while(0)
;   #define ROT() do{sl_prev=sl_cur;sl_cur=sl_next;sl_next=(sl_next==(NSLOT-1)*SLOTB)?0:sl_next+SLOTB;}while(0)
;   #define ENDW(tt) do{ if((tt)+3<NT){WAIT_BAR(3);} else if((tt)+2<NT){WAIT_BAR(2);} else {WAIT_BAR(0);} }while(0)
; #define WAIT_BAR(N) asm volatile("s_waitcnt vmcnt(" #N ") lgkmcnt(0)\n\ts_barrier":::"memory")
;   #define RESC() do{ if(resc){ asm volatile("s_waitcnt lgkmcnt(0)":::"memory"); \
;       _Pragma("unroll") for(int d_=0;d_<4;++d_) _Pragma("unroll") for(int r=0;r<16;++r)o[d_][r]*=wsf[crow(r,hi)]; } }while(0)
;   #define ROT() do{sl_prev=sl_cur;sl_cur=sl_next;sl_next=(sl_next==(NSLOT-1)*SLOTB)?0:sl_next+SLOTB;}while(0)
;   #define ENDW(tt) do{ if((tt)+3<NT){WAIT_BAR(5);} else if((tt)+2<NT){WAIT_BAR(4);} else {WAIT_BAR(0);} }while(0)
; #define WAIT_BAR(N) asm volatile("s_waitcnt vmcnt(" #N ") lgkmcnt(0)\n\ts_barrier":::"memory")
;   #define RESC() do{ if(resc){ asm volatile("s_waitcnt lgkmcnt(0)":::"memory"); \
;       _Pragma("unroll") for(int d_=0;d_<2;++d_) _Pragma("unroll") for(int r=0;r<16;++r)o[d_][r]*=wsf[crow(r,hi)]; } }while(0)
;   #define ROT() do{sl_prev=sl_cur;sl_cur=sl_next;sl_next=(sl_next==(NSLOT-1)*SLOTB)?0:sl_next+SLOTB;}while(0)
;   #define ENDW(tt) do{ if((tt)+3<NT){WAIT_BAR(3);} else if((tt)+2<NT){WAIT_BAR(2);} else {WAIT_BAR(0);} }while(0)
; template<int THRL,bool FIXED> __device__ __forceinline__ void attn_unit(int qb,const bf16*Qp,const bf16*__restrict__ Kh,const bf16*__restrict__ Vh,bf16*Op,int PO,char*shm,bool comb,float lam,const float*gsub,float gscale){
;     ...
;   int t=1;
;     ...
;   for(;t+5<NT;t+=2){
;     STEP(pB0,pB1,pA0,pA1,t,true,true,true);     WAIT_BAR(5); RESC(); ROT();
;     STEP(pA0,pA1,pB0,pB1,t+1,true,true,true);   WAIT_BAR(5); RESC(); ROT();
;   }
;     ...
;   for(;t+1<NT;t+=2){
;     STEP(pB0,pB1,pA0,pA1,t,(t+3<NT),(t+2<NT),(t+1<NT));       ENDW(t);   RESC(); ROT();
;     STEP(pA0,pA1,pB0,pB1,t+1,(t+4<NT),(t+3<NT),(t+2<NT));     ENDW(t+1); RESC(); ROT();
	v_mfma_f32_32x32x16_bf16 v[0:15], v[182:185], v[248:251], v[0:15]
	v_exp_f32_e32 v144, v144
	v_exp_f32_e32 v145, v145
	ds_read_b64_tr_b16 v[114:115], v211
	ds_read_b64_tr_b16 v[116:117], v211 offset:512
	s_waitcnt lgkmcnt(14)
	v_mfma_f32_32x32x16_bf16 v[16:31], v[182:185], v[222:225], v[16:31]
	v_exp_f32_e32 v146, v146
	v_exp_f32_e32 v147, v147
	ds_read_b64_tr_b16 v[118:119], v211 offset:4096
	ds_read_b64_tr_b16 v[120:121], v211 offset:4608
	s_waitcnt lgkmcnt(14)
	v_mfma_f32_32x32x16_bf16 v[0:15], v[178:181], v[130:133], v[0:15]
	v_exp_f32_e32 v148, v148
	v_exp_f32_e32 v149, v149
	ds_read_b64_tr_b16 v[122:123], v211 offset:1024
	ds_read_b64_tr_b16 v[124:125], v211 offset:1536
	s_waitcnt lgkmcnt(14)
	v_mfma_f32_32x32x16_bf16 v[16:31], v[178:181], v[98:101], v[16:31]
	v_exp_f32_e32 v150, v150
	v_exp_f32_e32 v151, v151
	ds_read_b64_tr_b16 v[96:97], v211 offset:5120
	ds_read_b64_tr_b16 v[98:99], v211 offset:5632
	s_waitcnt lgkmcnt(14)
	v_mfma_f32_32x32x16_bf16 v[0:15], v[170:173], v[134:137], v[0:15]
	v_exp_f32_e32 v152, v152
	v_exp_f32_e32 v153, v153
	ds_read_b64_tr_b16 v[130:131], v211 offset:2048
	ds_read_b64_tr_b16 v[132:133], v211 offset:2560
	s_waitcnt lgkmcnt(14)
	v_mfma_f32_32x32x16_bf16 v[16:31], v[170:173], v[102:105], v[16:31]
	v_exp_f32_e32 v154, v154
	v_exp_f32_e32 v155, v155
	ds_read_b64_tr_b16 v[100:101], v211 offset:6144
	ds_read_b64_tr_b16 v[102:103], v211 offset:6656
	s_waitcnt lgkmcnt(14)
	v_mfma_f32_32x32x16_bf16 v[0:15], v[166:169], v[110:113], v[0:15]
	v_exp_f32_e32 v156, v156
	v_exp_f32_e32 v157, v157
	ds_read_b64_tr_b16 v[110:111], v211 offset:3072
	ds_read_b64_tr_b16 v[112:113], v211 offset:3584
	s_waitcnt lgkmcnt(14)
	v_mfma_f32_32x32x16_bf16 v[16:31], v[166:169], v[106:109], v[16:31]
	v_exp_f32_e32 v158, v158
	v_exp_f32_e32 v159, v159
	ds_read_b64_tr_b16 v[104:105], v211 offset:7168
	ds_read_b64_tr_b16 v[106:107], v211 offset:7680
	s_waitcnt lgkmcnt(14)
	v_mfma_f32_32x32x16_bf16 v[32:47], v[182:185], v[114:117], v[32:47]
	v_exp_f32_e32 v80, v80
	v_exp_f32_e32 v81, v81
	s_waitcnt lgkmcnt(12)
	v_mfma_f32_32x32x16_bf16 v[48:63], v[182:185], v[118:121], v[48:63]
	v_exp_f32_e32 v82, v82
	v_exp_f32_e32 v83, v83
	v_add_u32_e32 v108, s22, v215
	ds_read_b128 v[134:137], v108
	ds_read_b128 v[138:141], v108 offset:512
	s_waitcnt lgkmcnt(12)
	v_mfma_f32_32x32x16_bf16 v[32:47], v[178:181], v[122:125], v[32:47]
	v_exp_f32_e32 v84, v84
	v_exp_f32_e32 v85, v85
	ds_read_b128 v[194:197], v108 offset:2048
	ds_read_b128 v[198:201], v108 offset:2560
	s_waitcnt lgkmcnt(12)
	v_mfma_f32_32x32x16_bf16 v[48:63], v[178:181], v[96:99], v[48:63]
	v_exp_f32_e32 v86, v86
	v_exp_f32_e32 v87, v87
	ds_read_b128 v[202:205], v108 offset:4096
	ds_read_b128 v[208:211], v108 offset:4608
	s_waitcnt lgkmcnt(12)
	v_mfma_f32_32x32x16_bf16 v[32:47], v[170:173], v[130:133], v[32:47]
	v_exp_f32_e32 v88, v88
	v_exp_f32_e32 v89, v89
	ds_read_b128 v[130:133], v108 offset:6144
	ds_read_b128 v[222:225], v108 offset:6656
	s_waitcnt lgkmcnt(12)
	v_mfma_f32_32x32x16_bf16 v[48:63], v[170:173], v[100:103], v[48:63]
	v_exp_f32_e32 v90, v90
	v_exp_f32_e32 v91, v91
	s_waitcnt lgkmcnt(10)
	v_mfma_f32_32x32x16_bf16 v[32:47], v[166:169], v[110:113], v[32:47]
	v_exp_f32_e32 v92, v92
	v_exp_f32_e32 v93, v93
	s_waitcnt lgkmcnt(8)
	v_mfma_f32_32x32x16_bf16 v[48:63], v[166:169], v[104:107], v[48:63]
	v_exp_f32_e32 v94, v94
	v_exp_f32_e32 v95, v95
	s_waitcnt vmcnt(5) lgkmcnt(0)
	s_barrier
	s_add_i32 s23, s22, 0x2000
	s_cmpk_lg_i32 s22, 0x4000
	s_cselect_b32 s22, s23, 0
	v_add_u32_e32 v212, 0x8000, v214
	ds_read_b64_tr_b16 v[244:245], v214 offset:24576
	ds_read_b64_tr_b16 v[246:247], v214 offset:25088
	v_add_f32_e32 v96, v144, v145
	v_add_f32_e32 v96, v146, v96
	v_add_f32_e32 v96, v147, v96
	v_add_f32_e32 v96, v148, v96
	v_add_f32_e32 v96, v149, v96
	v_cvt_pk_bf16_f32 v182, v144, v145
	v_cvt_pk_bf16_f32 v183, v146, v147
	s_waitcnt lgkmcnt(9)
	v_mfma_f32_32x32x16_bf16 v[112:127], v[134:137], v[190:193], v[64:79]
	ds_read_b64_tr_b16 v[134:135], v214 offset:28672
	ds_read_b64_tr_b16 v[136:137], v214 offset:29184
	v_add_f32_e32 v96, v150, v96
	v_add_f32_e32 v96, v151, v96
	v_add_f32_e32 v96, v152, v96
	v_add_f32_e32 v129, v153, v96
	v_cvt_pk_bf16_f32 v184, v148, v149
	v_cvt_pk_bf16_f32 v185, v150, v151
	s_waitcnt lgkmcnt(10)
	v_mfma_f32_32x32x16_bf16 v[96:111], v[138:141], v[190:193], v[64:79]
	ds_read_b64_tr_b16 v[138:139], v214 offset:25600
	ds_read_b64_tr_b16 v[140:141], v214 offset:26112
	v_add_f32_e32 v129, v154, v129
	v_add_f32_e32 v129, v155, v129
	v_add_f32_e32 v129, v156, v129
	v_add_f32_e32 v129, v157, v129
	v_cvt_pk_bf16_f32 v178, v152, v153
	v_cvt_pk_bf16_f32 v179, v154, v155
	s_waitcnt lgkmcnt(11)
	v_mfma_f32_32x32x16_bf16 v[112:127], v[194:197], v[186:189], v[112:127]
	ds_read_b64_tr_b16 v[146:147], v214 offset:29696
	ds_read_b64_tr_b16 v[148:149], v214 offset:30208
	v_add_f32_e32 v129, v158, v129
	v_add_f32_e32 v129, v159, v129
	v_add_f32_e32 v129, v80, v129
	v_add_f32_e32 v129, v81, v129
	v_cvt_pk_bf16_f32 v180, v156, v157
	v_cvt_pk_bf16_f32 v181, v158, v159
	s_waitcnt lgkmcnt(12)
	v_mfma_f32_32x32x16_bf16 v[96:111], v[198:201], v[186:189], v[96:111]
	ds_read_b64_tr_b16 v[150:151], v214 offset:26624
	ds_read_b64_tr_b16 v[152:153], v214 offset:27136
	v_add_f32_e32 v129, v82, v129
	v_add_f32_e32 v129, v83, v129
	v_add_f32_e32 v129, v84, v129
	v_add_f32_e32 v129, v85, v129
	v_cvt_pk_bf16_f32 v170, v80, v81
	v_cvt_pk_bf16_f32 v171, v82, v83
	s_waitcnt lgkmcnt(13)
	v_mfma_f32_32x32x16_bf16 v[112:127], v[202:205], v[174:177], v[112:127]
	ds_read_b64_tr_b16 v[80:81], v214 offset:30720
	ds_read_b64_tr_b16 v[82:83], v214 offset:31232
	v_add_f32_e32 v129, v86, v129
	v_add_f32_e32 v129, v87, v129
	v_add_f32_e32 v129, v88, v129
	v_add_f32_e32 v129, v89, v129
	v_cvt_pk_bf16_f32 v172, v84, v85
	v_cvt_pk_bf16_f32 v173, v86, v87
	s_waitcnt lgkmcnt(14)
; #define WAIT_BAR(N) asm volatile("s_waitcnt vmcnt(" #N ") lgkmcnt(0)\n\ts_barrier":::"memory")
;   #define RESC() do{ if(resc){ asm volatile("s_waitcnt lgkmcnt(0)":::"memory"); \
;       _Pragma("unroll") for(int d_=0;d_<2;++d_) _Pragma("unroll") for(int r=0;r<16;++r)o[d_][r]*=wsf[crow(r,hi)]; } }while(0)
;   #define ROT() do{sl_prev=sl_cur;sl_cur=sl_next;sl_next=(sl_next==(NSLOT-1)*SLOTB)?0:sl_next+SLOTB;}while(0)
;   #define ENDW(tt) do{ if((tt)+3<NT){WAIT_BAR(3);} else if((tt)+2<NT){WAIT_BAR(2);} else {WAIT_BAR(0);} }while(0)
; #define WAIT_BAR(N) asm volatile("s_waitcnt vmcnt(" #N ") lgkmcnt(0)\n\ts_barrier":::"memory")
;   #define RESC() do{ if(resc){ asm volatile("s_waitcnt lgkmcnt(0)":::"memory"); \
;       _Pragma("unroll") for(int d_=0;d_<4;++d_) _Pragma("unroll") for(int r=0;r<16;++r)o[d_][r]*=wsf[crow(r,hi)]; } }while(0)
;   #define ROT() do{sl_prev=sl_cur;sl_cur=sl_next;sl_next=(sl_next==(NSLOT-1)*SLOTB)?0:sl_next+SLOTB;}while(0)
;   #define ENDW(tt) do{ if((tt)+3<NT){WAIT_BAR(5);} else if((tt)+2<NT){WAIT_BAR(4);} else {WAIT_BAR(0);} }while(0)
; #define WAIT_BAR(N) asm volatile("s_waitcnt vmcnt(" #N ") lgkmcnt(0)\n\ts_barrier":::"memory")
;   #define RESC() do{ if(resc){ asm volatile("s_waitcnt lgkmcnt(0)":::"memory"); \
;       _Pragma("unroll") for(int d_=0;d_<2;++d_) _Pragma("unroll") for(int r=0;r<16;++r)o[d_][r]*=wsf[crow(r,hi)]; } }while(0)
;   #define ROT() do{sl_prev=sl_cur;sl_cur=sl_next;sl_next=(sl_next==(NSLOT-1)*SLOTB)?0:sl_next+SLOTB;}while(0)
;   #define ENDW(tt) do{ if((tt)+3<NT){WAIT_BAR(3);} else if((tt)+2<NT){WAIT_BAR(2);} else {WAIT_BAR(0);} }while(0)
; template<int THRL,bool FIXED> __device__ __forceinline__ void attn_unit(int qb,const bf16*Qp,const bf16*__restrict__ Kh,const bf16*__restrict__ Vh,bf16*Op,int PO,char*shm,bool comb,float lam,const float*gsub,float gscale){
;     ...
;   int t=1;
;     ...
;   for(;t+5<NT;t+=2){
;     STEP(pB0,pB1,pA0,pA1,t,true,true,true);     WAIT_BAR(5); RESC(); ROT();
;     STEP(pA0,pA1,pB0,pB1,t+1,true,true,true);   WAIT_BAR(5); RESC(); ROT();
;   }
;     ...
;   for(;t+1<NT;t+=2){
;     STEP(pB0,pB1,pA0,pA1,t,(t+3<NT),(t+2<NT),(t+1<NT));       ENDW(t);   RESC(); ROT();
;     STEP(pA0,pA1,pB0,pB1,t+1,(t+4<NT),(t+3<NT),(t+2<NT));     ENDW(t+1); RESC(); ROT();
	v_mfma_f32_32x32x16_bf16 v[96:111], v[208:211], v[174:177], v[96:111]
	ds_read_b64_tr_b16 v[84:85], v214 offset:27648
	ds_read_b64_tr_b16 v[86:87], v214 offset:28160
	v_add_f32_e32 v129, v90, v129
	v_add_f32_e32 v129, v91, v129
	v_add_f32_e32 v129, v92, v129
	v_add_f32_e32 v129, v93, v129
	v_cvt_pk_bf16_f32 v166, v88, v89
	v_cvt_pk_bf16_f32 v167, v90, v91
	s_waitcnt lgkmcnt(14)
	v_mfma_f32_32x32x16_bf16 v[112:127], v[130:133], v[162:165], v[112:127]
	ds_read_b64_tr_b16 v[88:89], v214 offset:31744
	ds_read_b64_tr_b16 v[90:91], v214 offset:32256
	v_add_f32_e32 v129, v94, v129
	v_add_f32_e32 v129, v95, v129
	v_add_f32_e32 v129, 0, v129
	v_cvt_pk_bf16_f32 v168, v92, v93
	v_cvt_pk_bf16_f32 v169, v94, v95
	v_mfma_f32_32x32x16_bf16 v[96:111], v[222:225], v[162:165], v[96:111]
	s_add_i32 s29, s44, 0x12000
	v_lshl_add_u64 v[92:93], v[206:207], 0, s[46:47]
	s_add_i32 s3, s3, s29
	s_mov_b32 s23, m0
	s_mov_b32 m0, s3
	s_nop 0
	global_load_lds_dwordx4 v[92:93], off
	s_mov_b32 m0, s23
	s_mov_b64 s[50:51], 0x47b8080
	v_lshl_add_u64 v[92:93], v[206:207], 0, s[50:51]
	s_add_i32 s35, s35, 0x14000
	s_mov_b32 s3, m0
	s_mov_b32 m0, s35
	s_nop 0
	global_load_lds_dwordx4 v[92:93], off
	s_mov_b32 m0, s3
	v_add_f32_e32 v144, v128, v129
	s_waitcnt lgkmcnt(14)
	v_mfma_f32_32x32x16_bf16 v[0:15], v[182:185], v[244:247], v[0:15]
	v_exp_f32_e32 v112, v112
	v_exp_f32_e32 v113, v113
	ds_read_b64_tr_b16 v[92:93], v212
	ds_read_b64_tr_b16 v[94:95], v212 offset:512
	s_waitcnt lgkmcnt(14)
	v_mfma_f32_32x32x16_bf16 v[16:31], v[182:185], v[134:137], v[16:31]
	v_exp_f32_e32 v114, v114
	v_exp_f32_e32 v115, v115
	ds_read_b64_tr_b16 v[128:129], v212 offset:4096
	ds_read_b64_tr_b16 v[130:131], v212 offset:4608
	s_waitcnt lgkmcnt(14)
	v_mfma_f32_32x32x16_bf16 v[0:15], v[178:181], v[138:141], v[0:15]
	v_exp_f32_e32 v116, v116
	v_exp_f32_e32 v117, v117
	ds_read_b64_tr_b16 v[132:133], v212 offset:1024
	ds_read_b64_tr_b16 v[134:135], v212 offset:1536
	s_waitcnt lgkmcnt(14)
	v_mfma_f32_32x32x16_bf16 v[16:31], v[178:181], v[146:149], v[16:31]
	v_exp_f32_e32 v118, v118
	v_exp_f32_e32 v119, v119
	ds_read_b64_tr_b16 v[136:137], v212 offset:5120
	ds_read_b64_tr_b16 v[138:139], v212 offset:5632
	s_waitcnt lgkmcnt(14)
	v_mfma_f32_32x32x16_bf16 v[0:15], v[170:173], v[150:153], v[0:15]
	v_exp_f32_e32 v120, v120
	v_exp_f32_e32 v121, v121
	ds_read_b64_tr_b16 v[140:141], v212 offset:2048
	ds_read_b64_tr_b16 v[142:143], v212 offset:2560
	s_waitcnt lgkmcnt(14)
	v_mfma_f32_32x32x16_bf16 v[16:31], v[170:173], v[80:83], v[16:31]
	v_exp_f32_e32 v122, v122
	v_exp_f32_e32 v123, v123
	ds_read_b64_tr_b16 v[80:81], v212 offset:6144
	ds_read_b64_tr_b16 v[82:83], v212 offset:6656
	s_waitcnt lgkmcnt(14)
	v_mfma_f32_32x32x16_bf16 v[0:15], v[166:169], v[84:87], v[0:15]
	v_exp_f32_e32 v124, v124
	v_exp_f32_e32 v125, v125
	ds_read_b64_tr_b16 v[84:85], v212 offset:3072
	ds_read_b64_tr_b16 v[86:87], v212 offset:3584
	s_waitcnt lgkmcnt(14)
	v_mfma_f32_32x32x16_bf16 v[16:31], v[166:169], v[88:91], v[16:31]
	v_exp_f32_e32 v126, v126
	v_exp_f32_e32 v127, v127
	ds_read_b64_tr_b16 v[88:89], v212 offset:7168
	ds_read_b64_tr_b16 v[90:91], v212 offset:7680
	s_waitcnt lgkmcnt(14)
	v_mfma_f32_32x32x16_bf16 v[32:47], v[182:185], v[92:95], v[32:47]
	v_exp_f32_e32 v96, v96
	v_exp_f32_e32 v97, v97
	s_waitcnt lgkmcnt(12)
	v_mfma_f32_32x32x16_bf16 v[48:63], v[182:185], v[128:131], v[48:63]
	v_exp_f32_e32 v98, v98
	v_exp_f32_e32 v99, v99
	v_add_u32_e32 v128, s22, v215
	ds_read_b128 v[92:95], v128
	ds_read_b128 v[146:149], v128 offset:512
	s_waitcnt lgkmcnt(12)
	v_mfma_f32_32x32x16_bf16 v[32:47], v[178:181], v[132:135], v[32:47]
	v_exp_f32_e32 v100, v100
	v_exp_f32_e32 v101, v101
	ds_read_b128 v[150:153], v128 offset:2048
	ds_read_b128 v[154:157], v128 offset:2560
	s_waitcnt lgkmcnt(12)
	v_mfma_f32_32x32x16_bf16 v[48:63], v[178:181], v[136:139], v[48:63]
	v_exp_f32_e32 v102, v102
	v_exp_f32_e32 v103, v103
	ds_read_b128 v[194:197], v128 offset:4096
	ds_read_b128 v[198:201], v128 offset:4608
	s_waitcnt lgkmcnt(12)
	v_mfma_f32_32x32x16_bf16 v[32:47], v[170:173], v[140:143], v[32:47]
	v_exp_f32_e32 v104, v104
	v_exp_f32_e32 v105, v105
	ds_read_b128 v[202:205], v128 offset:6144
	ds_read_b128 v[206:209], v128 offset:6656
	s_waitcnt lgkmcnt(12)
	v_mfma_f32_32x32x16_bf16 v[48:63], v[170:173], v[80:83], v[48:63]
	v_exp_f32_e32 v106, v106
	v_exp_f32_e32 v107, v107
	s_waitcnt lgkmcnt(10)
	v_mfma_f32_32x32x16_bf16 v[32:47], v[166:169], v[84:87], v[32:47]
	v_exp_f32_e32 v108, v108
	v_exp_f32_e32 v109, v109
	s_waitcnt lgkmcnt(8)
	v_mfma_f32_32x32x16_bf16 v[48:63], v[166:169], v[88:91], v[48:63]
	v_exp_f32_e32 v110, v110
	v_exp_f32_e32 v111, v111
	s_waitcnt vmcnt(4) lgkmcnt(0)
	s_barrier
; #define WAIT_BAR(N) asm volatile("s_waitcnt vmcnt(" #N ") lgkmcnt(0)\n\ts_barrier":::"memory")
;   #define RESC() do{ if(resc){ asm volatile("s_waitcnt lgkmcnt(0)":::"memory"); \
;       _Pragma("unroll") for(int d_=0;d_<2;++d_) _Pragma("unroll") for(int r=0;r<16;++r)o[d_][r]*=wsf[crow(r,hi)]; } }while(0)
;   #define ROT() do{sl_prev=sl_cur;sl_cur=sl_next;sl_next=(sl_next==(NSLOT-1)*SLOTB)?0:sl_next+SLOTB;}while(0)
;   #define ENDW(tt) do{ if((tt)+3<NT){WAIT_BAR(3);} else if((tt)+2<NT){WAIT_BAR(2);} else {WAIT_BAR(0);} }while(0)
; #define WAIT_BAR(N) asm volatile("s_waitcnt vmcnt(" #N ") lgkmcnt(0)\n\ts_barrier":::"memory")
;   #define RESC() do{ if(resc){ asm volatile("s_waitcnt lgkmcnt(0)":::"memory"); \
;       _Pragma("unroll") for(int d_=0;d_<4;++d_) _Pragma("unroll") for(int r=0;r<16;++r)o[d_][r]*=wsf[crow(r,hi)]; } }while(0)
;   #define ROT() do{sl_prev=sl_cur;sl_cur=sl_next;sl_next=(sl_next==(NSLOT-1)*SLOTB)?0:sl_next+SLOTB;}while(0)
;   #define ENDW(tt) do{ if((tt)+3<NT){WAIT_BAR(5);} else if((tt)+2<NT){WAIT_BAR(4);} else {WAIT_BAR(0);} }while(0)
; #define WAIT_BAR(N) asm volatile("s_waitcnt vmcnt(" #N ") lgkmcnt(0)\n\ts_barrier":::"memory")
;   #define RESC() do{ if(resc){ asm volatile("s_waitcnt lgkmcnt(0)":::"memory"); \
;       _Pragma("unroll") for(int d_=0;d_<2;++d_) _Pragma("unroll") for(int r=0;r<16;++r)o[d_][r]*=wsf[crow(r,hi)]; } }while(0)
;   #define ROT() do{sl_prev=sl_cur;sl_cur=sl_next;sl_next=(sl_next==(NSLOT-1)*SLOTB)?0:sl_next+SLOTB;}while(0)
;   #define ENDW(tt) do{ if((tt)+3<NT){WAIT_BAR(3);} else if((tt)+2<NT){WAIT_BAR(2);} else {WAIT_BAR(0);} }while(0)
; template<int THRL,bool FIXED> __device__ __forceinline__ void attn_unit(int qb,const bf16*Qp,const bf16*__restrict__ Kh,const bf16*__restrict__ Vh,bf16*Op,int PO,char*shm,bool comb,float lam,const float*gsub,float gscale){
;     ...
;   int t=1;
;     ...
;   for(;t+5<NT;t+=2){
;     STEP(pB0,pB1,pA0,pA1,t,true,true,true);     WAIT_BAR(5); RESC(); ROT();
;     STEP(pA0,pA1,pB0,pB1,t+1,true,true,true);   WAIT_BAR(5); RESC(); ROT();
;   }
;     ...
;   for(;t+1<NT;t+=2){
;     STEP(pB0,pB1,pA0,pA1,t,(t+3<NT),(t+2<NT),(t+1<NT));       ENDW(t);   RESC(); ROT();
;     STEP(pA0,pA1,pB0,pB1,t+1,(t+4<NT),(t+3<NT),(t+2<NT));     ENDW(t+1); RESC(); ROT();
	s_add_i32 s3, s22, 0x2000
	s_cmpk_lg_i32 s22, 0x4000
	s_cselect_b32 s3, s3, 0
	v_add_u32_e32 v158, 0xc000, v214
	ds_read_b64_tr_b16 v[210:211], v214 offset:40960
	ds_read_b64_tr_b16 v[212:213], v214 offset:41472
	v_add_f32_e32 v80, v112, v113
	v_add_f32_e32 v80, v114, v80
	v_add_f32_e32 v80, v115, v80
	v_add_f32_e32 v80, v116, v80
	v_add_f32_e32 v80, v117, v80
	v_cvt_pk_bf16_f32 v182, v112, v113
	v_cvt_pk_bf16_f32 v183, v114, v115
	s_waitcnt lgkmcnt(9)
	v_mfma_f32_32x32x16_bf16 v[128:143], v[92:95], v[190:193], v[64:79]
	ds_read_b64_tr_b16 v[222:223], v214 offset:45056
	ds_read_b64_tr_b16 v[224:225], v214 offset:45568
	v_add_f32_e32 v80, v118, v80
	v_add_f32_e32 v80, v119, v80
	v_add_f32_e32 v80, v120, v80
	v_add_f32_e32 v112, v121, v80
	s_waitcnt lgkmcnt(10)
	v_mfma_f32_32x32x16_bf16 v[80:95], v[146:149], v[190:193], v[64:79]
	v_cvt_pk_bf16_f32 v184, v116, v117
	v_cvt_pk_bf16_f32 v185, v118, v119
	ds_read_b64_tr_b16 v[114:115], v214 offset:41984
	ds_read_b64_tr_b16 v[116:117], v214 offset:42496
	v_add_f32_e32 v112, v122, v112
	v_add_f32_e32 v112, v123, v112
	v_add_f32_e32 v112, v124, v112
	v_add_f32_e32 v112, v125, v112
	v_cvt_pk_bf16_f32 v178, v120, v121
	v_cvt_pk_bf16_f32 v179, v122, v123
	s_waitcnt lgkmcnt(11)
	v_mfma_f32_32x32x16_bf16 v[128:143], v[150:153], v[186:189], v[128:143]
	ds_read_b64_tr_b16 v[118:119], v214 offset:46080
	ds_read_b64_tr_b16 v[120:121], v214 offset:46592
	s_waitcnt lgkmcnt(12)
	v_mfma_f32_32x32x16_bf16 v[80:95], v[154:157], v[186:189], v[80:95]
	v_add_f32_e32 v112, v126, v112
	v_add_f32_e32 v112, v127, v112
	v_add_f32_e32 v112, v96, v112
	v_add_f32_e32 v112, v97, v112
	v_cvt_pk_bf16_f32 v180, v124, v125
	v_cvt_pk_bf16_f32 v181, v126, v127
	ds_read_b64_tr_b16 v[122:123], v214 offset:43008
	ds_read_b64_tr_b16 v[124:125], v214 offset:43520
	v_add_f32_e32 v112, v98, v112
	v_add_f32_e32 v112, v99, v112
	v_add_f32_e32 v112, v100, v112
	v_add_f32_e32 v112, v101, v112
	v_cvt_pk_bf16_f32 v170, v96, v97
	v_cvt_pk_bf16_f32 v171, v98, v99
	s_waitcnt lgkmcnt(13)
	v_mfma_f32_32x32x16_bf16 v[128:143], v[194:197], v[174:177], v[128:143]
	ds_read_b64_tr_b16 v[96:97], v214 offset:47104
	ds_read_b64_tr_b16 v[98:99], v214 offset:47616
	s_waitcnt lgkmcnt(14)
	v_mfma_f32_32x32x16_bf16 v[80:95], v[198:201], v[174:177], v[80:95]
	v_add_f32_e32 v112, v102, v112
	v_add_f32_e32 v112, v103, v112
	v_add_f32_e32 v112, v104, v112
	v_add_f32_e32 v112, v105, v112
	v_cvt_pk_bf16_f32 v172, v100, v101
	v_cvt_pk_bf16_f32 v173, v102, v103
	ds_read_b64_tr_b16 v[100:101], v214 offset:44032
	ds_read_b64_tr_b16 v[102:103], v214 offset:44544
	v_add_f32_e32 v112, v106, v112
	v_add_f32_e32 v112, v107, v112
	v_add_f32_e32 v112, v108, v112
	v_add_f32_e32 v112, v109, v112
	v_cvt_pk_bf16_f32 v166, v104, v105
	v_cvt_pk_bf16_f32 v167, v106, v107
	s_waitcnt lgkmcnt(14)
	v_mfma_f32_32x32x16_bf16 v[128:143], v[202:205], v[162:165], v[128:143]
	ds_read_b64_tr_b16 v[104:105], v214 offset:48128
	ds_read_b64_tr_b16 v[106:107], v214 offset:48640
	v_mfma_f32_32x32x16_bf16 v[80:95], v[206:209], v[162:165], v[80:95]
	v_add_f32_e32 v112, v110, v112
	v_add_f32_e32 v112, v111, v112
	v_add_f32_e32 v112, 0, v112
	v_cvt_pk_bf16_f32 v168, v108, v109
	v_cvt_pk_bf16_f32 v169, v110, v111
	s_nop 0
	v_add_f32_e32 v112, v144, v112
	s_waitcnt lgkmcnt(14)
	v_mfma_f32_32x32x16_bf16 v[0:15], v[182:185], v[210:213], v[0:15]
	v_exp_f32_e32 v128, v128
	v_exp_f32_e32 v129, v129
	ds_read_b64_tr_b16 v[108:109], v158
	ds_read_b64_tr_b16 v[110:111], v158 offset:512
	s_waitcnt lgkmcnt(14)
	v_mfma_f32_32x32x16_bf16 v[16:31], v[182:185], v[222:225], v[16:31]
	v_exp_f32_e32 v130, v130
	v_exp_f32_e32 v131, v131
	ds_read_b64_tr_b16 v[144:145], v158 offset:4096
	ds_read_b64_tr_b16 v[146:147], v158 offset:4608
	s_waitcnt lgkmcnt(14)
	v_mfma_f32_32x32x16_bf16 v[0:15], v[178:181], v[114:117], v[0:15]
	v_exp_f32_e32 v132, v132
	v_exp_f32_e32 v133, v133
	ds_read_b64_tr_b16 v[114:115], v158 offset:1024
	ds_read_b64_tr_b16 v[116:117], v158 offset:1536
	s_waitcnt lgkmcnt(14)
	v_mfma_f32_32x32x16_bf16 v[16:31], v[178:181], v[118:121], v[16:31]
	v_exp_f32_e32 v134, v134
	v_exp_f32_e32 v135, v135
	ds_read_b64_tr_b16 v[118:119], v158 offset:5120
	ds_read_b64_tr_b16 v[120:121], v158 offset:5632
	s_waitcnt lgkmcnt(14)
	v_mfma_f32_32x32x16_bf16 v[0:15], v[170:173], v[122:125], v[0:15]
	v_exp_f32_e32 v136, v136
	v_exp_f32_e32 v137, v137
	ds_read_b64_tr_b16 v[122:123], v158 offset:2048
	ds_read_b64_tr_b16 v[124:125], v158 offset:2560
	s_waitcnt lgkmcnt(14)
	v_mfma_f32_32x32x16_bf16 v[16:31], v[170:173], v[96:99], v[16:31]
	v_exp_f32_e32 v138, v138
	v_exp_f32_e32 v139, v139
	ds_read_b64_tr_b16 v[96:97], v158 offset:6144
	ds_read_b64_tr_b16 v[98:99], v158 offset:6656
	s_waitcnt lgkmcnt(14)
	v_mfma_f32_32x32x16_bf16 v[0:15], v[166:169], v[100:103], v[0:15]
	v_exp_f32_e32 v140, v140
	v_exp_f32_e32 v141, v141
	ds_read_b64_tr_b16 v[100:101], v158 offset:3072
	ds_read_b64_tr_b16 v[102:103], v158 offset:3584
	s_waitcnt lgkmcnt(14)
	v_mfma_f32_32x32x16_bf16 v[16:31], v[166:169], v[104:107], v[16:31]
	v_exp_f32_e32 v142, v142
	v_exp_f32_e32 v143, v143
	ds_read_b64_tr_b16 v[104:105], v158 offset:7168
	ds_read_b64_tr_b16 v[106:107], v158 offset:7680
	s_waitcnt lgkmcnt(14)
	v_mfma_f32_32x32x16_bf16 v[32:47], v[182:185], v[108:111], v[32:47]
	v_exp_f32_e32 v80, v80
	v_exp_f32_e32 v81, v81
	s_waitcnt lgkmcnt(12)
	v_mfma_f32_32x32x16_bf16 v[48:63], v[182:185], v[144:147], v[48:63]
	v_exp_f32_e32 v82, v82
	v_exp_f32_e32 v83, v83
	v_add_u32_e32 v108, s3, v215
	ds_read_b128 v[144:147], v108
	ds_read_b128 v[148:151], v108 offset:512
	s_waitcnt lgkmcnt(12)
	v_mfma_f32_32x32x16_bf16 v[32:47], v[178:181], v[114:117], v[32:47]
	v_exp_f32_e32 v84, v84
	v_exp_f32_e32 v85, v85
	ds_read_b128 v[114:117], v108 offset:2048
	ds_read_b128 v[152:155], v108 offset:2560
	s_waitcnt lgkmcnt(12)
	v_mfma_f32_32x32x16_bf16 v[48:63], v[178:181], v[118:121], v[48:63]
	v_exp_f32_e32 v86, v86
	v_exp_f32_e32 v87, v87
	ds_read_b128 v[118:121], v108 offset:4096
	ds_read_b128 v[156:159], v108 offset:4608
	s_waitcnt lgkmcnt(12)
	v_mfma_f32_32x32x16_bf16 v[32:47], v[170:173], v[122:125], v[32:47]
	v_exp_f32_e32 v88, v88
	v_exp_f32_e32 v89, v89
	ds_read_b128 v[122:125], v108 offset:6144
	ds_read_b128 v[194:197], v108 offset:6656
	s_waitcnt lgkmcnt(12)
	v_mfma_f32_32x32x16_bf16 v[48:63], v[170:173], v[96:99], v[48:63]
	v_exp_f32_e32 v90, v90
	v_exp_f32_e32 v91, v91
	s_waitcnt lgkmcnt(10)
	v_mfma_f32_32x32x16_bf16 v[32:47], v[166:169], v[100:103], v[32:47]
	v_exp_f32_e32 v92, v92
	v_exp_f32_e32 v93, v93
	s_waitcnt lgkmcnt(8)
	v_mfma_f32_32x32x16_bf16 v[48:63], v[166:169], v[104:107], v[48:63]
	v_exp_f32_e32 v94, v94
	v_exp_f32_e32 v95, v95
	s_waitcnt vmcnt(0) lgkmcnt(0)
	s_barrier
;   #define RESC() do{ if(resc){ asm volatile("s_waitcnt lgkmcnt(0)":::"memory"); \
;       _Pragma("unroll") for(int d_=0;d_<2;++d_) _Pragma("unroll") for(int r=0;r<16;++r)o[d_][r]*=wsf[crow(r,hi)]; } }while(0)
;   #define RESC() do{ if(resc){ asm volatile("s_waitcnt lgkmcnt(0)":::"memory"); \
;       _Pragma("unroll") for(int d_=0;d_<4;++d_) _Pragma("unroll") for(int r=0;r<16;++r)o[d_][r]*=wsf[crow(r,hi)]; } }while(0)
;   #define RESC() do{ if(resc){ asm volatile("s_waitcnt lgkmcnt(0)":::"memory"); \
;       _Pragma("unroll") for(int d_=0;d_<2;++d_) _Pragma("unroll") for(int r=0;r<16;++r)o[d_][r]*=wsf[crow(r,hi)]; } }while(0)
; template<int THRL,bool FIXED> __device__ __forceinline__ void attn_unit(int qb,const bf16*Qp,const bf16*__restrict__ Kh,const bf16*__restrict__ Vh,bf16*Op,int PO,char*shm,bool comb,float lam,const float*gsub,float gscale){
;     ...
;   STEP(pB0,pB1,pA0,pA1,NT-1,false,false,false); RESC();
	ds_read_b64_tr_b16 v[198:199], v214 offset:57344
	ds_read_b64_tr_b16 v[200:201], v214 offset:57856
	v_add_f32_e32 v96, v128, v129
	v_add_f32_e32 v96, v130, v96
	v_add_f32_e32 v96, v131, v96
	v_add_f32_e32 v96, v132, v96
	v_add_f32_e32 v113, v133, v96
	v_cvt_pk_bf16_f32 v182, v128, v129
	v_cvt_pk_bf16_f32 v183, v130, v131
	s_waitcnt lgkmcnt(9)
	v_mfma_f32_32x32x16_bf16 v[96:111], v[144:147], v[190:193], v[64:79]
	ds_read_b64_tr_b16 v[126:127], v214 offset:61440
	ds_read_b64_tr_b16 v[128:129], v214 offset:61952
	s_waitcnt lgkmcnt(10)
	v_mfma_f32_32x32x16_bf16 v[64:79], v[148:151], v[190:193], v[64:79]
	v_add_f32_e32 v113, v134, v113
	v_add_f32_e32 v113, v135, v113
	v_add_f32_e32 v113, v136, v113
	v_add_f32_e32 v113, v137, v113
	v_cvt_pk_bf16_f32 v184, v132, v133
	v_cvt_pk_bf16_f32 v185, v134, v135
	ds_read_b64_tr_b16 v[130:131], v214 offset:58368
	ds_read_b64_tr_b16 v[132:133], v214 offset:58880
	v_add_f32_e32 v113, v138, v113
	v_add_f32_e32 v113, v139, v113
	v_add_f32_e32 v113, v140, v113
	v_add_f32_e32 v113, v141, v113
	v_cvt_pk_bf16_f32 v178, v136, v137
	v_cvt_pk_bf16_f32 v179, v138, v139
	s_waitcnt lgkmcnt(11)
	v_mfma_f32_32x32x16_bf16 v[96:111], v[114:117], v[186:189], v[96:111]
	ds_read_b64_tr_b16 v[114:115], v214 offset:62464
	ds_read_b64_tr_b16 v[116:117], v214 offset:62976
	s_waitcnt lgkmcnt(12)
	v_mfma_f32_32x32x16_bf16 v[64:79], v[152:155], v[186:189], v[64:79]
	v_add_f32_e32 v113, v142, v113
	v_add_f32_e32 v113, v143, v113
	v_add_f32_e32 v113, v80, v113
	v_add_f32_e32 v113, v81, v113
	v_cvt_pk_bf16_f32 v180, v140, v141
	v_cvt_pk_bf16_f32 v181, v142, v143
	ds_read_b64_tr_b16 v[134:135], v214 offset:59392
	ds_read_b64_tr_b16 v[136:137], v214 offset:59904
	v_add_f32_e32 v113, v82, v113
	v_add_f32_e32 v113, v83, v113
	v_add_f32_e32 v113, v84, v113
	v_add_f32_e32 v113, v85, v113
	v_cvt_pk_bf16_f32 v170, v80, v81
	v_cvt_pk_bf16_f32 v171, v82, v83
	s_waitcnt lgkmcnt(13)
	v_mfma_f32_32x32x16_bf16 v[96:111], v[118:121], v[174:177], v[96:111]
	ds_read_b64_tr_b16 v[80:81], v214 offset:63488
	ds_read_b64_tr_b16 v[82:83], v214 offset:64000
	s_waitcnt lgkmcnt(14)
	v_mfma_f32_32x32x16_bf16 v[64:79], v[156:159], v[174:177], v[64:79]
	v_add_f32_e32 v113, v86, v113
	v_add_f32_e32 v113, v87, v113
	v_add_f32_e32 v113, v88, v113
	v_add_f32_e32 v113, v89, v113
	v_cvt_pk_bf16_f32 v172, v84, v85
	v_cvt_pk_bf16_f32 v173, v86, v87
	ds_read_b64_tr_b16 v[84:85], v214 offset:60416
	ds_read_b64_tr_b16 v[86:87], v214 offset:60928
	v_add_f32_e32 v113, v90, v113
	v_add_f32_e32 v113, v91, v113
	v_add_f32_e32 v113, v92, v113
	v_add_f32_e32 v113, v93, v113
	v_cvt_pk_bf16_f32 v166, v88, v89
	v_cvt_pk_bf16_f32 v167, v90, v91
	s_waitcnt lgkmcnt(14)
	v_mfma_f32_32x32x16_bf16 v[96:111], v[122:125], v[162:165], v[96:111]
	ds_read_b64_tr_b16 v[88:89], v214 offset:64512
	ds_read_b64_tr_b16 v[90:91], v214 offset:65024
	v_mfma_f32_32x32x16_bf16 v[64:79], v[194:197], v[162:165], v[64:79]
	v_add_f32_e32 v113, v94, v113
	v_add_f32_e32 v113, v95, v113
	v_add_f32_e32 v113, 0, v113
	v_cvt_pk_bf16_f32 v168, v92, v93
	v_cvt_pk_bf16_f32 v169, v94, v95
	s_waitcnt lgkmcnt(14)
	v_mfma_f32_32x32x16_bf16 v[0:15], v[182:185], v[198:201], v[0:15]
	s_nop 1
	v_exp_f32_e32 v96, v96
	v_exp_f32_e32 v97, v97
	ds_read_b64_tr_b16 v[92:93], v160
	ds_read_b64_tr_b16 v[94:95], v160 offset:512
	s_waitcnt lgkmcnt(14)
	v_mfma_f32_32x32x16_bf16 v[16:31], v[182:185], v[126:129], v[16:31]
	v_exp_f32_e32 v98, v98
	v_exp_f32_e32 v99, v99
	ds_read_b64_tr_b16 v[118:119], v160 offset:4096
	ds_read_b64_tr_b16 v[120:121], v160 offset:4608
	s_waitcnt lgkmcnt(14)
	v_mfma_f32_32x32x16_bf16 v[0:15], v[178:181], v[130:133], v[0:15]
	v_exp_f32_e32 v100, v100
	v_exp_f32_e32 v101, v101
	ds_read_b64_tr_b16 v[122:123], v160 offset:1024
	ds_read_b64_tr_b16 v[124:125], v160 offset:1536
	s_waitcnt lgkmcnt(14)
	v_mfma_f32_32x32x16_bf16 v[16:31], v[178:181], v[114:117], v[16:31]
	v_exp_f32_e32 v102, v102
	v_exp_f32_e32 v103, v103
	ds_read_b64_tr_b16 v[114:115], v160 offset:5120
	ds_read_b64_tr_b16 v[116:117], v160 offset:5632
	s_waitcnt lgkmcnt(14)
	v_mfma_f32_32x32x16_bf16 v[0:15], v[170:173], v[134:137], v[0:15]
	v_exp_f32_e32 v104, v104
	v_exp_f32_e32 v105, v105
	ds_read_b64_tr_b16 v[126:127], v160 offset:2048
	ds_read_b64_tr_b16 v[128:129], v160 offset:2560
	s_waitcnt lgkmcnt(14)
	v_mfma_f32_32x32x16_bf16 v[16:31], v[170:173], v[80:83], v[16:31]
	v_exp_f32_e32 v106, v106
	v_exp_f32_e32 v107, v107
	ds_read_b64_tr_b16 v[80:81], v160 offset:6144
	ds_read_b64_tr_b16 v[82:83], v160 offset:6656
	s_waitcnt lgkmcnt(14)
	v_mfma_f32_32x32x16_bf16 v[0:15], v[166:169], v[84:87], v[0:15]
	v_exp_f32_e32 v108, v108
	v_exp_f32_e32 v109, v109
	ds_read_b64_tr_b16 v[84:85], v160 offset:3072
	ds_read_b64_tr_b16 v[86:87], v160 offset:3584
	s_waitcnt lgkmcnt(14)
	v_mfma_f32_32x32x16_bf16 v[16:31], v[166:169], v[88:91], v[16:31]
	v_exp_f32_e32 v110, v110
	v_exp_f32_e32 v111, v111
	ds_read_b64_tr_b16 v[88:89], v160 offset:7168
	ds_read_b64_tr_b16 v[90:91], v160 offset:7680
	s_waitcnt lgkmcnt(14)
	v_mfma_f32_32x32x16_bf16 v[32:47], v[182:185], v[92:95], v[32:47]
	v_exp_f32_e32 v64, v64
	v_exp_f32_e32 v65, v65
	s_waitcnt lgkmcnt(12)
	v_mfma_f32_32x32x16_bf16 v[48:63], v[182:185], v[118:121], v[48:63]
	v_exp_f32_e32 v66, v66
	v_exp_f32_e32 v67, v67
	s_waitcnt lgkmcnt(10)
	v_mfma_f32_32x32x16_bf16 v[32:47], v[178:181], v[122:125], v[32:47]
	v_exp_f32_e32 v68, v68
	v_exp_f32_e32 v69, v69
	s_waitcnt lgkmcnt(8)
	v_mfma_f32_32x32x16_bf16 v[48:63], v[178:181], v[114:117], v[48:63]
	v_exp_f32_e32 v70, v70
	v_exp_f32_e32 v71, v71
	s_waitcnt lgkmcnt(6)
	v_mfma_f32_32x32x16_bf16 v[32:47], v[170:173], v[126:129], v[32:47]
	v_exp_f32_e32 v72, v72
	v_exp_f32_e32 v73, v73
	s_waitcnt lgkmcnt(4)
; #define SBAR() __builtin_amdgcn_sched_barrier(0)
;   #define PKW(P,B) cvtpk_s(P[B],P[B+1])
; #define SBAR() __builtin_amdgcn_sched_barrier(0)
;   #define PKW(P,B) cvtpk_s(P[B],P[B+1])
; #define SBAR() __builtin_amdgcn_sched_barrier(0)
;   #define PKW(P,B) cvtpk_s(P[B],P[B+1])
; __device__ __forceinline__ void pv(f32x16*o,int vb,bf16x8 pa0,bf16x8 pa1,bf16x8 pa2,bf16x8 pa3){
;   #pragma unroll
;   for(int d0=0;d0<4;++d0){s16x4 lo[4],hi[4];
;     #pragma unroll
;     for(int ks=0;ks<4;++ks){
;       asm volatile("ds_read_b64_tr_b16 %0,%1 offset:%c2":"=&v"(lo[ks]):"v"(vb),"i"(d0*4096+ks*1024):"memory");
;       asm volatile("ds_read_b64_tr_b16 %0,%1 offset:%c2":"=&v"(hi[ks]):"v"(vb),"i"(d0*4096+ks*1024+512):"memory");}
;     asm volatile("s_waitcnt lgkmcnt(0)":::"memory");SBAR();
;     ...
;     o[d0]=__builtin_amdgcn_mfma_f32_32x32x16_bf16(pa0,PK(0),o[d0],0,0,0);
;     o[d0]=__builtin_amdgcn_mfma_f32_32x32x16_bf16(pa1,PK(1),o[d0],0,0,0);
;     o[d0]=__builtin_amdgcn_mfma_f32_32x32x16_bf16(pa2,PK(2),o[d0],0,0,0);
;     o[d0]=__builtin_amdgcn_mfma_f32_32x32x16_bf16(pa3,PK(3),o[d0],0,0,0);
;     ...
;   }
; }
; template<int THRL,bool FIXED> __device__ __forceinline__ void attn_unit(int qb,const bf16*Qp,const bf16*__restrict__ Kh,const bf16*__restrict__ Vh,bf16*Op,int PO,char*shm,bool comb,float lam,const float*gsub,float gscale){
;     ...
;   { float sacc=pB0[0]+pB0[1]; _Pragma("unroll") for(int r=2;r<16;++r)sacc+=pB0[r]; _Pragma("unroll") for(int r=0;r<16;++r)sacc+=pB1[r]; l_reg+=sacc;
;     pw0=(u32x4){PKW(pB0,0),PKW(pB0,2),PKW(pB0,4),PKW(pB0,6)};pw1=(u32x4){PKW(pB0,8),PKW(pB0,10),PKW(pB0,12),PKW(pB0,14)};pw2=(u32x4){PKW(pB1,0),PKW(pB1,2),PKW(pB1,4),PKW(pB1,6)};pw3=(u32x4){PKW(pB1,8),PKW(pB1,10),PKW(pB1,12),PKW(pB1,14)};
;     SBAR(); pv(o,vb0+VSL(NT-1),PAF(0),PAF(1),PAF(2),PAF(3)); }
;   asm volatile("s_waitcnt lgkmcnt(0)\n\ts_barrier":::"memory");
	v_mfma_f32_32x32x16_bf16 v[48:63], v[170:173], v[80:83], v[48:63]
	v_exp_f32_e32 v74, v74
	v_exp_f32_e32 v75, v75
	s_waitcnt lgkmcnt(2)
	v_mfma_f32_32x32x16_bf16 v[32:47], v[166:169], v[84:87], v[32:47]
	v_exp_f32_e32 v76, v76
	v_exp_f32_e32 v77, v77
	s_waitcnt lgkmcnt(0)
	v_mfma_f32_32x32x16_bf16 v[48:63], v[166:169], v[88:91], v[48:63]
	v_exp_f32_e32 v78, v78
	v_exp_f32_e32 v79, v79
	v_add_f32_e32 v80, v96, v97
	v_add_f32_e32 v80, v98, v80
	v_add_f32_e32 v80, v99, v80
	v_add_f32_e32 v80, v100, v80
	v_add_f32_e32 v80, v101, v80
	v_add_f32_e32 v80, v102, v80
	v_add_f32_e32 v80, v103, v80
	v_add_f32_e32 v80, v104, v80
	v_add_f32_e32 v80, v105, v80
	v_add_f32_e32 v80, v106, v80
	v_add_f32_e32 v80, v107, v80
	v_add_f32_e32 v80, v108, v80
	v_add_f32_e32 v80, v109, v80
	v_add_f32_e32 v80, v110, v80
	v_add_f32_e32 v80, v111, v80
	v_add_f32_e32 v80, v80, v64
	v_add_f32_e32 v80, v65, v80
	v_add_f32_e32 v80, v66, v80
	v_add_f32_e32 v80, v67, v80
	v_add_f32_e32 v80, v68, v80
	v_add_f32_e32 v80, v69, v80
	v_add_f32_e32 v80, v70, v80
	v_add_f32_e32 v80, v71, v80
	v_add_f32_e32 v80, v72, v80
	v_add_f32_e32 v80, v73, v80
	v_add_f32_e32 v80, v74, v80
	v_add_f32_e32 v80, v75, v80
	v_add_f32_e32 v80, v76, v80
	v_add_f32_e32 v80, v77, v80
	v_add_f32_e32 v80, v78, v80
	v_add_f32_e32 v80, v79, v80
	v_add_f32_e32 v81, v112, v113
	v_add_f32_e32 v80, v81, v80
	v_cvt_pk_bf16_f32 v64, v64, v65
	v_cvt_pk_bf16_f32 v82, v96, v97
	v_cvt_pk_bf16_f32 v83, v98, v99
	v_cvt_pk_bf16_f32 v84, v100, v101
	v_cvt_pk_bf16_f32 v85, v102, v103
	v_cvt_pk_bf16_f32 v86, v104, v105
	v_cvt_pk_bf16_f32 v87, v106, v107
	v_cvt_pk_bf16_f32 v88, v108, v109
	v_cvt_pk_bf16_f32 v89, v110, v111
	v_cvt_pk_bf16_f32 v65, v66, v67
	v_cvt_pk_bf16_f32 v66, v68, v69
	v_cvt_pk_bf16_f32 v67, v70, v71
	v_cvt_pk_bf16_f32 v68, v72, v73
	v_cvt_pk_bf16_f32 v69, v74, v75
	v_cvt_pk_bf16_f32 v70, v76, v77
	v_cvt_pk_bf16_f32 v71, v78, v79
	v_add_u32_e32 v72, s29, v236
	v_add3_u32 v81, v72, v237, v240
	ds_read_b64_tr_b16 v[72:73],v81 offset:0
	ds_read_b64_tr_b16 v[74:75],v81 offset:512
	ds_read_b64_tr_b16 v[76:77],v81 offset:1024
	ds_read_b64_tr_b16 v[78:79],v81 offset:1536
	ds_read_b64_tr_b16 v[90:91],v81 offset:2048
	ds_read_b64_tr_b16 v[92:93],v81 offset:2560
	ds_read_b64_tr_b16 v[94:95],v81 offset:3072
	ds_read_b64_tr_b16 v[96:97],v81 offset:3584
	s_waitcnt lgkmcnt(0)
	s_nop 0
	v_mfma_f32_32x32x16_bf16 v[0:15], v[82:85], v[72:75], v[0:15]
	ds_read_b64_tr_b16 v[72:73],v81 offset:4096
	ds_read_b64_tr_b16 v[74:75],v81 offset:4608
	v_mfma_f32_32x32x16_bf16 v[0:15], v[86:89], v[76:79], v[0:15]
	ds_read_b64_tr_b16 v[76:77],v81 offset:5120
	ds_read_b64_tr_b16 v[78:79],v81 offset:5632
	v_mfma_f32_32x32x16_bf16 v[0:15], v[64:67], v[90:93], v[0:15]
	ds_read_b64_tr_b16 v[90:91],v81 offset:6144
	ds_read_b64_tr_b16 v[92:93],v81 offset:6656
	v_mfma_f32_32x32x16_bf16 v[0:15], v[68:71], v[94:97], v[0:15]
	ds_read_b64_tr_b16 v[94:95],v81 offset:7168
	ds_read_b64_tr_b16 v[96:97],v81 offset:7680
	s_waitcnt lgkmcnt(0)
	v_mfma_f32_32x32x16_bf16 v[16:31], v[82:85], v[72:75], v[16:31]
	ds_read_b64_tr_b16 v[72:73],v81 offset:8192
	ds_read_b64_tr_b16 v[74:75],v81 offset:8704
	v_mfma_f32_32x32x16_bf16 v[16:31], v[86:89], v[76:79], v[16:31]
	ds_read_b64_tr_b16 v[76:77],v81 offset:9216
	ds_read_b64_tr_b16 v[78:79],v81 offset:9728
	v_mfma_f32_32x32x16_bf16 v[16:31], v[64:67], v[90:93], v[16:31]
	ds_read_b64_tr_b16 v[90:91],v81 offset:10240
	ds_read_b64_tr_b16 v[92:93],v81 offset:10752
	v_mfma_f32_32x32x16_bf16 v[16:31], v[68:71], v[94:97], v[16:31]
	ds_read_b64_tr_b16 v[94:95],v81 offset:11264
	ds_read_b64_tr_b16 v[96:97],v81 offset:11776
	s_waitcnt lgkmcnt(0)
	v_mfma_f32_32x32x16_bf16 v[32:47], v[82:85], v[72:75], v[32:47]
	ds_read_b64_tr_b16 v[72:73],v81 offset:12288
	ds_read_b64_tr_b16 v[74:75],v81 offset:12800
	v_mfma_f32_32x32x16_bf16 v[32:47], v[86:89], v[76:79], v[32:47]
	ds_read_b64_tr_b16 v[76:77],v81 offset:13312
	ds_read_b64_tr_b16 v[78:79],v81 offset:13824
	v_mfma_f32_32x32x16_bf16 v[32:47], v[64:67], v[90:93], v[32:47]
	ds_read_b64_tr_b16 v[90:91],v81 offset:14336
	ds_read_b64_tr_b16 v[92:93],v81 offset:14848
	v_mfma_f32_32x32x16_bf16 v[32:47], v[68:71], v[94:97], v[32:47]
	ds_read_b64_tr_b16 v[94:95],v81 offset:15360
	ds_read_b64_tr_b16 v[96:97],v81 offset:15872
	s_waitcnt lgkmcnt(0)
	v_mfma_f32_32x32x16_bf16 v[48:63], v[82:85], v[72:75], v[48:63]
	s_waitcnt lgkmcnt(0)
	s_barrier
; __device__ __forceinline__ int crow(int r,int hi){return (r&3)+8*(r>>2)+4*hi;}
; __device__ __forceinline__ int crow(int r,int hi){return (r&3)+8*(r>>2)+4*hi;}
; template<int THRL,bool FIXED> __device__ __forceinline__ void attn_unit(int qb,const bf16*Qp,const bf16*__restrict__ Kh,const bf16*__restrict__ Vh,bf16*Op,int PO,char*shm,bool comb,float lam,const float*gsub,float gscale){
;     ...
;   {auto rr=__builtin_amdgcn_permlane32_swap(__float_as_uint(l_reg),__float_as_uint(l_reg),false,false);l_reg=__uint_as_float(rr[0])+__uint_as_float(rr[1]);}
;   if(hi==0)wsf[32+r32]=l_reg;asm volatile("s_waitcnt lgkmcnt(0)":::"memory");
;   float rli[16];
;   #pragma unroll
;   for(int r=0;r<16;++r)rli[r]=__builtin_amdgcn_rcpf(wsf[32+crow(r,hi)]);
;   bf16*Ow=Op+(long)(q0+wid*QBLK)*PO;
;   { bf16*stg=(bf16*)(shm+LDS_OST)+wid*4096;
;     #pragma unroll
;     for(int r=0;r<16;++r){const int orow=crow(r,hi);
;       #pragma unroll
;       for(int d0=0;d0<4;++d0)stg[orow*128+d0*32+r32]=__float2bfloat16(o[d0][r]*rli[r]);}
	v_cmp_gt_u32_e32 vcc, 32, v234
	v_mfma_f32_32x32x16_bf16 v[48:63], v[86:89], v[76:79], v[48:63]
	v_mfma_f32_32x32x16_bf16 v[48:63], v[64:67], v[90:93], v[48:63]
	v_mov_b32_e32 v64, v80
	s_nop 1
	v_permlane32_swap_b32_e32 v80, v64
	v_mfma_f32_32x32x16_bf16 v[48:63], v[68:71], v[94:97], v[48:63]
	s_and_saveexec_b64 s[66:67], vcc
	v_lshl_add_u32 v65, v232, 2, s28
	v_add_f32_e32 v64, v80, v64
	ds_write_b32 v65, v64 offset:128
	s_or_b64 exec, exec, s[66:67]
	s_waitcnt lgkmcnt(0)
	v_lshl_add_u32 v72, v233, 4, s28
	ds_read_b128 v[64:67], v72 offset:128
	ds_read_b128 v[68:71], v72 offset:160
	s_lshl_b32 s3, s77, 13
	s_add_i32 s3, s3, 0
	s_lshl_b64 s[64:65], s[64:65], 11
	s_waitcnt lgkmcnt(1)
	v_rcp_f32_e32 v73, v64
	v_rcp_f32_e32 v74, v65
	v_rcp_f32_e32 v75, v66
	v_rcp_f32_e32 v76, v67
	s_waitcnt lgkmcnt(0)
	v_rcp_f32_e32 v77, v68
	ds_read_b128 v[64:67], v72 offset:192
	v_rcp_f32_e32 v78, v69
	v_rcp_f32_e32 v79, v70
	v_rcp_f32_e32 v80, v71
	ds_read_b128 v[68:71], v72 offset:224
	v_lshlrev_b32_e32 v72, 1, v232
	v_mul_f32_e32 v0, v0, v73
	v_add3_u32 v72, s3, v235, v72
	v_cvt_pk_bf16_f32 v0, v0, s0
	ds_write_b16 v72, v0
	v_mul_f32_e32 v0, v16, v73
	v_cvt_pk_bf16_f32 v0, v0, s0
	ds_write_b16 v72, v0 offset:64
	v_mul_f32_e32 v0, v32, v73
	v_cvt_pk_bf16_f32 v0, v0, s0
	ds_write_b16 v72, v0 offset:128
	v_mul_f32_e32 v0, v48, v73
	v_cvt_pk_bf16_f32 v0, v0, s0
	ds_write_b16 v72, v0 offset:192
	v_mul_f32_e32 v0, v1, v74
	v_cvt_pk_bf16_f32 v0, v0, s0
	ds_write_b16 v72, v0 offset:256
	v_mul_f32_e32 v0, v17, v74
	v_cvt_pk_bf16_f32 v0, v0, s0
	ds_write_b16 v72, v0 offset:320
	v_mul_f32_e32 v0, v33, v74
	v_cvt_pk_bf16_f32 v0, v0, s0
	ds_write_b16 v72, v0 offset:384
	v_mul_f32_e32 v0, v49, v74
	v_cvt_pk_bf16_f32 v0, v0, s0
	ds_write_b16 v72, v0 offset:448
	v_mul_f32_e32 v0, v2, v75
	v_cvt_pk_bf16_f32 v0, v0, s0
	ds_write_b16 v72, v0 offset:512
	v_mul_f32_e32 v0, v18, v75
	v_cvt_pk_bf16_f32 v0, v0, s0
	ds_write_b16 v72, v0 offset:576
	v_mul_f32_e32 v0, v34, v75
	v_cvt_pk_bf16_f32 v0, v0, s0
	ds_write_b16 v72, v0 offset:640
	v_mul_f32_e32 v0, v50, v75
	v_cvt_pk_bf16_f32 v0, v0, s0
	ds_write_b16 v72, v0 offset:704
	v_mul_f32_e32 v0, v3, v76
	v_cvt_pk_bf16_f32 v0, v0, s0
	ds_write_b16 v72, v0 offset:768
	v_mul_f32_e32 v0, v19, v76
	v_cvt_pk_bf16_f32 v0, v0, s0
	ds_write_b16 v72, v0 offset:832
	v_mul_f32_e32 v0, v35, v76
	v_cvt_pk_bf16_f32 v0, v0, s0
	ds_write_b16 v72, v0 offset:896
	v_mul_f32_e32 v0, v51, v76
	v_cvt_pk_bf16_f32 v0, v0, s0
	ds_write_b16 v72, v0 offset:960
	v_mul_f32_e32 v0, v4, v77
	v_cvt_pk_bf16_f32 v0, v0, s0
	ds_write_b16 v72, v0 offset:2048
	v_mul_f32_e32 v0, v20, v77
	v_cvt_pk_bf16_f32 v0, v0, s0
	ds_write_b16 v72, v0 offset:2112
	v_mul_f32_e32 v0, v36, v77
	v_cvt_pk_bf16_f32 v0, v0, s0
	ds_write_b16 v72, v0 offset:2176
	v_mul_f32_e32 v0, v52, v77
	v_cvt_pk_bf16_f32 v0, v0, s0
	ds_write_b16 v72, v0 offset:2240
	v_mul_f32_e32 v0, v5, v78
	v_cvt_pk_bf16_f32 v0, v0, s0
	ds_write_b16 v72, v0 offset:2304
	v_mul_f32_e32 v0, v21, v78
	v_cvt_pk_bf16_f32 v0, v0, s0
	ds_write_b16 v72, v0 offset:2368
	v_mul_f32_e32 v0, v37, v78
	v_cvt_pk_bf16_f32 v0, v0, s0
	ds_write_b16 v72, v0 offset:2432
	v_mul_f32_e32 v0, v53, v78
	v_cvt_pk_bf16_f32 v0, v0, s0
	ds_write_b16 v72, v0 offset:2496
	v_mul_f32_e32 v0, v6, v79
	v_cvt_pk_bf16_f32 v0, v0, s0
	ds_write_b16 v72, v0 offset:2560
	v_mul_f32_e32 v0, v22, v79
	v_cvt_pk_bf16_f32 v0, v0, s0
	ds_write_b16 v72, v0 offset:2624
	v_mul_f32_e32 v0, v38, v79
	v_cvt_pk_bf16_f32 v0, v0, s0
	ds_write_b16 v72, v0 offset:2688
	v_mul_f32_e32 v0, v54, v79
	v_cvt_pk_bf16_f32 v0, v0, s0
	ds_write_b16 v72, v0 offset:2752
	v_mul_f32_e32 v0, v7, v80
	v_cvt_pk_bf16_f32 v0, v0, s0
	ds_write_b16 v72, v0 offset:2816
	v_mul_f32_e32 v0, v23, v80
	v_cvt_pk_bf16_f32 v0, v0, s0
	s_waitcnt lgkmcnt(14)
; __device__ __forceinline__ int crow(int r,int hi){return (r&3)+8*(r>>2)+4*hi;}
; __device__ __forceinline__ int crow(int r,int hi){return (r&3)+8*(r>>2)+4*hi;}
; template<int THRL,bool FIXED> __device__ __forceinline__ void attn_unit(int qb,const bf16*Qp,const bf16*__restrict__ Kh,const bf16*__restrict__ Vh,bf16*Op,int PO,char*shm,bool comb,float lam,const float*gsub,float gscale){
;     ...
;   { bf16*stg=(bf16*)(shm+LDS_OST)+wid*4096;
;     #pragma unroll
;     for(int r=0;r<16;++r){const int orow=crow(r,hi);
;       #pragma unroll
;       for(int d0=0;d0<4;++d0)stg[orow*128+d0*32+r32]=__float2bfloat16(o[d0][r]*rli[r]);}
;     asm volatile("s_waitcnt lgkmcnt(0)":::"memory");
;     if(!comb){
;       #pragma unroll
;       for(int i=0;i<8;++i){const int row=i*4+(lane>>4),ch=lane&15; const u32x4 v=*(const u32x4*)(stg+row*128+ch*8); ATTN_STORE16(Ow+(long)row*PO+ch*8,v);}
	v_rcp_f32_e32 v64, v64
	ds_write_b16 v72, v0 offset:2880
	v_mul_f32_e32 v0, v39, v80
	v_cvt_pk_bf16_f32 v0, v0, s0
	ds_write_b16 v72, v0 offset:2944
	v_mul_f32_e32 v0, v55, v80
	v_cvt_pk_bf16_f32 v0, v0, s0
	ds_write_b16 v72, v0 offset:3008
	v_mul_f32_e32 v0, v8, v64
	v_cvt_pk_bf16_f32 v0, v0, s0
	ds_write_b16 v72, v0 offset:4096
	v_mul_f32_e32 v0, v24, v64
	v_cvt_pk_bf16_f32 v0, v0, s0
	v_rcp_f32_e32 v65, v65
	ds_write_b16 v72, v0 offset:4160
	v_mul_f32_e32 v0, v40, v64
	v_cvt_pk_bf16_f32 v0, v0, s0
	ds_write_b16 v72, v0 offset:4224
	v_mul_f32_e32 v0, v56, v64
	v_cvt_pk_bf16_f32 v0, v0, s0
	ds_write_b16 v72, v0 offset:4288
	v_mul_f32_e32 v0, v9, v65
	v_cvt_pk_bf16_f32 v0, v0, s0
	ds_write_b16 v72, v0 offset:4352
	v_mul_f32_e32 v0, v25, v65
	v_cvt_pk_bf16_f32 v0, v0, s0
	v_rcp_f32_e32 v66, v66
	ds_write_b16 v72, v0 offset:4416
	v_mul_f32_e32 v0, v41, v65
	v_cvt_pk_bf16_f32 v0, v0, s0
	ds_write_b16 v72, v0 offset:4480
	v_mul_f32_e32 v0, v57, v65
	v_cvt_pk_bf16_f32 v0, v0, s0
	ds_write_b16 v72, v0 offset:4544
	v_mul_f32_e32 v0, v10, v66
	v_cvt_pk_bf16_f32 v0, v0, s0
	ds_write_b16 v72, v0 offset:4608
	v_mul_f32_e32 v0, v26, v66
	v_cvt_pk_bf16_f32 v0, v0, s0
	v_rcp_f32_e32 v67, v67
	ds_write_b16 v72, v0 offset:4672
	v_mul_f32_e32 v0, v42, v66
	v_cvt_pk_bf16_f32 v0, v0, s0
	ds_write_b16 v72, v0 offset:4736
	v_mul_f32_e32 v0, v58, v66
	v_cvt_pk_bf16_f32 v0, v0, s0
	ds_write_b16 v72, v0 offset:4800
	v_mul_f32_e32 v0, v11, v67
	v_cvt_pk_bf16_f32 v0, v0, s0
	ds_write_b16 v72, v0 offset:4864
	v_mul_f32_e32 v0, v27, v67
	v_cvt_pk_bf16_f32 v0, v0, s0
	v_rcp_f32_e32 v68, v68
	ds_write_b16 v72, v0 offset:4928
	v_mul_f32_e32 v0, v43, v67
	v_cvt_pk_bf16_f32 v0, v0, s0
	ds_write_b16 v72, v0 offset:4992
	v_mul_f32_e32 v0, v59, v67
	v_cvt_pk_bf16_f32 v0, v0, s0
	ds_write_b16 v72, v0 offset:5056
	v_mul_f32_e32 v0, v12, v68
	v_cvt_pk_bf16_f32 v0, v0, s0
	ds_write_b16 v72, v0 offset:6144
	v_mul_f32_e32 v0, v28, v68
	v_cvt_pk_bf16_f32 v0, v0, s0
	v_rcp_f32_e32 v69, v69
	ds_write_b16 v72, v0 offset:6208
	v_mul_f32_e32 v0, v44, v68
	v_cvt_pk_bf16_f32 v0, v0, s0
	ds_write_b16 v72, v0 offset:6272
	v_mul_f32_e32 v0, v60, v68
	v_cvt_pk_bf16_f32 v0, v0, s0
	ds_write_b16 v72, v0 offset:6336
	v_mul_f32_e32 v0, v13, v69
	v_cvt_pk_bf16_f32 v0, v0, s0
	ds_write_b16 v72, v0 offset:6400
	v_mul_f32_e32 v0, v29, v69
	v_cvt_pk_bf16_f32 v0, v0, s0
	v_rcp_f32_e32 v70, v70
	ds_write_b16 v72, v0 offset:6464
	v_mul_f32_e32 v0, v45, v69
	v_cvt_pk_bf16_f32 v0, v0, s0
	ds_write_b16 v72, v0 offset:6528
	v_mul_f32_e32 v0, v61, v69
	v_cvt_pk_bf16_f32 v0, v0, s0
	ds_write_b16 v72, v0 offset:6592
	v_mul_f32_e32 v0, v14, v70
	v_cvt_pk_bf16_f32 v0, v0, s0
	ds_write_b16 v72, v0 offset:6656
	v_mul_f32_e32 v0, v30, v70
	v_cvt_pk_bf16_f32 v0, v0, s0
	v_rcp_f32_e32 v71, v71
	ds_write_b16 v72, v0 offset:6720
	v_mul_f32_e32 v0, v46, v70
	v_cvt_pk_bf16_f32 v0, v0, s0
	ds_write_b16 v72, v0 offset:6784
	v_mul_f32_e32 v0, v62, v70
	v_cvt_pk_bf16_f32 v0, v0, s0
	ds_write_b16 v72, v0 offset:6848
	v_mul_f32_e32 v0, v15, v71
	v_cvt_pk_bf16_f32 v0, v0, s0
	ds_write_b16 v72, v0 offset:6912
	v_mul_f32_e32 v0, v31, v71
	v_cvt_pk_bf16_f32 v0, v0, s0
	ds_write_b16 v72, v0 offset:6976
	v_mul_f32_e32 v0, v47, v71
	v_cvt_pk_bf16_f32 v0, v0, s0
	ds_write_b16 v72, v0 offset:7040
	v_mul_f32_e32 v0, v63, v71
	v_cvt_pk_bf16_f32 v0, v0, s0
	ds_write_b16 v72, v0 offset:7104
	s_waitcnt lgkmcnt(0)
	s_add_u32 s64, s72, s64
	v_lshlrev_b32_e32 v6, 3, v231
	v_or_b32_e32 v28, 4, v230
	v_or_b32_e32 v60, 8, v230
	v_or_b32_e32 v59, 12, v230
	v_or_b32_e32 v58, 16, v230
	v_or_b32_e32 v57, 20, v230
	v_or_b32_e32 v56, 24, v230
	s_addc_u32 s65, s73, s65
	s_mov_b64 s[66:67], -1
	s_andn2_b64 vcc, exec, s[12:13]
	v_lshlrev_b32_e32 v4, 11, v230
	v_lshlrev_b32_e32 v160, 1, v6
	v_lshlrev_b32_e32 v52, 11, v28
	v_lshlrev_b32_e32 v50, 11, v60
	v_lshlrev_b32_e32 v48, 11, v59
	v_lshlrev_b32_e32 v46, 11, v58
	v_lshlrev_b32_e32 v42, 11, v57
	v_lshlrev_b32_e32 v40, 11, v56
	v_or_b32_e32 v54, 28, v230
	s_cbranch_vccnz .LBB0_555
	v_add_u32_e32 v7, s3, v160
	v_lshl_add_u32 v0, v230, 8, v7
	ds_read_b128 v[0:3], v0
	v_lshl_add_u64 v[8:9], s[64:65], 0, v[160:161]
	v_mov_b32_e32 v5, v161
	v_lshl_add_u64 v[10:11], v[8:9], 0, v[4:5]
	v_mov_b32_e32 v53, v161
	s_waitcnt lgkmcnt(0)
	global_store_dwordx4 v[10:11], v[0:3], off offset:1024
	v_lshl_add_u64 v[10:11], v[8:9], 0, v[52:53]
	v_mov_b32_e32 v51, v161
	v_lshl_add_u32 v0, v28, 8, v7
	ds_read_b128 v[0:3], v0
	v_mov_b32_e32 v49, v161
	v_mov_b32_e32 v47, v161
	v_mov_b32_e32 v43, v161
	v_mov_b32_e32 v41, v161
	s_waitcnt lgkmcnt(0)
	global_store_dwordx4 v[10:11], v[0:3], off offset:1024
	v_lshl_add_u64 v[10:11], v[8:9], 0, v[50:51]
	v_or_b32_e32 v5, 28, v230
	v_lshl_add_u32 v0, v60, 8, v7
	ds_read_b128 v[0:3], v0
	s_mov_b64 s[66:67], 0
	s_waitcnt lgkmcnt(0)
	global_store_dwordx4 v[10:11], v[0:3], off offset:1024
	s_nop 1
	v_lshl_add_u32 v0, v59, 8, v7
	ds_read_b128 v[0:3], v0
	v_lshl_add_u64 v[10:11], v[8:9], 0, v[48:49]
	s_waitcnt lgkmcnt(0)
	global_store_dwordx4 v[10:11], v[0:3], off offset:1024
	s_nop 1
	v_lshl_add_u32 v0, v58, 8, v7
	ds_read_b128 v[0:3], v0
	v_lshl_add_u64 v[10:11], v[8:9], 0, v[46:47]
	s_waitcnt lgkmcnt(0)
	global_store_dwordx4 v[10:11], v[0:3], off offset:1024
	s_nop 1
	v_lshl_add_u32 v0, v57, 8, v7
	ds_read_b128 v[0:3], v0
	v_lshl_add_u64 v[10:11], v[8:9], 0, v[42:43]
	v_lshl_add_u64 v[8:9], v[8:9], 0, v[40:41]
	s_waitcnt lgkmcnt(0)
	global_store_dwordx4 v[10:11], v[0:3], off offset:1024
	s_nop 1
	v_lshl_add_u32 v0, v56, 8, v7
	ds_read_b128 v[0:3], v0
	s_waitcnt lgkmcnt(0)
	global_store_dwordx4 v[8:9], v[0:3], off offset:1024
	s_nop 1
	v_lshl_add_u32 v0, v5, 8, v7
	ds_read_b128 v[0:3], v0
